# P0: streaming (nt) policy on the read-once f32 loads (x rows, FFN1-up weights) so they do not displace the bf16 copies P1 re-reads
# speedup vs baseline: 1.0171x; 1.0103x over previous
; #define CONVERT_LIST(LIST, first_, stride_) convert_list<LIST>((first_), (stride_), P, (LAS float*)(lds + wave * 16384), lane)
; __device__ __forceinline__ void conv_fetch(const ConvJob& j, int lane, ConvSet& s) {
;     const int k0 = 64 * j.kb; int cnt; const int src = vgroup_src(j.kind, j.g, cnt);
;     const int ks = lane >> 3, n4 = (lane & 7) * 4, c = lane & 7; const bool okc = n4 < cnt;
;     const float* gp = j.gain ? j.gain + k0 + 8 * c : j.W;
;     s.g0 = *(const f32x4*)gp; s.g1 = *(const f32x4*)(gp + 4);
;     const float* wp = j.W + (size_t)(k0 + ks) * j.Norig + src + (okc ? n4 : 0);
; #pragma unroll
;     for (int i = 0; i < 8; ++i) s.v[i] = *(const f32x4*)(wp + (size_t)(8 * i) * j.Norig);
; }
; __global__ void __launch_bounds__(NTHREADS, 2) fwd_kernel(Params P) {
;     ...
;     bf16_t* Wup1 = (bf16_t*)(outb + OW_UP1); bf16_t* Wdn1 = (bf16_t*)(outb + OW_DN1); bf16_t* Win = (bf16_t*)(outb + OW_IN); bf16_t* Wbr = (bf16_t*)(outb + OW_BR);
;     bf16_t* Wout = (bf16_t*)(outb + OW_OUT); bf16_t* Wup2 = (bf16_t*)(outb + OW_UP2); bf16_t* Wdn2 = (bf16_t*)(ws + WS_WDN2);
;     float* DS = (float*)(outb + O_DS);
;     const int gw = bx * NWAVES + wave, NGW = G * NWAVES;
;     ...
;     const bool split_conv = (lo == 0 && hi == 12);
;     if (IN(0)) {
;         CONVERT_LIST(0, gw, NGW);
.LBB0_13:
	s_lshr_b32 s3, s3, 6
	s_add_u32 s26, s50, 0xb00000
	s_addc_u32 s27, s51, 0
	s_add_u32 s0, s50, 0x1080000
	s_addc_u32 s1, s51, 0
	v_writelane_b32 v252, s0, 3
	v_and_b32_e32 v198, 63, v0
	s_nop 0
	v_writelane_b32 v252, s1, 4
	s_add_u32 s0, s50, 0x1e00000
	s_addc_u32 s1, s51, 0
	v_writelane_b32 v252, s0, 5
	s_nop 1
	v_writelane_b32 v252, s1, 6
	s_add_u32 s0, s50, 0x2200000
	s_addc_u32 s1, s51, 0
	v_writelane_b32 v252, s0, 7
	s_nop 1
	v_writelane_b32 v252, s1, 8
	s_add_u32 s0, s50, 0x2400000
	s_addc_u32 s1, s51, 0
	s_add_u32 s78, s68, 0xf940000
	s_addc_u32 s79, s69, 0
	s_lshl_b32 s76, s2, 3
	s_add_i32 s70, s3, s76
	s_lshl_b32 s92, s71, 3
	v_writelane_b32 v252, s0, 9
	s_cmp_eq_u32 s94, 0
	s_nop 0
	v_writelane_b32 v252, s1, 10
	s_cselect_b64 s[0:1], -1, 0
	s_cmp_eq_u32 s95, 12
	s_cselect_b64 s[4:5], -1, 0
	v_writelane_b32 v252, s3, 11
	s_and_b64 s[0:1], s[0:1], s[4:5]
	v_writelane_b32 v252, s0, 12
	s_cmp_lt_i32 s94, 1
	s_nop 0
	v_writelane_b32 v252, s1, 13
	s_cselect_b64 s[0:1], -1, 0
	s_cmp_gt_i32 s95, 0
	s_cselect_b64 s[4:5], -1, 0
	s_and_b64 s[4:5], s[0:1], s[4:5]
	s_andn2_b64 vcc, exec, s[4:5]
	v_writelane_b32 v252, s78, 14
	s_nop 1
	v_writelane_b32 v252, s79, 15
	s_cbranch_vccnz .LBB0_262
	v_readlane_b32 s0, v252, 12
	v_readlane_b32 s1, v252, 13
	s_xor_b64 s[28:29], s[0:1], -1
	v_readlane_b32 s0, v252, 11
	s_lshl_b32 s0, s0, 14
	s_add_i32 s3, s0, 0
	s_cmpk_lt_i32 s70, 0xb00
	s_cselect_b64 s[6:7], -1, 0
	s_cmpk_gt_i32 s70, 0xaff
	s_cbranch_scc1 .LBB0_21
	s_mul_hi_i32 s0, s70, 0x2e8ba2e9
	s_lshr_b32 s1, s0, 31
	s_ashr_i32 s0, s0, 5
	s_add_i32 s0, s0, s1
	s_mul_i32 s1, s0, 0xb0
	s_sub_i32 s1, s70, s1
	s_lshl_b32 s24, s0, 6
	s_bfe_i32 s0, s1, 0x10002
	s_lshl_b32 s25, s1, 4
	s_and_b32 s0, s0, 0xb00
	s_and_b32 s25, s25, 0xffffff80
	s_lshl_b32 s1, s1, 5
	s_add_i32 s0, s0, s25
	s_and_b32 s1, s1, 0x60
	s_or_b32 s30, s0, s1
	s_cmp_eq_u64 s[18:19], 0
	s_cselect_b64 s[0:1], -1, 0
	s_ashr_i32 s25, s24, 31
	s_lshl_b64 s[34:35], s[24:25], 2
	v_and_b32_e32 v85, 7, v0
	s_add_u32 s34, s18, s34
	v_lshrrev_b32_e32 v130, 3, v198
	s_addc_u32 s35, s19, s35
	v_mov_b32_e32 v123, 0
	v_lshlrev_b32_e32 v122, 5, v85
	v_or_b32_e32 v12, s24, v130
	s_movk_i32 s24, 0x5800
	v_mov_b64_e32 v[10:11], s[20:21]
	v_lshl_add_u64 v[2:3], s[34:35], 0, v[122:123]
	v_mad_i64_i32 v[10:11], s[34:35], v12, s24, v[10:11]
	s_ashr_i32 s31, s30, 31
	v_lshl_add_u64 v[10:11], s[30:31], 2, v[10:11]
	s_add_i32 s30, s92, s70
	s_min_i32 s30, s30, 0xaff
	s_mul_hi_i32 s31, s30, 0x2e8ba2e9
	v_lshlrev_b32_e32 v82, 4, v85
	v_mov_b32_e32 v83, v123
	s_lshr_b32 s75, s31, 31
	s_ashr_i32 s31, s31, 5
	v_lshl_add_u64 v[18:19], v[10:11], 0, v[82:83]
	s_mov_b32 s25, 0x2c000
	s_add_i32 s31, s31, s75
	v_add_co_u32_e32 v10, vcc, s25, v18
	s_mul_i32 s75, s31, 0xb0
	s_nop 0
	v_addc_co_u32_e32 v11, vcc, 0, v19, vcc
	s_mov_b32 s33, 0x58000
	s_sub_i32 s75, s30, s75
	v_add_co_u32_e32 v20, vcc, s33, v18
	s_lshl_b32 s30, s31, 6
	s_bfe_i32 s31, s75, 0x10002
	s_lshl_b32 s77, s75, 4
	v_addc_co_u32_e32 v21, vcc, 0, v19, vcc
	s_mov_b32 s34, 0x84000
	s_and_b32 s31, s31, 0xb00
	s_and_b32 s77, s77, 0xffffff80
	s_lshl_b32 s75, s75, 5
	v_add_co_u32_e32 v22, vcc, s34, v18
	s_add_i32 s31, s31, s77
	s_and_b32 s75, s75, 0x60
	v_addc_co_u32_e32 v23, vcc, 0, v19, vcc
	s_mov_b32 s35, 0xb0000
	s_or_b32 s78, s31, s75
	s_ashr_i32 s31, s30, 31
	v_add_co_u32_e32 v24, vcc, s35, v18
	s_lshl_b64 s[80:81], s[30:31], 2
	s_nop 0
	v_addc_co_u32_e32 v25, vcc, 0, v19, vcc
	s_mov_b32 s72, 0xdc000
	s_add_u32 s80, s18, s80
	v_add_co_u32_e32 v26, vcc, s72, v18
	s_addc_u32 s81, s19, s81
	v_mov_b32_e32 v32, s21
	v_mov_b32_e32 v33, s20
	v_addc_co_u32_e32 v27, vcc, 0, v19, vcc
	s_mov_b32 s73, 0x108000
	v_lshl_add_u64 v[30:31], s[80:81], 0, v[122:123]
	v_cndmask_b32_e64 v7, v3, v32, s[0:1]
	v_cndmask_b32_e64 v6, v2, v33, s[0:1]
	v_add_co_u32_e32 v28, vcc, s73, v18
	v_cndmask_b32_e64 v31, v31, v32, s[0:1]
	v_cndmask_b32_e64 v30, v30, v33, s[0:1]
	v_or_b32_e32 v34, s30, v130
	v_mov_b64_e32 v[32:33], s[20:21]
	v_addc_co_u32_e32 v29, vcc, 0, v19, vcc
	s_mov_b32 s74, 0x134000
	v_mad_i64_i32 v[32:33], s[30:31], v34, s24, v[32:33]
	s_ashr_i32 s79, s78, 31
	global_load_dwordx4 v[2:5], v[6:7], off offset:16 nt
	s_nop 0
	global_load_dwordx4 v[6:9], v[6:7], off nt
	s_nop 0
	global_load_dwordx4 v[14:17], v[18:19], off nt
	s_nop 0
	global_load_dwordx4 v[10:13], v[10:11], off nt
	v_add_co_u32_e32 v18, vcc, s74, v18
	v_lshl_add_u64 v[32:33], s[78:79], 2, v[32:33]
	s_nop 0
	v_addc_co_u32_e32 v19, vcc, 0, v19, vcc
	v_lshl_add_u64 v[32:33], v[32:33], 0, v[82:83]
	v_add_co_u32_e32 v34, vcc, s25, v32
	v_add_u32_e32 v82, s3, v82
	s_nop 0
	v_addc_co_u32_e32 v35, vcc, 0, v33, vcc
	v_add_co_u32_e32 v36, vcc, s33, v32
	v_mul_u32_u24_e32 v83, 0x84, v130
	s_nop 0
	v_addc_co_u32_e32 v37, vcc, 0, v33, vcc
	v_add_co_u32_e32 v38, vcc, s34, v32
	v_lshl_add_u64 v[124:125], s[18:19], 0, v[122:123]
	s_nop 0
	v_addc_co_u32_e32 v39, vcc, 0, v33, vcc
	v_add_co_u32_e32 v42, vcc, s35, v32
	s_add_i32 s18, s2, s71
	s_nop 0
	v_addc_co_u32_e32 v43, vcc, 0, v33, vcc
	v_add_co_u32_e32 v46, vcc, s72, v32
	v_lshlrev_b32_e32 v84, 2, v85
	s_nop 0
	v_addc_co_u32_e32 v47, vcc, 0, v33, vcc
	v_add_co_u32_e32 v50, vcc, s73, v32
	v_mul_u32_u24_e32 v86, 0x420, v85
	s_nop 0
	v_addc_co_u32_e32 v51, vcc, 0, v33, vcc
	v_add_co_u32_e32 v54, vcc, s74, v32
	v_lshlrev_b32_e32 v87, 2, v130
	s_nop 0
	v_addc_co_u32_e32 v55, vcc, 0, v33, vcc
	global_load_dwordx4 v[78:81], v[20:21], off nt
	global_load_dwordx4 v[74:77], v[22:23], off nt
	global_load_dwordx4 v[70:73], v[24:25], off nt
	global_load_dwordx4 v[66:69], v[26:27], off nt
	global_load_dwordx4 v[62:65], v[28:29], off nt
	global_load_dwordx4 v[58:61], v[18:19], off nt
	s_nop 0
	global_load_dwordx4 v[18:21], v[30:31], off offset:16 nt
	global_load_dwordx4 v[22:25], v[30:31], off nt
	global_load_dwordx4 v[26:29], v[32:33], off nt
	s_nop 0
	global_load_dwordx4 v[30:33], v[34:35], off nt
	s_nop 0
	global_load_dwordx4 v[34:37], v[36:37], off nt
	s_nop 0
	global_load_dwordx4 v[38:41], v[38:39], off nt
	s_nop 0
	global_load_dwordx4 v[42:45], v[42:43], off nt
	s_nop 0
	global_load_dwordx4 v[46:49], v[46:47], off nt
	s_nop 0
	global_load_dwordx4 v[50:53], v[50:51], off nt
	s_nop 0
	global_load_dwordx4 v[54:57], v[54:55], off nt
	v_add_u32_e32 v132, v82, v83
	s_lshl_b32 s18, s18, 3
	v_readlane_b32 s19, v252, 11
	v_lshlrev_b32_e32 v82, 3, v85
	v_add3_u32 v131, s3, v86, v87
	v_lshlrev_b32_e32 v122, 2, v84
	s_lshl_b32 s75, s71, 4
	s_mul_i32 s77, s71, 24
	s_add_i32 s78, s19, s18
	s_lshl_b32 s79, s71, 5
	v_lshlrev_b32_e32 v126, 1, v82
	s_mov_b32 s81, s70
	v_or_b32_e32 v133, 8, v130
	v_or_b32_e32 v134, 16, v130
	v_or_b32_e32 v135, 24, v130
	s_waitcnt vmcnt(10)
	s_waitcnt vmcnt(0)
	s_branch .LBB0_17

; #define LAS __attribute__((address_space(3)))
; __device__ __forceinline__ unsigned cvtpk(float lo, float hi) { f32x2_t v = {lo, hi}; bf16x2_t b = __builtin_convertvector(v, bf16x2_t); return __builtin_bit_cast(unsigned, b); }
; #define LDS_WAIT() asm volatile("s_waitcnt lgkmcnt(0)" ::: "memory")
; #define CONV_JOB(it_) conv_job<LIST>((it_) < n ? (it_) : n - 1, P)
; __device__ __forceinline__ void conv_fetch(const ConvJob& j, int lane, ConvSet& s) {
;     const int k0 = 64 * j.kb; int cnt; const int src = vgroup_src(j.kind, j.g, cnt);
;     const int ks = lane >> 3, n4 = (lane & 7) * 4, c = lane & 7; const bool okc = n4 < cnt;
;     const float* gp = j.gain ? j.gain + k0 + 8 * c : j.W;
;     s.g0 = *(const f32x4*)gp; s.g1 = *(const f32x4*)(gp + 4);
;     const float* wp = j.W + (size_t)(k0 + ks) * j.Norig + src + (okc ? n4 : 0);
; #pragma unroll
;     for (int i = 0; i < 8; ++i) s.v[i] = *(const f32x4*)(wp + (size_t)(8 * i) * j.Norig);
; }
; __device__ __forceinline__ void conv_emit(const ConvJob& j, int lane, const ConvSet& s, LAS float* scr) {
;     const int k0 = 64 * j.kb; int cnt; (void)vgroup_src(j.kind, j.g, cnt);
;     const int ks = lane >> 3, n4 = (lane & 7) * 4, c = lane & 7; const bool okc = n4 < cnt;
;     const f32x4 one = (f32x4){1.f, 1.f, 1.f, 1.f}; const f32x4 g0 = j.gain ? s.g0 : one, g1 = j.gain ? s.g1 : one;
; #pragma unroll
;     for (int i = 0; i < 8; ++i) { LAS float* sp = scr + (8 * i + ks) * 33 + n4;
; #pragma unroll
;         for (int e = 0; e < 4; ++e) sp[e] = okc ? s.v[i][e] : 0.f; }
;     LDS_WAIT(); asm volatile("" ::: "memory");
; #pragma unroll
;     for (int q = 0; q < 4; ++q) { const int nn = (lane >> 3) + 8 * q; const LAS float* sr = scr + (8 * c) * 33 + nn;
;         u32x4 o; o.x = cvtpk(sr[0 * 33] * g0[0], sr[1 * 33] * g0[1]); o.y = cvtpk(sr[2 * 33] * g0[2], sr[3 * 33] * g0[3]); o.z = cvtpk(sr[4 * 33] * g1[0], sr[5 * 33] * g1[1]); o.w = cvtpk(sr[6 * 33] * g1[2], sr[7 * 33] * g1[3]);
;         *(u32x4*)(j.WT + (size_t)(j.g * 32 + nn) * j.K + k0 + 8 * c) = o; }
;     LDS_WAIT(); asm volatile("" ::: "memory");
; }
; template <int LIST> __device__ __forceinline__ void convert_list(int first, int stride, const Params& P, LAS float* scr, int lane) {
;     ...
;     for (int it = first; it < n; it += 3 * stride) {
;         conv_fetch(CONV_JOB(it + 2 * stride), lane, C); conv_emit(CONV_JOB(it), lane, A, scr);
.LBB0_17:
	s_add_i32 s80, s81, s75
	s_cmpk_lt_i32 s80, 0xb00
	s_cselect_b64 s[18:19], -1, 0
	s_and_b64 s[30:31], s[18:19], exec
	s_cselect_b32 s30, s80, 0xaff
	s_mul_hi_i32 s31, s30, 0x2e8ba2e9
	s_lshr_b32 s82, s31, 31
	s_ashr_i32 s31, s31, 5
	s_add_i32 s31, s31, s82
	s_mul_i32 s82, s31, 0xb0
	s_sub_i32 s82, s30, s82
	s_lshl_b32 s30, s31, 6
	s_bfe_i32 s31, s82, 0x10002
	s_lshl_b32 s83, s82, 4
	s_and_b32 s31, s31, 0xb00
	s_and_b32 s83, s83, 0xffffff80
	s_lshl_b32 s82, s82, 5
	s_add_i32 s31, s31, s83
	s_and_b32 s82, s82, 0x60
	s_or_b32 s82, s31, s82
	s_ashr_i32 s31, s30, 31
	s_waitcnt vmcnt(31)
	v_or_b32_e32 v90, s30, v130
	v_mov_b64_e32 v[128:129], s[20:21]
	v_lshl_add_u64 v[82:83], s[30:31], 2, v[124:125]
	v_mad_i64_i32 v[90:91], s[30:31], v90, s24, v[128:129]
	s_ashr_i32 s83, s82, 31
	v_lshl_add_u64 v[90:91], s[82:83], 2, v[90:91]
	s_waitcnt vmcnt(26)
	v_lshl_add_u64 v[106:107], v[90:91], 0, v[122:123]
	v_add_co_u32_e32 v94, vcc, s25, v106
	v_mov_b32_e32 v150, s21
	s_nop 0
	v_addc_co_u32_e32 v95, vcc, 0, v107, vcc
	v_add_co_u32_e32 v98, vcc, s33, v106
	v_mov_b32_e32 v151, s20
	s_nop 0
	v_addc_co_u32_e32 v99, vcc, 0, v107, vcc
	v_add_co_u32_e32 v102, vcc, s34, v106
	v_cndmask_b32_e64 v87, v83, v150, s[0:1]
	s_nop 0
	v_addc_co_u32_e32 v103, vcc, 0, v107, vcc
	v_add_co_u32_e32 v108, vcc, s35, v106
	v_cndmask_b32_e64 v86, v82, v151, s[0:1]
	s_nop 0
	v_addc_co_u32_e32 v109, vcc, 0, v107, vcc
	s_waitcnt vmcnt(24)
	v_add_co_u32_e32 v114, vcc, s72, v106
	v_add_u32_e32 v136, 0x420, v132
	s_nop 0
	v_addc_co_u32_e32 v115, vcc, 0, v107, vcc
	v_add_co_u32_e32 v116, vcc, s73, v106
	v_add_u32_e32 v137, 0x428, v132
	s_nop 0
	v_addc_co_u32_e32 v117, vcc, 0, v107, vcc
	v_add_co_u32_e32 v138, vcc, s74, v106
	global_load_dwordx4 v[82:85], v[86:87], off offset:16 nt
	s_nop 0
	global_load_dwordx4 v[86:89], v[86:87], off nt
	s_nop 0
	global_load_dwordx4 v[90:93], v[106:107], off nt
	s_nop 0
	global_load_dwordx4 v[94:97], v[94:95], off nt
	s_nop 0
	global_load_dwordx4 v[98:101], v[98:99], off nt
	s_nop 0
	global_load_dwordx4 v[102:105], v[102:103], off nt
	v_addc_co_u32_e32 v139, vcc, 0, v107, vcc
	global_load_dwordx4 v[110:113], v[108:109], off nt
	s_nop 0
	global_load_dwordx4 v[106:109], v[114:115], off nt
	s_waitcnt vmcnt(25)
	ds_write2_b32 v132, v14, v15 offset1:1
	ds_write2_b32 v132, v16, v17 offset0:2 offset1:3
	s_waitcnt vmcnt(24)
	ds_write2_b32 v136, v10, v11 offset1:1
	ds_write2_b32 v137, v12, v13 offset1:1
	global_load_dwordx4 v[118:121], v[116:117], off nt
	s_nop 0
	global_load_dwordx4 v[114:117], v[138:139], off nt
	v_add_u32_e32 v138, 0x840, v132
	v_add_u32_e32 v139, 0x848, v132
	v_add_u32_e32 v140, 0xc60, v132
	v_add_u32_e32 v141, 0xc68, v132
	v_add_u32_e32 v142, 0x1080, v132
	v_add_u32_e32 v143, 0x1088, v132
	v_add_u32_e32 v144, 0x14a0, v132
	v_add_u32_e32 v145, 0x14a8, v132
	v_add_u32_e32 v146, 0x18c0, v132
	v_add_u32_e32 v147, 0x18c8, v132
	v_add_u32_e32 v148, 0x1ce0, v132
	v_add_u32_e32 v149, 0x1ce8, v132
	s_waitcnt vmcnt(25)
	ds_write2_b32 v138, v78, v79 offset1:1
	ds_write2_b32 v139, v80, v81 offset1:1
	s_waitcnt vmcnt(24)
	ds_write2_b32 v140, v74, v75 offset1:1
	ds_write2_b32 v141, v76, v77 offset1:1
	s_waitcnt vmcnt(23)
	ds_write2_b32 v142, v70, v71 offset1:1
	ds_write2_b32 v143, v72, v73 offset1:1
	s_waitcnt vmcnt(22)
	ds_write2_b32 v144, v66, v67 offset1:1
	ds_write2_b32 v145, v68, v69 offset1:1
	s_waitcnt vmcnt(21)
	ds_write2_b32 v146, v62, v63 offset1:1
	ds_write2_b32 v147, v64, v65 offset1:1
	s_waitcnt vmcnt(20)
	ds_write2_b32 v148, v58, v59 offset1:1
	ds_write2_b32 v149, v60, v61 offset1:1
	s_waitcnt lgkmcnt(0)
	ds_read2_b32 v[12:13], v131 offset1:8
	ds_read2_b32 v[16:17], v131 offset0:33 offset1:41
	ds_read2_b32 v[58:59], v131 offset0:66 offset1:74
	ds_read2_b32 v[60:61], v131 offset0:99 offset1:107
	ds_read2_b32 v[62:63], v131 offset0:132 offset1:140
	ds_read2_b32 v[64:65], v131 offset0:165 offset1:173
	ds_read2_b32 v[66:67], v131 offset0:198 offset1:206
	ds_read2_b32 v[68:69], v131 offset0:231 offset1:239
	s_mul_hi_i32 s30, s81, 0x2e8ba2e9
	s_lshr_b32 s31, s30, 31
	s_ashr_i32 s30, s30, 5
	v_cndmask_b32_e64 v9, v9, 1.0, s[0:1]
	v_cndmask_b32_e64 v8, v8, 1.0, s[0:1]
	v_cndmask_b32_e64 v7, v7, 1.0, s[0:1]
	v_cndmask_b32_e64 v6, v6, 1.0, s[0:1]
	v_cndmask_b32_e64 v11, v5, 1.0, s[0:1]
	v_cndmask_b32_e64 v10, v4, 1.0, s[0:1]
	v_cndmask_b32_e64 v15, v3, 1.0, s[0:1]
	v_cndmask_b32_e64 v14, v2, 1.0, s[0:1]
	s_waitcnt lgkmcnt(7)
	v_mov_b32_e32 v2, v12
	s_waitcnt lgkmcnt(6)
	v_mov_b32_e32 v3, v16
	s_waitcnt lgkmcnt(5)
	v_mov_b32_e32 v4, v58
	s_waitcnt lgkmcnt(4)
	v_mov_b32_e32 v5, v60
	s_add_i32 s30, s30, s31
	v_pk_mul_f32 v[2:3], v[6:7], v[2:3]
	v_pk_mul_f32 v[4:5], v[8:9], v[4:5]
	s_mul_i32 s31, s30, 0xb0
	v_cvt_pk_bf16_f32 v2, v2, v3
	v_cvt_pk_bf16_f32 v3, v4, v5
	s_waitcnt lgkmcnt(3)
	v_mov_b32_e32 v4, v62
	s_waitcnt lgkmcnt(2)
	v_mov_b32_e32 v5, v64
	s_waitcnt lgkmcnt(1)
	v_mov_b32_e32 v70, v66
	s_waitcnt lgkmcnt(0)
; #define LAS __attribute__((address_space(3)))
; __device__ __forceinline__ unsigned cvtpk(float lo, float hi) { f32x2_t v = {lo, hi}; bf16x2_t b = __builtin_convertvector(v, bf16x2_t); return __builtin_bit_cast(unsigned, b); }
; #define LDS_WAIT() asm volatile("s_waitcnt lgkmcnt(0)" ::: "memory")
; #define CONV_JOB(it_) conv_job<LIST>((it_) < n ? (it_) : n - 1, P)
; __device__ __forceinline__ void conv_emit(const ConvJob& j, int lane, const ConvSet& s, LAS float* scr) {
;     const int k0 = 64 * j.kb; int cnt; (void)vgroup_src(j.kind, j.g, cnt);
;     const int ks = lane >> 3, n4 = (lane & 7) * 4, c = lane & 7; const bool okc = n4 < cnt;
;     const f32x4 one = (f32x4){1.f, 1.f, 1.f, 1.f}; const f32x4 g0 = j.gain ? s.g0 : one, g1 = j.gain ? s.g1 : one;
; #pragma unroll
;     for (int i = 0; i < 8; ++i) { LAS float* sp = scr + (8 * i + ks) * 33 + n4;
; #pragma unroll
;         for (int e = 0; e < 4; ++e) sp[e] = okc ? s.v[i][e] : 0.f; }
;     LDS_WAIT(); asm volatile("" ::: "memory");
; #pragma unroll
;     for (int q = 0; q < 4; ++q) { const int nn = (lane >> 3) + 8 * q; const LAS float* sr = scr + (8 * c) * 33 + nn;
;         u32x4 o; o.x = cvtpk(sr[0 * 33] * g0[0], sr[1 * 33] * g0[1]); o.y = cvtpk(sr[2 * 33] * g0[2], sr[3 * 33] * g0[3]); o.z = cvtpk(sr[4 * 33] * g1[0], sr[5 * 33] * g1[1]); o.w = cvtpk(sr[6 * 33] * g1[2], sr[7 * 33] * g1[3]);
;         *(u32x4*)(j.WT + (size_t)(j.g * 32 + nn) * j.K + k0 + 8 * c) = o; }
;     LDS_WAIT(); asm volatile("" ::: "memory");
; }
; template <int LIST> __device__ __forceinline__ void convert_list(int first, int stride, const Params& P, LAS float* scr, int lane) {
;     ...
;         conv_fetch(CONV_JOB(it + 3 * stride), lane, A); if (it + stride < n) conv_emit(CONV_JOB(it + stride), lane, B, scr);
	v_mov_b32_e32 v71, v68
	s_sub_i32 s82, s81, s31
	v_pk_mul_f32 v[4:5], v[14:15], v[4:5]
	v_pk_mul_f32 v[70:71], v[10:11], v[70:71]
	s_lshl_b32 s82, s82, 5
	v_cvt_pk_bf16_f32 v4, v4, v5
	v_cvt_pk_bf16_f32 v5, v70, v71
	v_or_b32_e32 v70, s82, v130
	s_lshl_b32 s30, s30, 6
	v_ashrrev_i32_e32 v71, 31, v70
	s_ashr_i32 s31, s30, 31
	v_lshlrev_b64 v[70:71], 11, v[70:71]
	v_lshl_add_u64 v[70:71], s[50:51], 0, v[70:71]
	s_lshl_b64 s[30:31], s[30:31], 1
	v_lshl_add_u64 v[70:71], v[70:71], 0, s[30:31]
	v_mov_b32_e32 v127, v123
	v_lshl_add_u64 v[70:71], v[70:71], 0, v[126:127]
	v_mov_b32_e32 v16, v13
	v_mov_b32_e32 v60, v59
	global_store_dwordx4 v[70:71], v[2:5], off
	v_mov_b32_e32 v64, v63
	v_mov_b32_e32 v68, v67
	v_pk_mul_f32 v[2:3], v[6:7], v[16:17]
	v_pk_mul_f32 v[4:5], v[8:9], v[60:61]
	v_cvt_pk_bf16_f32 v2, v2, v3
	v_cvt_pk_bf16_f32 v3, v4, v5
	v_pk_mul_f32 v[4:5], v[14:15], v[64:65]
	v_pk_mul_f32 v[12:13], v[10:11], v[68:69]
	v_cvt_pk_bf16_f32 v4, v4, v5
	v_cvt_pk_bf16_f32 v5, v12, v13
	v_or_b32_e32 v12, s82, v133
	v_ashrrev_i32_e32 v13, 31, v12
	v_lshlrev_b64 v[12:13], 11, v[12:13]
	v_lshl_add_u64 v[12:13], s[50:51], 0, v[12:13]
	v_lshl_add_u64 v[12:13], v[12:13], 0, s[30:31]
	v_lshl_add_u64 v[12:13], v[12:13], 0, v[126:127]
	global_store_dwordx4 v[12:13], v[2:5], off
	ds_read2_b32 v[16:17], v131 offset0:16 offset1:24
	ds_read2_b32 v[58:59], v131 offset0:49 offset1:57
	ds_read2_b32 v[12:13], v131 offset0:82 offset1:90
	ds_read2_b32 v[60:61], v131 offset0:115 offset1:123
	ds_read2_b32 v[62:63], v131 offset0:148 offset1:156
	ds_read2_b32 v[64:65], v131 offset0:181 offset1:189
	ds_read2_b32 v[66:67], v131 offset0:214 offset1:222
	ds_read2_b32 v[68:69], v131 offset0:247 offset1:255
	s_waitcnt lgkmcnt(7)
	v_mov_b32_e32 v2, v16
	s_waitcnt lgkmcnt(6)
	v_mov_b32_e32 v3, v58
	s_waitcnt lgkmcnt(5)
	v_mov_b32_e32 v4, v12
	s_waitcnt lgkmcnt(4)
	v_mov_b32_e32 v5, v60
	v_pk_mul_f32 v[2:3], v[6:7], v[2:3]
	v_pk_mul_f32 v[4:5], v[8:9], v[4:5]
	v_cvt_pk_bf16_f32 v2, v2, v3
	v_cvt_pk_bf16_f32 v3, v4, v5
	s_waitcnt lgkmcnt(3)
	v_mov_b32_e32 v4, v62
	s_waitcnt lgkmcnt(2)
	v_mov_b32_e32 v5, v64
	s_waitcnt lgkmcnt(1)
	v_mov_b32_e32 v70, v66
	s_waitcnt lgkmcnt(0)
	v_mov_b32_e32 v71, v68
	v_pk_mul_f32 v[4:5], v[14:15], v[4:5]
	v_pk_mul_f32 v[70:71], v[10:11], v[70:71]
	v_cvt_pk_bf16_f32 v4, v4, v5
	v_cvt_pk_bf16_f32 v5, v70, v71
	v_or_b32_e32 v70, s82, v134
	v_ashrrev_i32_e32 v71, 31, v70
	v_lshlrev_b64 v[70:71], 11, v[70:71]
	v_lshl_add_u64 v[70:71], s[50:51], 0, v[70:71]
	v_lshl_add_u64 v[70:71], v[70:71], 0, s[30:31]
	v_lshl_add_u64 v[70:71], v[70:71], 0, v[126:127]
	v_mov_b32_e32 v58, v17
	v_mov_b32_e32 v60, v13
	global_store_dwordx4 v[70:71], v[2:5], off
	v_mov_b32_e32 v64, v63
	v_mov_b32_e32 v68, v67
	v_pk_mul_f32 v[2:3], v[6:7], v[58:59]
	v_pk_mul_f32 v[4:5], v[8:9], v[60:61]
	v_cvt_pk_bf16_f32 v2, v2, v3
	v_cvt_pk_bf16_f32 v3, v4, v5
	v_pk_mul_f32 v[4:5], v[14:15], v[64:65]
	v_pk_mul_f32 v[6:7], v[10:11], v[68:69]
	v_cvt_pk_bf16_f32 v4, v4, v5
	v_cvt_pk_bf16_f32 v5, v6, v7
	v_or_b32_e32 v6, s82, v135
	v_ashrrev_i32_e32 v7, 31, v6
	v_lshlrev_b64 v[6:7], 11, v[6:7]
	v_lshl_add_u64 v[6:7], s[50:51], 0, v[6:7]
	v_lshl_add_u64 v[6:7], v[6:7], 0, s[30:31]
	s_add_i32 s30, s77, s81
	s_min_i32 s30, s30, 0xaff
	s_mul_hi_i32 s31, s30, 0x2e8ba2e9
	s_lshr_b32 s82, s31, 31
	s_ashr_i32 s31, s31, 5
	s_add_i32 s31, s31, s82
	s_mul_i32 s82, s31, 0xb0
	s_sub_i32 s82, s30, s82
	s_lshl_b32 s30, s31, 6
	s_bfe_i32 s31, s82, 0x10002
	s_lshl_b32 s83, s82, 4
	s_and_b32 s31, s31, 0xb00
	s_and_b32 s83, s83, 0xffffff80
	s_lshl_b32 s82, s82, 5
	s_add_i32 s31, s31, s83
	s_and_b32 s82, s82, 0x60
	v_lshl_add_u64 v[6:7], v[6:7], 0, v[126:127]
	s_or_b32 s82, s31, s82
	s_ashr_i32 s31, s30, 31
	v_or_b32_e32 v10, s30, v130
	global_store_dwordx4 v[6:7], v[2:5], off
	s_ashr_i32 s83, s82, 31
	s_waitcnt lgkmcnt(0)
	s_cmpk_gt_i32 s78, 0xaff
	v_lshl_add_u64 v[2:3], s[30:31], 2, v[124:125]
	v_mad_i64_i32 v[10:11], s[30:31], v10, s24, v[128:129]
	v_lshl_add_u64 v[10:11], s[82:83], 2, v[10:11]
	v_lshl_add_u64 v[10:11], v[10:11], 0, v[122:123]
	v_add_co_u32_e32 v12, vcc, s25, v10
	v_cndmask_b32_e64 v7, v3, v150, s[0:1]
	s_nop 0
	v_addc_co_u32_e32 v13, vcc, 0, v11, vcc
	v_add_co_u32_e32 v58, vcc, s33, v10
	v_cndmask_b32_e64 v6, v2, v151, s[0:1]
	s_nop 0
	v_addc_co_u32_e32 v59, vcc, 0, v11, vcc
	v_add_co_u32_e32 v60, vcc, s34, v10
	global_load_dwordx4 v[2:5], v[6:7], off offset:16 nt
	s_nop 0
	global_load_dwordx4 v[6:9], v[6:7], off nt
	v_addc_co_u32_e32 v61, vcc, 0, v11, vcc
	v_add_co_u32_e32 v62, vcc, s35, v10
	s_nop 1
	v_addc_co_u32_e32 v63, vcc, 0, v11, vcc
	v_add_co_u32_e32 v64, vcc, 0xdc000, v10
	s_nop 1
	v_addc_co_u32_e32 v65, vcc, 0, v11, vcc
	v_add_co_u32_e32 v128, vcc, 0x108000, v10
	s_nop 1
	v_addc_co_u32_e32 v129, vcc, 0, v11, vcc
	v_add_co_u32_e32 v150, vcc, 0x134000, v10
	s_nop 1
	v_addc_co_u32_e32 v151, vcc, 0, v11, vcc
	global_load_dwordx4 v[14:17], v[10:11], off nt
	s_nop 0
	global_load_dwordx4 v[10:13], v[12:13], off nt
	s_nop 0
	global_load_dwordx4 v[78:81], v[58:59], off nt
	global_load_dwordx4 v[74:77], v[60:61], off nt
	global_load_dwordx4 v[70:73], v[62:63], off nt
	global_load_dwordx4 v[66:69], v[64:65], off nt
	s_nop 0
	global_load_dwordx4 v[62:65], v[128:129], off nt
	global_load_dwordx4 v[58:61], v[150:151], off nt
	s_cbranch_scc1 .LBB0_19
; #define LAS __attribute__((address_space(3)))
; __device__ __forceinline__ unsigned cvtpk(float lo, float hi) { f32x2_t v = {lo, hi}; bf16x2_t b = __builtin_convertvector(v, bf16x2_t); return __builtin_bit_cast(unsigned, b); }
; #define LDS_WAIT() asm volatile("s_waitcnt lgkmcnt(0)" ::: "memory")
; #define CONV_JOB(it_) conv_job<LIST>((it_) < n ? (it_) : n - 1, P)
; __device__ __forceinline__ void conv_emit(const ConvJob& j, int lane, const ConvSet& s, LAS float* scr) {
;     const int k0 = 64 * j.kb; int cnt; (void)vgroup_src(j.kind, j.g, cnt);
;     const int ks = lane >> 3, n4 = (lane & 7) * 4, c = lane & 7; const bool okc = n4 < cnt;
;     const f32x4 one = (f32x4){1.f, 1.f, 1.f, 1.f}; const f32x4 g0 = j.gain ? s.g0 : one, g1 = j.gain ? s.g1 : one;
; #pragma unroll
;     for (int i = 0; i < 8; ++i) { LAS float* sp = scr + (8 * i + ks) * 33 + n4;
; #pragma unroll
;         for (int e = 0; e < 4; ++e) sp[e] = okc ? s.v[i][e] : 0.f; }
;     LDS_WAIT(); asm volatile("" ::: "memory");
; #pragma unroll
;     for (int q = 0; q < 4; ++q) { const int nn = (lane >> 3) + 8 * q; const LAS float* sr = scr + (8 * c) * 33 + nn;
;         u32x4 o; o.x = cvtpk(sr[0 * 33] * g0[0], sr[1 * 33] * g0[1]); o.y = cvtpk(sr[2 * 33] * g0[2], sr[3 * 33] * g0[3]); o.z = cvtpk(sr[4 * 33] * g1[0], sr[5 * 33] * g1[1]); o.w = cvtpk(sr[6 * 33] * g1[2], sr[7 * 33] * g1[3]);
;         *(u32x4*)(j.WT + (size_t)(j.g * 32 + nn) * j.K + k0 + 8 * c) = o; }
;     LDS_WAIT(); asm volatile("" ::: "memory");
; }
; template <int LIST> __device__ __forceinline__ void convert_list(int first, int stride, const Params& P, LAS float* scr, int lane) {
;     ...
;         conv_fetch(CONV_JOB(it + 3 * stride), lane, A); if (it + stride < n) conv_emit(CONV_JOB(it + stride), lane, B, scr);
	s_waitcnt vmcnt(31)
	ds_write2_b32 v132, v26, v27 offset1:1
	ds_write2_b32 v132, v28, v29 offset0:2 offset1:3
	s_waitcnt vmcnt(30)
	ds_write2_b32 v136, v30, v31 offset1:1
	ds_write2_b32 v137, v32, v33 offset1:1
	s_waitcnt vmcnt(29)
	ds_write2_b32 v138, v34, v35 offset1:1
	ds_write2_b32 v139, v36, v37 offset1:1
	s_waitcnt vmcnt(28)
	ds_write2_b32 v140, v38, v39 offset1:1
	ds_write2_b32 v141, v40, v41 offset1:1
	s_waitcnt vmcnt(27)
	ds_write2_b32 v142, v42, v43 offset1:1
	ds_write2_b32 v143, v44, v45 offset1:1
	s_waitcnt vmcnt(26)
	ds_write2_b32 v144, v46, v47 offset1:1
	ds_write2_b32 v145, v48, v49 offset1:1
	s_waitcnt vmcnt(25)
	ds_write2_b32 v146, v50, v51 offset1:1
	ds_write2_b32 v147, v52, v53 offset1:1
	s_waitcnt vmcnt(24)
	ds_write2_b32 v148, v54, v55 offset1:1
	ds_write2_b32 v149, v56, v57 offset1:1
	s_waitcnt lgkmcnt(0)
	ds_read2_b32 v[28:29], v131 offset1:8
	ds_read2_b32 v[32:33], v131 offset0:33 offset1:41
	ds_read2_b32 v[34:35], v131 offset0:66 offset1:74
	ds_read2_b32 v[36:37], v131 offset0:99 offset1:107
	ds_read2_b32 v[38:39], v131 offset0:132 offset1:140
	ds_read2_b32 v[40:41], v131 offset0:165 offset1:173
	ds_read2_b32 v[42:43], v131 offset0:198 offset1:206
	ds_read2_b32 v[44:45], v131 offset0:231 offset1:239
	s_mul_hi_i32 s30, s78, 0x2e8ba2e9
	s_lshr_b32 s31, s30, 31
	s_ashr_i32 s30, s30, 5
	s_add_i32 s30, s30, s31
	v_cndmask_b32_e64 v25, v25, 1.0, s[0:1]
	v_cndmask_b32_e64 v24, v24, 1.0, s[0:1]
	v_cndmask_b32_e64 v23, v23, 1.0, s[0:1]
	v_cndmask_b32_e64 v22, v22, 1.0, s[0:1]
	v_cndmask_b32_e64 v27, v21, 1.0, s[0:1]
	v_cndmask_b32_e64 v26, v20, 1.0, s[0:1]
	v_cndmask_b32_e64 v31, v19, 1.0, s[0:1]
	v_cndmask_b32_e64 v30, v18, 1.0, s[0:1]
	s_waitcnt lgkmcnt(7)
	v_mov_b32_e32 v18, v28
	s_waitcnt lgkmcnt(6)
	v_mov_b32_e32 v19, v32
	s_waitcnt lgkmcnt(5)
	v_mov_b32_e32 v20, v34
	s_waitcnt lgkmcnt(4)
	v_mov_b32_e32 v21, v36
	s_mul_i32 s31, s30, 0xb0
	v_pk_mul_f32 v[18:19], v[22:23], v[18:19]
	v_pk_mul_f32 v[20:21], v[24:25], v[20:21]
	s_sub_i32 s82, s78, s31
	v_cvt_pk_bf16_f32 v18, v18, v19
	v_cvt_pk_bf16_f32 v19, v20, v21
	s_waitcnt lgkmcnt(3)
	v_mov_b32_e32 v20, v38
	s_waitcnt lgkmcnt(2)
	v_mov_b32_e32 v21, v40
	s_waitcnt lgkmcnt(1)
	v_mov_b32_e32 v46, v42
	s_waitcnt lgkmcnt(0)
	v_mov_b32_e32 v47, v44
	v_pk_mul_f32 v[20:21], v[30:31], v[20:21]
	v_pk_mul_f32 v[46:47], v[26:27], v[46:47]
	s_lshl_b32 s82, s82, 5
	v_cvt_pk_bf16_f32 v20, v20, v21
	v_cvt_pk_bf16_f32 v21, v46, v47
	v_or_b32_e32 v46, s82, v130
	s_lshl_b32 s30, s30, 6
	v_ashrrev_i32_e32 v47, 31, v46
	s_ashr_i32 s31, s30, 31
	v_lshlrev_b64 v[46:47], 11, v[46:47]
	v_lshl_add_u64 v[46:47], s[50:51], 0, v[46:47]
	s_lshl_b64 s[30:31], s[30:31], 1
	v_lshl_add_u64 v[46:47], v[46:47], 0, s[30:31]
	v_lshl_add_u64 v[46:47], v[46:47], 0, v[126:127]
	v_mov_b32_e32 v32, v29
	v_mov_b32_e32 v36, v35
	global_store_dwordx4 v[46:47], v[18:21], off
	v_mov_b32_e32 v40, v39
	v_mov_b32_e32 v44, v43
	v_pk_mul_f32 v[18:19], v[22:23], v[32:33]
	v_pk_mul_f32 v[20:21], v[24:25], v[36:37]
	v_cvt_pk_bf16_f32 v18, v18, v19
	v_cvt_pk_bf16_f32 v19, v20, v21
	v_pk_mul_f32 v[20:21], v[30:31], v[40:41]
	v_pk_mul_f32 v[28:29], v[26:27], v[44:45]
	v_cvt_pk_bf16_f32 v20, v20, v21
	v_cvt_pk_bf16_f32 v21, v28, v29
	v_or_b32_e32 v28, s82, v133
	v_ashrrev_i32_e32 v29, 31, v28
	v_lshlrev_b64 v[28:29], 11, v[28:29]
	v_lshl_add_u64 v[28:29], s[50:51], 0, v[28:29]
	v_lshl_add_u64 v[28:29], v[28:29], 0, s[30:31]
	v_lshl_add_u64 v[28:29], v[28:29], 0, v[126:127]
	ds_read2_b32 v[32:33], v131 offset0:16 offset1:24
	ds_read2_b32 v[34:35], v131 offset0:49 offset1:57
	global_store_dwordx4 v[28:29], v[18:21], off
	ds_read2_b32 v[28:29], v131 offset0:82 offset1:90
	ds_read2_b32 v[36:37], v131 offset0:115 offset1:123
	ds_read2_b32 v[38:39], v131 offset0:148 offset1:156
	ds_read2_b32 v[40:41], v131 offset0:181 offset1:189
	ds_read2_b32 v[42:43], v131 offset0:214 offset1:222
	ds_read2_b32 v[44:45], v131 offset0:247 offset1:255
	s_waitcnt lgkmcnt(7)
	v_mov_b32_e32 v18, v32
	s_waitcnt lgkmcnt(6)
	v_mov_b32_e32 v19, v34
	s_waitcnt lgkmcnt(5)
	v_mov_b32_e32 v20, v28
	s_waitcnt lgkmcnt(4)
	v_mov_b32_e32 v21, v36
	v_pk_mul_f32 v[18:19], v[22:23], v[18:19]
	v_pk_mul_f32 v[20:21], v[24:25], v[20:21]
	v_cvt_pk_bf16_f32 v18, v18, v19
	v_cvt_pk_bf16_f32 v19, v20, v21
	s_waitcnt lgkmcnt(3)
	v_mov_b32_e32 v20, v38
	s_waitcnt lgkmcnt(2)
	v_mov_b32_e32 v21, v40
	s_waitcnt lgkmcnt(1)
	v_mov_b32_e32 v46, v42
	s_waitcnt lgkmcnt(0)
	v_mov_b32_e32 v47, v44
	v_pk_mul_f32 v[20:21], v[30:31], v[20:21]
	v_pk_mul_f32 v[46:47], v[26:27], v[46:47]
	v_cvt_pk_bf16_f32 v20, v20, v21
	v_cvt_pk_bf16_f32 v21, v46, v47
	v_or_b32_e32 v46, s82, v134
	v_ashrrev_i32_e32 v47, 31, v46
	v_lshlrev_b64 v[46:47], 11, v[46:47]
	v_lshl_add_u64 v[46:47], s[50:51], 0, v[46:47]
	v_lshl_add_u64 v[46:47], v[46:47], 0, s[30:31]
	v_lshl_add_u64 v[46:47], v[46:47], 0, v[126:127]
	v_mov_b32_e32 v34, v33
	v_mov_b32_e32 v36, v29
	global_store_dwordx4 v[46:47], v[18:21], off
	v_mov_b32_e32 v40, v39
	v_mov_b32_e32 v44, v43
	v_pk_mul_f32 v[18:19], v[22:23], v[34:35]
	v_pk_mul_f32 v[20:21], v[24:25], v[36:37]
	v_cvt_pk_bf16_f32 v18, v18, v19
	v_cvt_pk_bf16_f32 v19, v20, v21
	v_pk_mul_f32 v[20:21], v[30:31], v[40:41]
	v_pk_mul_f32 v[22:23], v[26:27], v[44:45]
	v_cvt_pk_bf16_f32 v20, v20, v21
	v_cvt_pk_bf16_f32 v21, v22, v23
	v_or_b32_e32 v22, s82, v135
	v_ashrrev_i32_e32 v23, 31, v22
	v_lshlrev_b64 v[22:23], 11, v[22:23]
	v_lshl_add_u64 v[22:23], s[50:51], 0, v[22:23]
	v_lshl_add_u64 v[22:23], v[22:23], 0, s[30:31]
	v_lshl_add_u64 v[22:23], v[22:23], 0, v[126:127]
	global_store_dwordx4 v[22:23], v[18:21], off
	s_waitcnt lgkmcnt(0)
; #define CONV_JOB(it_) conv_job<LIST>((it_) < n ? (it_) : n - 1, P)
; __device__ __forceinline__ void conv_fetch(const ConvJob& j, int lane, ConvSet& s) {
;     const int k0 = 64 * j.kb; int cnt; const int src = vgroup_src(j.kind, j.g, cnt);
;     const int ks = lane >> 3, n4 = (lane & 7) * 4, c = lane & 7; const bool okc = n4 < cnt;
;     const float* gp = j.gain ? j.gain + k0 + 8 * c : j.W;
;     s.g0 = *(const f32x4*)gp; s.g1 = *(const f32x4*)(gp + 4);
;     const float* wp = j.W + (size_t)(k0 + ks) * j.Norig + src + (okc ? n4 : 0);
; #pragma unroll
;     for (int i = 0; i < 8; ++i) s.v[i] = *(const f32x4*)(wp + (size_t)(8 * i) * j.Norig);
; }
; template <int LIST> __device__ __forceinline__ void convert_list(int first, int stride, const Params& P, LAS float* scr, int lane) {
;     ...
;         conv_fetch(CONV_JOB(it + 4 * stride), lane, B); if (it + 2 * stride < n) conv_emit(CONV_JOB(it + 2 * stride), lane, C, scr);
.LBB0_19:
	s_add_i32 s30, s79, s81
	s_min_i32 s30, s30, 0xaff
	s_mul_hi_i32 s31, s30, 0x2e8ba2e9
	s_lshr_b32 s81, s31, 31
	s_ashr_i32 s31, s31, 5
	s_add_i32 s31, s31, s81
	s_mul_i32 s81, s31, 0xb0
	s_sub_i32 s81, s30, s81
	s_lshl_b32 s30, s31, 6
	s_bfe_i32 s31, s81, 0x10002
	s_lshl_b32 s82, s81, 4
	s_and_b32 s31, s31, 0xb00
	s_and_b32 s82, s82, 0xffffff80
	s_lshl_b32 s81, s81, 5
	s_add_i32 s31, s31, s82
	s_and_b32 s81, s81, 0x60
	s_or_b32 s82, s31, s81
	s_ashr_i32 s31, s30, 31
	s_waitcnt vmcnt(31)
	v_or_b32_e32 v28, s30, v130
	v_mov_b64_e32 v[26:27], s[20:21]
	v_lshl_add_u64 v[18:19], s[30:31], 2, v[124:125]
	v_mad_i64_i32 v[26:27], s[30:31], v28, s24, v[26:27]
	s_ashr_i32 s83, s82, 31
	v_lshl_add_u64 v[26:27], s[82:83], 2, v[26:27]
	s_waitcnt vmcnt(25)
	v_lshl_add_u64 v[50:51], v[26:27], 0, v[122:123]
	v_add_co_u32_e32 v30, vcc, s25, v50
	v_mov_b32_e32 v20, s21
	s_nop 0
	v_addc_co_u32_e32 v31, vcc, 0, v51, vcc
	v_add_co_u32_e32 v34, vcc, s33, v50
	v_cndmask_b32_e64 v23, v19, v20, s[0:1]
	s_nop 0
	v_addc_co_u32_e32 v35, vcc, 0, v51, vcc
	v_add_co_u32_e32 v38, vcc, s34, v50
	v_mov_b32_e32 v19, s20
	s_nop 0
	v_addc_co_u32_e32 v39, vcc, 0, v51, vcc
	v_add_co_u32_e32 v42, vcc, s35, v50
	v_cndmask_b32_e64 v22, v18, v19, s[0:1]
	s_nop 0
	v_addc_co_u32_e32 v43, vcc, 0, v51, vcc
	v_add_co_u32_e32 v46, vcc, 0xdc000, v50
	global_load_dwordx4 v[18:21], v[22:23], off offset:16 nt
	s_nop 0
	global_load_dwordx4 v[22:25], v[22:23], off nt
	v_addc_co_u32_e32 v47, vcc, 0, v51, vcc
	v_add_co_u32_e32 v52, vcc, 0x108000, v50
	global_load_dwordx4 v[26:29], v[50:51], off nt
	s_nop 0
	global_load_dwordx4 v[30:33], v[30:31], off nt
	v_addc_co_u32_e32 v53, vcc, 0, v51, vcc
	s_waitcnt vmcnt(28)
	v_add_co_u32_e32 v54, vcc, 0x134000, v50
	global_load_dwordx4 v[34:37], v[34:35], off nt
	s_nop 0
	global_load_dwordx4 v[38:41], v[38:39], off nt
	v_addc_co_u32_e32 v55, vcc, 0, v51, vcc
	global_load_dwordx4 v[42:45], v[42:43], off nt
	s_nop 0
	global_load_dwordx4 v[46:49], v[46:47], off nt
	s_nop 0
	global_load_dwordx4 v[50:53], v[52:53], off nt
	s_nop 0
	global_load_dwordx4 v[54:57], v[54:55], off nt
	s_andn2_b64 vcc, exec, s[18:19]
	s_cbranch_vccnz .LBB0_16
; #define LAS __attribute__((address_space(3)))
; __device__ __forceinline__ unsigned cvtpk(float lo, float hi) { f32x2_t v = {lo, hi}; bf16x2_t b = __builtin_convertvector(v, bf16x2_t); return __builtin_bit_cast(unsigned, b); }
; #define LDS_WAIT() asm volatile("s_waitcnt lgkmcnt(0)" ::: "memory")
; #define CONV_JOB(it_) conv_job<LIST>((it_) < n ? (it_) : n - 1, P)
; __device__ __forceinline__ void conv_emit(const ConvJob& j, int lane, const ConvSet& s, LAS float* scr) {
;     const int k0 = 64 * j.kb; int cnt; (void)vgroup_src(j.kind, j.g, cnt);
;     const int ks = lane >> 3, n4 = (lane & 7) * 4, c = lane & 7; const bool okc = n4 < cnt;
;     const f32x4 one = (f32x4){1.f, 1.f, 1.f, 1.f}; const f32x4 g0 = j.gain ? s.g0 : one, g1 = j.gain ? s.g1 : one;
; #pragma unroll
;     for (int i = 0; i < 8; ++i) { LAS float* sp = scr + (8 * i + ks) * 33 + n4;
; #pragma unroll
;         for (int e = 0; e < 4; ++e) sp[e] = okc ? s.v[i][e] : 0.f; }
;     LDS_WAIT(); asm volatile("" ::: "memory");
; #pragma unroll
;     for (int q = 0; q < 4; ++q) { const int nn = (lane >> 3) + 8 * q; const LAS float* sr = scr + (8 * c) * 33 + nn;
;         u32x4 o; o.x = cvtpk(sr[0 * 33] * g0[0], sr[1 * 33] * g0[1]); o.y = cvtpk(sr[2 * 33] * g0[2], sr[3 * 33] * g0[3]); o.z = cvtpk(sr[4 * 33] * g1[0], sr[5 * 33] * g1[1]); o.w = cvtpk(sr[6 * 33] * g1[2], sr[7 * 33] * g1[3]);
;         *(u32x4*)(j.WT + (size_t)(j.g * 32 + nn) * j.K + k0 + 8 * c) = o; }
;     LDS_WAIT(); asm volatile("" ::: "memory");
; }
; template <int LIST> __device__ __forceinline__ void convert_list(int first, int stride, const Params& P, LAS float* scr, int lane) {
;     ...
;         conv_fetch(CONV_JOB(it + 4 * stride), lane, B); if (it + 2 * stride < n) conv_emit(CONV_JOB(it + 2 * stride), lane, C, scr);
	s_waitcnt vmcnt(31)
	ds_write2_b32 v132, v90, v91 offset1:1
	ds_write2_b32 v132, v92, v93 offset0:2 offset1:3
	s_waitcnt vmcnt(30)
	ds_write2_b32 v136, v94, v95 offset1:1
	ds_write2_b32 v137, v96, v97 offset1:1
	s_waitcnt vmcnt(29)
	ds_write2_b32 v138, v98, v99 offset1:1
	ds_write2_b32 v139, v100, v101 offset1:1
	s_waitcnt vmcnt(28)
	ds_write2_b32 v140, v102, v103 offset1:1
	ds_write2_b32 v141, v104, v105 offset1:1
	s_waitcnt vmcnt(27)
	ds_write2_b32 v142, v110, v111 offset1:1
	ds_write2_b32 v143, v112, v113 offset1:1
	s_waitcnt vmcnt(26)
	ds_write2_b32 v144, v106, v107 offset1:1
	ds_write2_b32 v145, v108, v109 offset1:1
	s_waitcnt vmcnt(25)
	ds_write2_b32 v146, v118, v119 offset1:1
	ds_write2_b32 v147, v120, v121 offset1:1
	s_waitcnt vmcnt(24)
	ds_write2_b32 v148, v114, v115 offset1:1
	ds_write2_b32 v149, v116, v117 offset1:1
	s_waitcnt lgkmcnt(0)
	ds_read2_b32 v[92:93], v131 offset1:8
	ds_read2_b32 v[96:97], v131 offset0:33 offset1:41
	ds_read2_b32 v[98:99], v131 offset0:66 offset1:74
	ds_read2_b32 v[100:101], v131 offset0:99 offset1:107
	ds_read2_b32 v[102:103], v131 offset0:132 offset1:140
	ds_read2_b32 v[104:105], v131 offset0:165 offset1:173
	ds_read2_b32 v[106:107], v131 offset0:198 offset1:206
	ds_read2_b32 v[108:109], v131 offset0:231 offset1:239
	s_mul_hi_i32 s18, s80, 0x2e8ba2e9
	s_lshr_b32 s19, s18, 31
	s_ashr_i32 s18, s18, 5
	s_add_i32 s18, s18, s19
	v_cndmask_b32_e64 v89, v89, 1.0, s[0:1]
	v_cndmask_b32_e64 v88, v88, 1.0, s[0:1]
	v_cndmask_b32_e64 v87, v87, 1.0, s[0:1]
	v_cndmask_b32_e64 v86, v86, 1.0, s[0:1]
	v_cndmask_b32_e64 v91, v85, 1.0, s[0:1]
	v_cndmask_b32_e64 v90, v84, 1.0, s[0:1]
	v_cndmask_b32_e64 v95, v83, 1.0, s[0:1]
	v_cndmask_b32_e64 v94, v82, 1.0, s[0:1]
	s_waitcnt lgkmcnt(7)
	v_mov_b32_e32 v82, v92
	s_waitcnt lgkmcnt(6)
	v_mov_b32_e32 v83, v96
	s_waitcnt lgkmcnt(5)
	v_mov_b32_e32 v84, v98
	s_waitcnt lgkmcnt(4)
	v_mov_b32_e32 v85, v100
	s_mul_i32 s19, s18, 0xb0
	v_pk_mul_f32 v[82:83], v[86:87], v[82:83]
	v_pk_mul_f32 v[84:85], v[88:89], v[84:85]
	s_sub_i32 s30, s80, s19
	v_cvt_pk_bf16_f32 v82, v82, v83
	v_cvt_pk_bf16_f32 v83, v84, v85
	s_waitcnt lgkmcnt(3)
	v_mov_b32_e32 v84, v102
	s_waitcnt lgkmcnt(2)
	v_mov_b32_e32 v85, v104
	s_waitcnt lgkmcnt(1)
	v_mov_b32_e32 v110, v106
	s_waitcnt lgkmcnt(0)
	v_mov_b32_e32 v111, v108
	v_pk_mul_f32 v[84:85], v[94:95], v[84:85]
	v_pk_mul_f32 v[110:111], v[90:91], v[110:111]
	s_lshl_b32 s30, s30, 5
	v_cvt_pk_bf16_f32 v84, v84, v85
	v_cvt_pk_bf16_f32 v85, v110, v111
	v_or_b32_e32 v110, s30, v130
	s_lshl_b32 s18, s18, 6
	v_ashrrev_i32_e32 v111, 31, v110
	s_ashr_i32 s19, s18, 31
	v_lshlrev_b64 v[110:111], 11, v[110:111]
	v_lshl_add_u64 v[110:111], s[50:51], 0, v[110:111]
	s_lshl_b64 s[18:19], s[18:19], 1
	v_lshl_add_u64 v[110:111], v[110:111], 0, s[18:19]
	v_mov_b32_e32 v127, v123
	v_lshl_add_u64 v[110:111], v[110:111], 0, v[126:127]
	v_mov_b32_e32 v96, v93
	v_mov_b32_e32 v100, v99
	global_store_dwordx4 v[110:111], v[82:85], off
	v_mov_b32_e32 v104, v103
	v_mov_b32_e32 v108, v107
	v_pk_mul_f32 v[82:83], v[86:87], v[96:97]
	v_pk_mul_f32 v[84:85], v[88:89], v[100:101]
	v_cvt_pk_bf16_f32 v82, v82, v83
	v_cvt_pk_bf16_f32 v83, v84, v85
	v_pk_mul_f32 v[84:85], v[94:95], v[104:105]
	v_pk_mul_f32 v[92:93], v[90:91], v[108:109]
	v_cvt_pk_bf16_f32 v84, v84, v85
	v_cvt_pk_bf16_f32 v85, v92, v93
	v_or_b32_e32 v92, s30, v133
	v_ashrrev_i32_e32 v93, 31, v92
	v_lshlrev_b64 v[92:93], 11, v[92:93]
	v_lshl_add_u64 v[92:93], s[50:51], 0, v[92:93]
	v_lshl_add_u64 v[92:93], v[92:93], 0, s[18:19]
	v_lshl_add_u64 v[92:93], v[92:93], 0, v[126:127]
	ds_read2_b32 v[96:97], v131 offset0:16 offset1:24
	ds_read2_b32 v[98:99], v131 offset0:49 offset1:57
	global_store_dwordx4 v[92:93], v[82:85], off
	ds_read2_b32 v[92:93], v131 offset0:82 offset1:90
	ds_read2_b32 v[100:101], v131 offset0:115 offset1:123
	ds_read2_b32 v[102:103], v131 offset0:148 offset1:156
	ds_read2_b32 v[104:105], v131 offset0:181 offset1:189
	ds_read2_b32 v[106:107], v131 offset0:214 offset1:222
	ds_read2_b32 v[108:109], v131 offset0:247 offset1:255
	s_waitcnt lgkmcnt(7)
	v_mov_b32_e32 v82, v96
	s_waitcnt lgkmcnt(6)
	v_mov_b32_e32 v83, v98
	s_waitcnt lgkmcnt(5)
	v_mov_b32_e32 v84, v92
	s_waitcnt lgkmcnt(4)
	v_mov_b32_e32 v85, v100
	v_pk_mul_f32 v[82:83], v[86:87], v[82:83]
	v_pk_mul_f32 v[84:85], v[88:89], v[84:85]
	v_cvt_pk_bf16_f32 v82, v82, v83
	v_cvt_pk_bf16_f32 v83, v84, v85
	s_waitcnt lgkmcnt(3)
	v_mov_b32_e32 v84, v102
	s_waitcnt lgkmcnt(2)
	v_mov_b32_e32 v85, v104
	s_waitcnt lgkmcnt(1)
	v_mov_b32_e32 v110, v106
	s_waitcnt lgkmcnt(0)
	v_mov_b32_e32 v111, v108
	v_pk_mul_f32 v[84:85], v[94:95], v[84:85]
	v_pk_mul_f32 v[110:111], v[90:91], v[110:111]
	v_cvt_pk_bf16_f32 v84, v84, v85
	v_cvt_pk_bf16_f32 v85, v110, v111
	v_or_b32_e32 v110, s30, v134
	v_ashrrev_i32_e32 v111, 31, v110
	v_lshlrev_b64 v[110:111], 11, v[110:111]
	v_lshl_add_u64 v[110:111], s[50:51], 0, v[110:111]
	v_lshl_add_u64 v[110:111], v[110:111], 0, s[18:19]
	v_lshl_add_u64 v[110:111], v[110:111], 0, v[126:127]
	v_mov_b32_e32 v98, v97
	v_mov_b32_e32 v100, v93
	global_store_dwordx4 v[110:111], v[82:85], off
	v_mov_b32_e32 v104, v103
	v_mov_b32_e32 v108, v107
	v_pk_mul_f32 v[82:83], v[86:87], v[98:99]
	v_pk_mul_f32 v[84:85], v[88:89], v[100:101]
	v_cvt_pk_bf16_f32 v82, v82, v83
	v_cvt_pk_bf16_f32 v83, v84, v85
	v_pk_mul_f32 v[84:85], v[94:95], v[104:105]
	v_pk_mul_f32 v[86:87], v[90:91], v[108:109]
	v_cvt_pk_bf16_f32 v84, v84, v85
	v_cvt_pk_bf16_f32 v85, v86, v87
	v_or_b32_e32 v86, s30, v135
	v_ashrrev_i32_e32 v87, 31, v86
	v_lshlrev_b64 v[86:87], 11, v[86:87]
	v_lshl_add_u64 v[86:87], s[50:51], 0, v[86:87]
	v_lshl_add_u64 v[86:87], v[86:87], 0, s[18:19]
	v_lshl_add_u64 v[86:87], v[86:87], 0, v[126:127]
	global_store_dwordx4 v[86:87], v[82:85], off
	s_waitcnt lgkmcnt(0)
	s_branch .LBB0_16

; #define CJ_SET(W_, K_, N_, kind_, gain_, WT_, NG_) do { j.W = (W_); j.K = (K_); j.Norig = (N_); j.kind = (kind_); j.gain = (gain_); j.WT = (bf16_t*)(WT_); j.kb = r / (NG_); j.g = r % (NG_); } while (0)
; template <int LIST> __device__ __forceinline__ ConvJob conv_job(int r, const Params& P) {
;     unsigned char* outb = (unsigned char*)P.out; ConvJob j;
;     ...
;     if (LIST == 0) CJ_SET(P.in[6], D, NUP, 1, P.in[5], outb + OW_UP1, G_UP);
;     else if (LIST == 2) CJ_SET(P.in[20], D, NUP, 1, P.in[19], outb + OW_UP2, G_UP);
;     else if (LIST == 3) CJ_SET(P.in[21], FF, D, 0, nullptr, P.ws + WS_WDN2, G_DN);
;     else if (r < I_DN) CJ_SET(P.in[7], FF, D, 0, nullptr, outb + OW_DN1, G_DN);
;     else if ((r -= I_DN) < I_IN) CJ_SET(P.in[9], D, 6672, 2, P.in[8], outb + OW_IN, G_IN);
;     else if ((r -= I_IN) < I_BR) CJ_SET(P.in[17], 2048, D, 0, nullptr, outb + OW_BR, G_BR);
;     else { r -= I_BR; CJ_SET(P.in[18], D, D, 0, nullptr, outb + OW_OUT, G_BR); }
;     ...
;     return j;
; }
; __device__ __forceinline__ void conv_fetch(const ConvJob& j, int lane, ConvSet& s) {
;     const int k0 = 64 * j.kb; int cnt; const int src = vgroup_src(j.kind, j.g, cnt);
;     const int ks = lane >> 3, n4 = (lane & 7) * 4, c = lane & 7; const bool okc = n4 < cnt;
;     const float* gp = j.gain ? j.gain + k0 + 8 * c : j.W;
;     s.g0 = *(const f32x4*)gp; s.g1 = *(const f32x4*)(gp + 4);
;     const float* wp = j.W + (size_t)(k0 + ks) * j.Norig + src + (okc ? n4 : 0);
; #pragma unroll
;     for (int i = 0; i < 8; ++i) s.v[i] = *(const f32x4*)(wp + (size_t)(8 * i) * j.Norig);
; }
.LBB0_61:
	s_lshl_b32 s24, s24, 6
	s_cmp_eq_u64 s[20:21], 0
	s_cselect_b64 vcc, -1, 0
	s_ashr_i32 s25, s24, 31
	s_lshl_b64 s[30:31], s[24:25], 2
	s_waitcnt vmcnt(33)
	v_and_b32_e32 v82, 7, v0
	s_add_u32 s20, s20, s30
	s_addc_u32 s21, s21, s31
	s_waitcnt vmcnt(16)
	v_mov_b32_e32 v11, 0
	v_lshlrev_b32_e32 v10, 5, v82
	v_lshrrev_b32_e32 v127, 3, v198
	v_mov_b32_e32 v4, s1
	v_lshl_add_u64 v[2:3], s[20:21], 0, v[10:11]
	v_or_b32_e32 v10, s24, v127
	v_cndmask_b32_e32 v7, v3, v4, vcc
	v_mov_b32_e32 v3, s0
	v_lshlrev_b32_e32 v126, 2, v82
	v_mul_lo_u32 v14, s19, v10
	s_mul_i32 s24, s18, s25
	v_mad_u64_u32 v[12:13], s[20:21], s18, v10, 0
	v_cndmask_b32_e32 v6, v2, v3, vcc
	v_add3_u32 v13, v13, s24, v14
	v_cmp_gt_u32_e32 vcc, s33, v126
	v_lshl_add_u64 v[12:13], v[12:13], 2, s[0:1]
	s_ashr_i32 s29, s28, 31
	v_cndmask_b32_e32 v10, 0, v126, vcc
	v_lshl_add_u64 v[12:13], s[28:29], 2, v[12:13]
	v_lshlrev_b32_e32 v10, 2, v10
	v_lshl_add_u64 v[10:11], v[12:13], 0, v[10:11]
	s_lshl_b64 s[0:1], s[18:19], 5
	v_lshl_add_u64 v[12:13], v[10:11], 0, s[0:1]
	global_load_dwordx4 v[2:5], v[6:7], off offset:16 nt
	s_nop 0
	global_load_dwordx4 v[6:9], v[6:7], off nt
	s_nop 0
	global_load_dwordx4 v[38:41], v[10:11], off nt
	global_load_dwordx4 v[34:37], v[12:13], off nt
	v_lshl_add_u64 v[10:11], v[12:13], 0, s[0:1]
	v_lshl_add_u64 v[12:13], v[10:11], 0, s[0:1]
	global_load_dwordx4 v[30:33], v[10:11], off nt
	global_load_dwordx4 v[26:29], v[12:13], off nt
	v_lshl_add_u64 v[10:11], v[12:13], 0, s[0:1]
	v_lshl_add_u64 v[12:13], v[10:11], 0, s[0:1]
	global_load_dwordx4 v[22:25], v[10:11], off nt
	global_load_dwordx4 v[18:21], v[12:13], off nt
	v_lshl_add_u64 v[10:11], v[12:13], 0, s[0:1]
	v_lshl_add_u64 v[12:13], v[10:11], 0, s[0:1]
	global_load_dwordx4 v[14:17], v[10:11], off nt
	s_nop 0
	global_load_dwordx4 v[10:13], v[12:13], off nt
	s_add_i32 s0, s92, s70
	s_min_i32 s33, s0, 0x18ff
	s_cmpk_gt_i32 s0, 0x57f
	s_cbranch_scc0 .LBB0_65
	s_cmpk_gt_u32 s0, 0x12ff
	s_mov_b64 s[28:29], -1
	s_cbranch_scc0 .LBB0_66
	s_cmpk_gt_u32 s0, 0x16ff
	s_cbranch_scc0 .LBB0_67
	s_add_i32 s0, s33, 0xffffe900
	s_lshr_b32 s24, s0, 5
	s_mov_b64 s[18:19], 0
	s_mov_b64 s[0:1], s[40:41]
	s_branch .LBB0_68

; #define CJ_SET(W_, K_, N_, kind_, gain_, WT_, NG_) do { j.W = (W_); j.K = (K_); j.Norig = (N_); j.kind = (kind_); j.gain = (gain_); j.WT = (bf16_t*)(WT_); j.kb = r / (NG_); j.g = r % (NG_); } while (0)
; #define CONV_LANDED(s_) do { asm volatile("" :: "v"((s_).v[0]), "v"((s_).v[1]), "v"((s_).v[2]), "v"((s_).v[3]), "v"((s_).v[4]), "v"((s_).v[5]), "v"((s_).v[6]), "v"((s_).v[7]), "v"((s_).g0), "v"((s_).g1)); } while (0)
; #define CONV_JOB(it_) conv_job<LIST>((it_) < n ? (it_) : n - 1, P)
; template <int LIST> __device__ __forceinline__ ConvJob conv_job(int r, const Params& P) {
;     unsigned char* outb = (unsigned char*)P.out; ConvJob j;
;     ...
;     if (LIST == 0) CJ_SET(P.in[6], D, NUP, 1, P.in[5], outb + OW_UP1, G_UP);
;     else if (LIST == 2) CJ_SET(P.in[20], D, NUP, 1, P.in[19], outb + OW_UP2, G_UP);
;     else if (LIST == 3) CJ_SET(P.in[21], FF, D, 0, nullptr, P.ws + WS_WDN2, G_DN);
;     else if (r < I_DN) CJ_SET(P.in[7], FF, D, 0, nullptr, outb + OW_DN1, G_DN);
;     else if ((r -= I_DN) < I_IN) CJ_SET(P.in[9], D, 6672, 2, P.in[8], outb + OW_IN, G_IN);
;     else if ((r -= I_IN) < I_BR) CJ_SET(P.in[17], 2048, D, 0, nullptr, outb + OW_BR, G_BR);
;     else { r -= I_BR; CJ_SET(P.in[18], D, D, 0, nullptr, outb + OW_OUT, G_BR); }
;     ...
;     return j;
; }
; __device__ __forceinline__ void conv_fetch(const ConvJob& j, int lane, ConvSet& s) {
;     const int k0 = 64 * j.kb; int cnt; const int src = vgroup_src(j.kind, j.g, cnt);
;     const int ks = lane >> 3, n4 = (lane & 7) * 4, c = lane & 7; const bool okc = n4 < cnt;
;     const float* gp = j.gain ? j.gain + k0 + 8 * c : j.W;
;     s.g0 = *(const f32x4*)gp; s.g1 = *(const f32x4*)(gp + 4);
;     const float* wp = j.W + (size_t)(k0 + ks) * j.Norig + src + (okc ? n4 : 0);
; #pragma unroll
;     for (int i = 0; i < 8; ++i) s.v[i] = *(const f32x4*)(wp + (size_t)(8 * i) * j.Norig);
; }
; template <int LIST> __device__ __forceinline__ void convert_list(int first, int stride, const Params& P, LAS float* scr, int lane) {
;     ...
;     conv_fetch(CONV_JOB(first), lane, A); conv_fetch(CONV_JOB(first + stride), lane, B);
;     CONV_LANDED(A); CONV_LANDED(B);
;     for (int it = first; it < n; it += 3 * stride) {
.LBB0_99:
	s_lshl_b32 s24, s24, 6
	s_cmp_eq_u64 s[20:21], 0
	s_cselect_b64 vcc, -1, 0
	s_ashr_i32 s25, s24, 31
	s_lshl_b64 s[30:31], s[24:25], 2
	s_add_u32 s20, s20, s30
	s_addc_u32 s21, s21, s31
	v_lshlrev_b32_e32 v122, 2, v128
	v_mov_b32_e32 v123, 0
	s_waitcnt vmcnt(13)
	v_mov_b32_e32 v44, s1
	v_lshl_add_u64 v[42:43], s[20:21], 0, v[122:123]
	s_waitcnt vmcnt(11)
	v_or_b32_e32 v50, s24, v127
	v_cndmask_b32_e32 v47, v43, v44, vcc
	v_mov_b32_e32 v43, s0
	s_mul_i32 s24, s18, s25
	v_mul_lo_u32 v52, s19, v50
	v_mad_u64_u32 v[50:51], s[20:21], s18, v50, 0
	v_cndmask_b32_e32 v46, v42, v43, vcc
	v_add3_u32 v51, v51, s24, v52
	v_cmp_gt_u32_e32 vcc, s33, v126
	v_lshl_add_u64 v[50:51], v[50:51], 2, s[0:1]
	s_ashr_i32 s29, s28, 31
	v_cndmask_b32_e32 v52, 0, v126, vcc
	v_lshl_add_u64 v[50:51], s[28:29], 2, v[50:51]
	v_lshlrev_b32_e32 v52, 2, v52
	v_mov_b32_e32 v53, v123
	v_lshl_add_u64 v[50:51], v[50:51], 0, v[52:53]
	s_lshl_b64 s[0:1], s[18:19], 5
	v_lshl_add_u64 v[52:53], v[50:51], 0, s[0:1]
	global_load_dwordx4 v[42:45], v[46:47], off offset:16 nt
	s_nop 0
	global_load_dwordx4 v[46:49], v[46:47], off nt
	s_nop 0
	global_load_dwordx4 v[78:81], v[50:51], off nt
	global_load_dwordx4 v[70:73], v[52:53], off nt
	v_lshl_add_u64 v[50:51], v[52:53], 0, s[0:1]
	v_lshl_add_u64 v[52:53], v[50:51], 0, s[0:1]
	global_load_dwordx4 v[74:77], v[50:51], off nt
	global_load_dwordx4 v[62:65], v[52:53], off nt
	v_lshl_add_u64 v[50:51], v[52:53], 0, s[0:1]
	v_lshl_add_u64 v[52:53], v[50:51], 0, s[0:1]
	global_load_dwordx4 v[66:69], v[50:51], off nt
	global_load_dwordx4 v[54:57], v[52:53], off nt
	v_lshl_add_u64 v[50:51], v[52:53], 0, s[0:1]
	v_lshl_add_u64 v[52:53], v[50:51], 0, s[0:1]
	global_load_dwordx4 v[58:61], v[50:51], off nt
	s_nop 0
	global_load_dwordx4 v[50:53], v[52:53], off nt
	s_lshl_b32 s25, s71, 4
	v_lshl_add_u32 v83, v126, 2, s3
	v_mul_u32_u24_e32 v84, 0x84, v127
	v_mul_u32_u24_e32 v82, 0x420, v82
	v_lshlrev_b32_e32 v85, 2, v127
	s_mul_i32 s24, s71, 24
	s_cmp_eq_u64 s[52:53], 0
	v_or_b32_e32 v129, 8, v127
	v_or_b32_e32 v130, 16, v127
	v_or_b32_e32 v131, 24, v127
	v_add3_u32 v132, s3, v82, v85
	v_add_u32_e32 v133, v83, v84
	s_cselect_b64 s[0:1], -1, 0
	s_sub_i32 s33, s24, s25
	s_add_i32 s77, s24, s92
	s_mov_b32 s79, s70
	s_waitcnt vmcnt(10)
	s_waitcnt vmcnt(0)
	s_branch .LBB0_102

; #define CJ_SET(W_, K_, N_, kind_, gain_, WT_, NG_) do { j.W = (W_); j.K = (K_); j.Norig = (N_); j.kind = (kind_); j.gain = (gain_); j.WT = (bf16_t*)(WT_); j.kb = r / (NG_); j.g = r % (NG_); } while (0)
; #define CONV_JOB(it_) conv_job<LIST>((it_) < n ? (it_) : n - 1, P)
; template <int LIST> __device__ __forceinline__ ConvJob conv_job(int r, const Params& P) {
;     unsigned char* outb = (unsigned char*)P.out; ConvJob j;
;     ...
;     if (LIST == 0) CJ_SET(P.in[6], D, NUP, 1, P.in[5], outb + OW_UP1, G_UP);
;     else if (LIST == 2) CJ_SET(P.in[20], D, NUP, 1, P.in[19], outb + OW_UP2, G_UP);
;     else if (LIST == 3) CJ_SET(P.in[21], FF, D, 0, nullptr, P.ws + WS_WDN2, G_DN);
;     else if (r < I_DN) CJ_SET(P.in[7], FF, D, 0, nullptr, outb + OW_DN1, G_DN);
;     else if ((r -= I_DN) < I_IN) CJ_SET(P.in[9], D, 6672, 2, P.in[8], outb + OW_IN, G_IN);
;     else if ((r -= I_IN) < I_BR) CJ_SET(P.in[17], 2048, D, 0, nullptr, outb + OW_BR, G_BR);
;     else { r -= I_BR; CJ_SET(P.in[18], D, D, 0, nullptr, outb + OW_OUT, G_BR); }
;     ...
;     return j;
; }
; __device__ __forceinline__ void conv_fetch(const ConvJob& j, int lane, ConvSet& s) {
;     const int k0 = 64 * j.kb; int cnt; const int src = vgroup_src(j.kind, j.g, cnt);
;     const int ks = lane >> 3, n4 = (lane & 7) * 4, c = lane & 7; const bool okc = n4 < cnt;
;     const float* gp = j.gain ? j.gain + k0 + 8 * c : j.W;
;     s.g0 = *(const f32x4*)gp; s.g1 = *(const f32x4*)(gp + 4);
;     const float* wp = j.W + (size_t)(k0 + ks) * j.Norig + src + (okc ? n4 : 0);
; #pragma unroll
;     for (int i = 0; i < 8; ++i) s.v[i] = *(const f32x4*)(wp + (size_t)(8 * i) * j.Norig);
; }
; template <int LIST> __device__ __forceinline__ void convert_list(int first, int stride, const Params& P, LAS float* scr, int lane) {
;     ...
;     for (int it = first; it < n; it += 3 * stride) {
;         conv_fetch(CONV_JOB(it + 2 * stride), lane, C); conv_emit(CONV_JOB(it), lane, A, scr);
;         conv_fetch(CONV_JOB(it + 3 * stride), lane, A); if (it + stride < n) conv_emit(CONV_JOB(it + stride), lane, B, scr);
;         conv_fetch(CONV_JOB(it + 4 * stride), lane, B); if (it + 2 * stride < n) conv_emit(CONV_JOB(it + 2 * stride), lane, C, scr);
.LBB0_117:
	s_lshl_b32 s72, s80, 6
	s_cmp_eq_u64 s[28:29], 0
	s_cselect_b64 vcc, -1, 0
	s_ashr_i32 s73, s72, 31
	s_lshl_b64 s[80:81], s[72:73], 2
	s_add_u32 s28, s28, s80
	s_addc_u32 s29, s29, s81
	s_waitcnt vmcnt(33)
	v_mov_b32_e32 v84, s21
	v_lshl_add_u64 v[82:83], s[28:29], 0, v[122:123]
	s_waitcnt vmcnt(24)
	v_or_b32_e32 v90, s72, v127
	v_cndmask_b32_e32 v87, v83, v84, vcc
	v_mov_b32_e32 v83, s20
	s_mul_i32 s35, s30, s73
	v_mul_lo_u32 v92, s31, v90
	v_mad_u64_u32 v[90:91], s[28:29], s30, v90, 0
	v_cndmask_b32_e32 v86, v82, v83, vcc
	v_add3_u32 v91, v91, s35, v92
	v_cmp_gt_u32_e32 vcc, s74, v126
	v_lshl_add_u64 v[90:91], v[90:91], 2, s[20:21]
	s_ashr_i32 s35, s34, 31
	v_cndmask_b32_e32 v92, 0, v126, vcc
	v_lshl_add_u64 v[90:91], s[34:35], 2, v[90:91]
	v_lshlrev_b32_e32 v92, 2, v92
	v_mov_b32_e32 v93, v123
	v_lshl_add_u64 v[90:91], v[90:91], 0, v[92:93]
	s_lshl_b64 s[20:21], s[30:31], 5
	v_lshl_add_u64 v[92:93], v[90:91], 0, s[20:21]
	global_load_dwordx4 v[82:85], v[86:87], off offset:16 nt
	s_nop 0
	global_load_dwordx4 v[86:89], v[86:87], off nt
	s_nop 0
	global_load_dwordx4 v[118:121], v[90:91], off nt
	global_load_dwordx4 v[114:117], v[92:93], off nt
	v_lshl_add_u64 v[90:91], v[92:93], 0, s[20:21]
	v_lshl_add_u64 v[92:93], v[90:91], 0, s[20:21]
	global_load_dwordx4 v[110:113], v[90:91], off nt
	global_load_dwordx4 v[106:109], v[92:93], off nt
	v_lshl_add_u64 v[90:91], v[92:93], 0, s[20:21]
	v_lshl_add_u64 v[92:93], v[90:91], 0, s[20:21]
	global_load_dwordx4 v[102:105], v[90:91], off nt
	global_load_dwordx4 v[98:101], v[92:93], off nt
	v_lshl_add_u64 v[90:91], v[92:93], 0, s[20:21]
	v_lshl_add_u64 v[92:93], v[90:91], 0, s[20:21]
	global_load_dwordx4 v[94:97], v[90:91], off nt
	s_nop 0
	global_load_dwordx4 v[90:93], v[92:93], off nt
	s_cmpk_gt_i32 s79, 0x57f
	s_mov_b64 s[74:75], -1
	s_cbranch_scc0 .LBB0_127
	s_mov_b64 s[30:31], -1
	s_cmpk_gt_u32 s79, 0x12ff
	s_mov_b64 s[34:35], -1
	s_cbranch_scc0 .LBB0_124
	s_cmpk_gt_u32 s79, 0x16ff
	s_mov_b64 s[28:29], -1
	s_cbranch_scc0 .LBB0_121
	s_add_i32 s20, s79, 0xffffe900
	s_lshr_b32 s73, s20, 5
	s_mov_b64 s[28:29], 0

; #define CJ_SET(W_, K_, N_, kind_, gain_, WT_, NG_) do { j.W = (W_); j.K = (K_); j.Norig = (N_); j.kind = (kind_); j.gain = (gain_); j.WT = (bf16_t*)(WT_); j.kb = r / (NG_); j.g = r % (NG_); } while (0)
; #define CONV_JOB(it_) conv_job<LIST>((it_) < n ? (it_) : n - 1, P)
; template <int LIST> __device__ __forceinline__ ConvJob conv_job(int r, const Params& P) {
;     unsigned char* outb = (unsigned char*)P.out; ConvJob j;
;     ...
;     if (LIST == 0) CJ_SET(P.in[6], D, NUP, 1, P.in[5], outb + OW_UP1, G_UP);
;     else if (LIST == 2) CJ_SET(P.in[20], D, NUP, 1, P.in[19], outb + OW_UP2, G_UP);
;     else if (LIST == 3) CJ_SET(P.in[21], FF, D, 0, nullptr, P.ws + WS_WDN2, G_DN);
;     else if (r < I_DN) CJ_SET(P.in[7], FF, D, 0, nullptr, outb + OW_DN1, G_DN);
;     else if ((r -= I_DN) < I_IN) CJ_SET(P.in[9], D, 6672, 2, P.in[8], outb + OW_IN, G_IN);
;     else if ((r -= I_IN) < I_BR) CJ_SET(P.in[17], 2048, D, 0, nullptr, outb + OW_BR, G_BR);
;     else { r -= I_BR; CJ_SET(P.in[18], D, D, 0, nullptr, outb + OW_OUT, G_BR); }
;     ...
;     return j;
; }
; __device__ __forceinline__ void conv_fetch(const ConvJob& j, int lane, ConvSet& s) {
;     const int k0 = 64 * j.kb; int cnt; const int src = vgroup_src(j.kind, j.g, cnt);
;     const int ks = lane >> 3, n4 = (lane & 7) * 4, c = lane & 7; const bool okc = n4 < cnt;
;     const float* gp = j.gain ? j.gain + k0 + 8 * c : j.W;
;     s.g0 = *(const f32x4*)gp; s.g1 = *(const f32x4*)(gp + 4);
;     const float* wp = j.W + (size_t)(k0 + ks) * j.Norig + src + (okc ? n4 : 0);
; #pragma unroll
;     for (int i = 0; i < 8; ++i) s.v[i] = *(const f32x4*)(wp + (size_t)(8 * i) * j.Norig);
; }
; template <int LIST> __device__ __forceinline__ void convert_list(int first, int stride, const Params& P, LAS float* scr, int lane) {
;     ...
;     for (int it = first; it < n; it += 3 * stride) {
;         conv_fetch(CONV_JOB(it + 2 * stride), lane, C); conv_emit(CONV_JOB(it), lane, A, scr);
;         conv_fetch(CONV_JOB(it + 3 * stride), lane, A); if (it + stride < n) conv_emit(CONV_JOB(it + stride), lane, B, scr);
;         conv_fetch(CONV_JOB(it + 4 * stride), lane, B); if (it + 2 * stride < n) conv_emit(CONV_JOB(it + 2 * stride), lane, C, scr);
.LBB0_161:
	s_lshl_b32 s72, s81, 6
	s_cmp_eq_u64 s[28:29], 0
	s_cselect_b64 vcc, -1, 0
	s_ashr_i32 s73, s72, 31
	s_lshl_b64 s[82:83], s[72:73], 2
	s_add_u32 s28, s28, s82
	s_addc_u32 s29, s29, s83
	v_mov_b32_e32 v4, s21
	v_lshl_add_u64 v[2:3], s[28:29], 0, v[122:123]
	v_or_b32_e32 v10, s72, v127
	v_cndmask_b32_e32 v7, v3, v4, vcc
	v_mov_b32_e32 v3, s20
	s_mul_i32 s35, s30, s73
	v_mul_lo_u32 v12, s31, v10
	v_mad_u64_u32 v[10:11], s[28:29], s30, v10, 0
	v_cndmask_b32_e32 v6, v2, v3, vcc
	v_add3_u32 v11, v11, s35, v12
	v_cmp_gt_u32_e32 vcc, s74, v126
	v_lshl_add_u64 v[10:11], v[10:11], 2, s[20:21]
	s_ashr_i32 s35, s34, 31
	v_cndmask_b32_e32 v12, 0, v126, vcc
	v_lshl_add_u64 v[10:11], s[34:35], 2, v[10:11]
	v_lshlrev_b32_e32 v12, 2, v12
	v_mov_b32_e32 v13, v123
	v_lshl_add_u64 v[10:11], v[10:11], 0, v[12:13]
	s_lshl_b64 s[20:21], s[30:31], 5
	v_lshl_add_u64 v[12:13], v[10:11], 0, s[20:21]
	global_load_dwordx4 v[2:5], v[6:7], off offset:16 nt
	s_nop 0
	global_load_dwordx4 v[6:9], v[6:7], off nt
	s_nop 0
	global_load_dwordx4 v[38:41], v[10:11], off nt
	global_load_dwordx4 v[34:37], v[12:13], off nt
	v_lshl_add_u64 v[10:11], v[12:13], 0, s[20:21]
	v_lshl_add_u64 v[12:13], v[10:11], 0, s[20:21]
	global_load_dwordx4 v[30:33], v[10:11], off nt
	global_load_dwordx4 v[26:29], v[12:13], off nt
	v_lshl_add_u64 v[10:11], v[12:13], 0, s[20:21]
	v_lshl_add_u64 v[12:13], v[10:11], 0, s[20:21]
	global_load_dwordx4 v[22:25], v[10:11], off nt
	global_load_dwordx4 v[18:21], v[12:13], off nt
	v_lshl_add_u64 v[10:11], v[12:13], 0, s[20:21]
	v_lshl_add_u64 v[12:13], v[10:11], 0, s[20:21]
	global_load_dwordx4 v[14:17], v[10:11], off nt
	s_nop 0
	global_load_dwordx4 v[10:13], v[12:13], off nt
	s_add_i32 s81, s33, s79
	s_cmpk_gt_i32 s81, 0x18ff
	s_cbranch_scc1 .LBB0_175
	s_cmpk_gt_i32 s81, 0x57f
	s_mov_b64 s[74:75], -1
	s_cbranch_scc0 .LBB0_172
	s_mov_b64 s[30:31], -1
	s_cmpk_gt_u32 s81, 0x12ff
	s_mov_b64 s[34:35], -1
	s_cbranch_scc0 .LBB0_169
	s_cmpk_gt_u32 s81, 0x16ff
	s_mov_b64 s[28:29], -1
	s_cbranch_scc0 .LBB0_166
	s_add_i32 s20, s81, 0xffffe900
	s_lshr_b32 s73, s20, 5
	s_mov_b64 s[28:29], 0

; #define CJ_SET(W_, K_, N_, kind_, gain_, WT_, NG_) do { j.W = (W_); j.K = (K_); j.Norig = (N_); j.kind = (kind_); j.gain = (gain_); j.WT = (bf16_t*)(WT_); j.kb = r / (NG_); j.g = r % (NG_); } while (0)
; #define CONV_JOB(it_) conv_job<LIST>((it_) < n ? (it_) : n - 1, P)
; template <int LIST> __device__ __forceinline__ ConvJob conv_job(int r, const Params& P) {
;     unsigned char* outb = (unsigned char*)P.out; ConvJob j;
;     ...
;     if (LIST == 0) CJ_SET(P.in[6], D, NUP, 1, P.in[5], outb + OW_UP1, G_UP);
;     else if (LIST == 2) CJ_SET(P.in[20], D, NUP, 1, P.in[19], outb + OW_UP2, G_UP);
;     else if (LIST == 3) CJ_SET(P.in[21], FF, D, 0, nullptr, P.ws + WS_WDN2, G_DN);
;     else if (r < I_DN) CJ_SET(P.in[7], FF, D, 0, nullptr, outb + OW_DN1, G_DN);
;     else if ((r -= I_DN) < I_IN) CJ_SET(P.in[9], D, 6672, 2, P.in[8], outb + OW_IN, G_IN);
;     else if ((r -= I_IN) < I_BR) CJ_SET(P.in[17], 2048, D, 0, nullptr, outb + OW_BR, G_BR);
;     else { r -= I_BR; CJ_SET(P.in[18], D, D, 0, nullptr, outb + OW_OUT, G_BR); }
;     ...
;     return j;
; }
; __device__ __forceinline__ void conv_fetch(const ConvJob& j, int lane, ConvSet& s) {
;     const int k0 = 64 * j.kb; int cnt; const int src = vgroup_src(j.kind, j.g, cnt);
;     const int ks = lane >> 3, n4 = (lane & 7) * 4, c = lane & 7; const bool okc = n4 < cnt;
;     const float* gp = j.gain ? j.gain + k0 + 8 * c : j.W;
;     s.g0 = *(const f32x4*)gp; s.g1 = *(const f32x4*)(gp + 4);
;     const float* wp = j.W + (size_t)(k0 + ks) * j.Norig + src + (okc ? n4 : 0);
; #pragma unroll
;     for (int i = 0; i < 8; ++i) s.v[i] = *(const f32x4*)(wp + (size_t)(8 * i) * j.Norig);
; }
; template <int LIST> __device__ __forceinline__ void convert_list(int first, int stride, const Params& P, LAS float* scr, int lane) {
;     ...
;     for (int it = first; it < n; it += 3 * stride) {
;         conv_fetch(CONV_JOB(it + 2 * stride), lane, C); conv_emit(CONV_JOB(it), lane, A, scr);
;         conv_fetch(CONV_JOB(it + 3 * stride), lane, A); if (it + stride < n) conv_emit(CONV_JOB(it + stride), lane, B, scr);
;         conv_fetch(CONV_JOB(it + 4 * stride), lane, B); if (it + 2 * stride < n) conv_emit(CONV_JOB(it + 2 * stride), lane, C, scr);
.LBB0_207:
	s_lshl_b32 s72, s79, 6
	s_cmp_eq_u64 s[28:29], 0
	s_cselect_b64 vcc, -1, 0
	s_ashr_i32 s73, s72, 31
	s_lshl_b64 s[82:83], s[72:73], 2
	s_add_u32 s28, s28, s82
	s_addc_u32 s29, s29, s83
	s_waitcnt vmcnt(33)
	v_mov_b32_e32 v44, s21
	v_lshl_add_u64 v[42:43], s[28:29], 0, v[122:123]
	s_waitcnt vmcnt(24)
	v_or_b32_e32 v50, s72, v127
	v_cndmask_b32_e32 v47, v43, v44, vcc
	v_mov_b32_e32 v43, s20
	s_mul_i32 s35, s30, s73
	v_mul_lo_u32 v52, s31, v50
	v_mad_u64_u32 v[50:51], s[28:29], s30, v50, 0
	v_cndmask_b32_e32 v46, v42, v43, vcc
	v_add3_u32 v51, v51, s35, v52
	v_cmp_gt_u32_e32 vcc, s74, v126
	v_lshl_add_u64 v[50:51], v[50:51], 2, s[20:21]
	s_ashr_i32 s35, s34, 31
	v_cndmask_b32_e32 v52, 0, v126, vcc
	v_lshl_add_u64 v[50:51], s[34:35], 2, v[50:51]
	v_lshlrev_b32_e32 v52, 2, v52
	v_mov_b32_e32 v53, v123
	v_lshl_add_u64 v[50:51], v[50:51], 0, v[52:53]
	s_lshl_b64 s[20:21], s[30:31], 5
	v_lshl_add_u64 v[52:53], v[50:51], 0, s[20:21]
	global_load_dwordx4 v[42:45], v[46:47], off offset:16 nt
	s_nop 0
	global_load_dwordx4 v[46:49], v[46:47], off nt
	s_nop 0
	global_load_dwordx4 v[78:81], v[50:51], off nt
	global_load_dwordx4 v[70:73], v[52:53], off nt
	v_lshl_add_u64 v[50:51], v[52:53], 0, s[20:21]
	v_lshl_add_u64 v[52:53], v[50:51], 0, s[20:21]
	global_load_dwordx4 v[74:77], v[50:51], off nt
	global_load_dwordx4 v[62:65], v[52:53], off nt
	v_lshl_add_u64 v[50:51], v[52:53], 0, s[20:21]
	v_lshl_add_u64 v[52:53], v[50:51], 0, s[20:21]
	global_load_dwordx4 v[66:69], v[50:51], off nt
	global_load_dwordx4 v[54:57], v[52:53], off nt
	v_lshl_add_u64 v[50:51], v[52:53], 0, s[20:21]
	v_lshl_add_u64 v[52:53], v[50:51], 0, s[20:21]
	global_load_dwordx4 v[58:61], v[50:51], off nt
	s_nop 0
	global_load_dwordx4 v[50:53], v[52:53], off nt
	s_andn2_b64 vcc, exec, s[18:19]
	s_cbranch_vccnz .LBB0_101
	s_cmpk_gt_i32 s78, 0x57f
	s_mov_b64 s[34:35], -1
	s_cbranch_scc0 .LBB0_218
	s_mov_b64 s[28:29], -1
	s_cmpk_gt_u32 s78, 0x12ff
	s_mov_b64 s[30:31], -1
	s_cbranch_scc0 .LBB0_215
	s_cmpk_gt_u32 s78, 0x16ff
	s_mov_b64 s[20:21], -1
	s_cbranch_scc0 .LBB0_212
	s_add_i32 s18, s78, 0xffffe900
	s_lshr_b32 s73, s18, 5
	s_mov_b64 s[20:21], 0

; #define CONV_LANDED(s_) do { asm volatile("" :: "v"((s_).v[0]), "v"((s_).v[1]), "v"((s_).v[2]), "v"((s_).v[3]), "v"((s_).v[4]), "v"((s_).v[5]), "v"((s_).v[6]), "v"((s_).v[7]), "v"((s_).g0), "v"((s_).g1)); } while (0)
; #define CONV_JOB(it_) conv_job<LIST>((it_) < n ? (it_) : n - 1, P)
; __device__ __forceinline__ void conv_fetch(const ConvJob& j, int lane, ConvSet& s) {
;     const int k0 = 64 * j.kb; int cnt; const int src = vgroup_src(j.kind, j.g, cnt);
;     const int ks = lane >> 3, n4 = (lane & 7) * 4, c = lane & 7; const bool okc = n4 < cnt;
;     const float* gp = j.gain ? j.gain + k0 + 8 * c : j.W;
;     s.g0 = *(const f32x4*)gp; s.g1 = *(const f32x4*)(gp + 4);
;     const float* wp = j.W + (size_t)(k0 + ks) * j.Norig + src + (okc ? n4 : 0);
; #pragma unroll
;     for (int i = 0; i < 8; ++i) s.v[i] = *(const f32x4*)(wp + (size_t)(8 * i) * j.Norig);
; }
; template <int LIST> __device__ __forceinline__ void convert_list(int first, int stride, const Params& P, LAS float* scr, int lane) {
;     ...
;     conv_fetch(CONV_JOB(first), lane, A); conv_fetch(CONV_JOB(first + stride), lane, B);
;     CONV_LANDED(A); CONV_LANDED(B);
;     for (int it = first; it < n; it += 3 * stride) {
.LBB0_237:
	s_andn2_b64 vcc, exec, s[6:7]
	s_cbranch_vccnz .LBB0_244
	s_mul_hi_i32 s0, s70, 0x2e8ba2e9
	s_lshr_b32 s1, s0, 31
	s_ashr_i32 s0, s0, 5
	s_add_i32 s0, s0, s1
	s_mul_i32 s1, s0, 0xb0
	s_sub_i32 s1, s70, s1
	s_lshl_b32 s6, s0, 6
	s_bfe_i32 s0, s1, 0x10002
	s_lshl_b32 s7, s1, 4
	s_and_b32 s0, s0, 0xb00
	s_and_b32 s7, s7, 0xffffff80
	s_lshl_b32 s1, s1, 5
	s_add_i32 s0, s0, s7
	s_and_b32 s1, s1, 0x60
	s_or_b32 s18, s0, s1
	s_cmp_eq_u64 s[42:43], 0
	s_cselect_b64 s[0:1], -1, 0
	s_ashr_i32 s7, s6, 31
	s_lshl_b64 s[20:21], s[6:7], 2
	s_waitcnt vmcnt(33)
	v_and_b32_e32 v85, 7, v0
	s_add_u32 s20, s42, s20
	s_addc_u32 s21, s43, s21
	v_mov_b32_e32 v123, 0
	v_lshlrev_b32_e32 v122, 5, v85
	v_lshrrev_b32_e32 v130, 3, v198
	s_waitcnt vmcnt(19)
	v_lshl_add_u64 v[2:3], s[20:21], 0, v[122:123]
	s_waitcnt vmcnt(10)
	v_or_b32_e32 v10, s6, v130
	s_movk_i32 s20, 0x5800
	s_waitcnt vmcnt(0)
	v_mov_b64_e32 v[50:51], s[44:45]
	v_mad_i64_i32 v[10:11], s[6:7], v10, s20, v[50:51]
	s_ashr_i32 s19, s18, 31
	v_lshl_add_u64 v[10:11], s[18:19], 2, v[10:11]
	v_lshlrev_b32_e32 v82, 4, v85
	v_mov_b32_e32 v83, v123
	s_add_i32 s6, s92, s70
	v_lshl_add_u64 v[18:19], v[10:11], 0, v[82:83]
	s_mov_b32 s21, 0x2c000
	s_min_i32 s6, s6, 0xaff
	v_add_co_u32_e32 v14, vcc, s21, v18
	s_mul_hi_i32 s7, s6, 0x2e8ba2e9
	s_nop 0
	v_addc_co_u32_e32 v15, vcc, 0, v19, vcc
	s_mov_b32 s24, 0x58000
	s_lshr_b32 s18, s7, 31
	s_ashr_i32 s7, s7, 5
	v_add_co_u32_e32 v20, vcc, s24, v18
	s_add_i32 s7, s7, s18
	s_nop 0
	v_addc_co_u32_e32 v21, vcc, 0, v19, vcc
	s_mov_b32 s25, 0x84000
	s_mul_i32 s18, s7, 0xb0
	v_mov_b32_e32 v32, s45
	v_mov_b32_e32 v33, s44
	v_add_co_u32_e32 v26, vcc, s25, v18
	s_sub_i32 s18, s6, s18
	v_cndmask_b32_e64 v7, v3, v32, s[0:1]
	v_cndmask_b32_e64 v6, v2, v33, s[0:1]
	v_addc_co_u32_e32 v27, vcc, 0, v19, vcc
	s_mov_b32 s28, 0xb0000
	s_lshl_b32 s6, s7, 6
	s_bfe_i32 s7, s18, 0x10002
	s_lshl_b32 s19, s18, 4
	global_load_dwordx4 v[2:5], v[6:7], off offset:16 nt
	s_nop 0
	global_load_dwordx4 v[6:9], v[6:7], off nt
	s_nop 0
	global_load_dwordx4 v[10:13], v[18:19], off nt
	s_nop 0
	global_load_dwordx4 v[14:17], v[14:15], off nt
	s_nop 0
	global_load_dwordx4 v[22:25], v[20:21], off nt
	s_nop 0
	global_load_dwordx4 v[26:29], v[26:27], off nt
	v_add_co_u32_e32 v20, vcc, s28, v18
	s_and_b32 s7, s7, 0xb00
	s_and_b32 s19, s19, 0xffffff80
	s_lshl_b32 s18, s18, 5
	v_addc_co_u32_e32 v21, vcc, 0, v19, vcc
	s_mov_b32 s29, 0xdc000
	s_add_i32 s7, s7, s19
	s_and_b32 s18, s18, 0x60
	v_add_co_u32_e32 v30, vcc, s29, v18
	s_or_b32 s18, s7, s18
	s_ashr_i32 s7, s6, 31
	v_addc_co_u32_e32 v31, vcc, 0, v19, vcc
	s_mov_b32 s30, 0x108000
	s_lshl_b64 s[34:35], s[6:7], 2
	global_load_dwordx4 v[34:37], v[20:21], off nt
	global_load_dwordx4 v[38:41], v[30:31], off nt
	v_add_co_u32_e32 v20, vcc, s30, v18
	s_add_u32 s34, s42, s34
	v_or_b32_e32 v52, s6, v130
	v_addc_co_u32_e32 v21, vcc, 0, v19, vcc
	s_mov_b32 s31, 0x134000
	s_addc_u32 s35, s43, s35
	v_mad_i64_i32 v[50:51], s[6:7], v52, s20, v[50:51]
	s_ashr_i32 s19, s18, 31
	v_add_co_u32_e32 v18, vcc, s31, v18
	v_lshl_add_u64 v[50:51], s[18:19], 2, v[50:51]
	s_nop 0
	v_addc_co_u32_e32 v19, vcc, 0, v19, vcc
	v_lshl_add_u64 v[74:75], v[50:51], 0, v[82:83]
	v_add_co_u32_e32 v54, vcc, s21, v74
	global_load_dwordx4 v[42:45], v[20:21], off nt
	global_load_dwordx4 v[46:49], v[18:19], off nt
	v_addc_co_u32_e32 v55, vcc, 0, v75, vcc
	v_add_co_u32_e32 v58, vcc, s24, v74
	v_lshl_add_u64 v[18:19], s[34:35], 0, v[122:123]
	s_nop 0
	v_addc_co_u32_e32 v59, vcc, 0, v75, vcc
	v_add_co_u32_e32 v62, vcc, s25, v74
	v_cndmask_b32_e64 v31, v19, v32, s[0:1]
	s_nop 0
	v_addc_co_u32_e32 v63, vcc, 0, v75, vcc
	v_add_co_u32_e32 v66, vcc, s28, v74
	v_cndmask_b32_e64 v30, v18, v33, s[0:1]
	s_nop 0
	v_addc_co_u32_e32 v67, vcc, 0, v75, vcc
	v_add_co_u32_e32 v70, vcc, s29, v74
	global_load_dwordx4 v[18:21], v[30:31], off offset:16 nt
	s_nop 0
	global_load_dwordx4 v[30:33], v[30:31], off nt
	v_addc_co_u32_e32 v71, vcc, 0, v75, vcc
	v_add_co_u32_e32 v76, vcc, s30, v74
	global_load_dwordx4 v[50:53], v[74:75], off nt
	s_nop 0
	global_load_dwordx4 v[54:57], v[54:55], off nt
	v_addc_co_u32_e32 v77, vcc, 0, v75, vcc
	v_add_co_u32_e32 v78, vcc, s31, v74
	global_load_dwordx4 v[58:61], v[58:59], off nt
	s_nop 0
	global_load_dwordx4 v[62:65], v[62:63], off nt
	v_addc_co_u32_e32 v79, vcc, 0, v75, vcc
	global_load_dwordx4 v[66:69], v[66:67], off nt
	s_nop 0
	global_load_dwordx4 v[70:73], v[70:71], off nt
	s_nop 0
	global_load_dwordx4 v[74:77], v[76:77], off nt
	s_nop 0
	global_load_dwordx4 v[78:81], v[78:79], off nt
	s_add_i32 s6, s2, s71
	v_lshlrev_b32_e32 v84, 3, v85
	v_lshlrev_b32_e32 v86, 2, v85
	v_add_u32_e32 v82, s3, v82
	v_mul_u32_u24_e32 v83, 0x84, v130
	v_mul_u32_u24_e32 v85, 0x420, v85
	v_lshlrev_b32_e32 v87, 2, v130
	s_lshl_b32 s6, s6, 3
	v_readlane_b32 s7, v252, 11
	s_lshl_b32 s33, s71, 4
	v_or_b32_e32 v131, 8, v130
	v_or_b32_e32 v132, 16, v130
	v_or_b32_e32 v133, 24, v130
	v_add3_u32 v134, s3, v85, v87
	v_lshl_add_u64 v[124:125], s[42:43], 0, v[122:123]
	s_mul_i32 s34, s71, 24
	s_add_i32 s35, s7, s6
	s_lshl_b32 s72, s71, 5
	v_lshlrev_b32_e32 v122, 2, v86
	v_lshlrev_b32_e32 v126, 1, v84
	v_add_u32_e32 v135, v82, v83
	s_mov_b32 s74, s70
	s_waitcnt vmcnt(10)
	s_waitcnt vmcnt(0)
	s_branch .LBB0_240

; #define LAS __attribute__((address_space(3)))
; __device__ __forceinline__ unsigned cvtpk(float lo, float hi) { f32x2_t v = {lo, hi}; bf16x2_t b = __builtin_convertvector(v, bf16x2_t); return __builtin_bit_cast(unsigned, b); }
; #define LDS_WAIT() asm volatile("s_waitcnt lgkmcnt(0)" ::: "memory")
; #define CONV_JOB(it_) conv_job<LIST>((it_) < n ? (it_) : n - 1, P)
; __device__ __forceinline__ void conv_fetch(const ConvJob& j, int lane, ConvSet& s) {
;     const int k0 = 64 * j.kb; int cnt; const int src = vgroup_src(j.kind, j.g, cnt);
;     const int ks = lane >> 3, n4 = (lane & 7) * 4, c = lane & 7; const bool okc = n4 < cnt;
;     const float* gp = j.gain ? j.gain + k0 + 8 * c : j.W;
;     s.g0 = *(const f32x4*)gp; s.g1 = *(const f32x4*)(gp + 4);
;     const float* wp = j.W + (size_t)(k0 + ks) * j.Norig + src + (okc ? n4 : 0);
; #pragma unroll
;     for (int i = 0; i < 8; ++i) s.v[i] = *(const f32x4*)(wp + (size_t)(8 * i) * j.Norig);
; }
; __device__ __forceinline__ void conv_emit(const ConvJob& j, int lane, const ConvSet& s, LAS float* scr) {
;     const int k0 = 64 * j.kb; int cnt; (void)vgroup_src(j.kind, j.g, cnt);
;     const int ks = lane >> 3, n4 = (lane & 7) * 4, c = lane & 7; const bool okc = n4 < cnt;
;     const f32x4 one = (f32x4){1.f, 1.f, 1.f, 1.f}; const f32x4 g0 = j.gain ? s.g0 : one, g1 = j.gain ? s.g1 : one;
; #pragma unroll
;     for (int i = 0; i < 8; ++i) { LAS float* sp = scr + (8 * i + ks) * 33 + n4;
; #pragma unroll
;         for (int e = 0; e < 4; ++e) sp[e] = okc ? s.v[i][e] : 0.f; }
;     LDS_WAIT(); asm volatile("" ::: "memory");
; #pragma unroll
;     for (int q = 0; q < 4; ++q) { const int nn = (lane >> 3) + 8 * q; const LAS float* sr = scr + (8 * c) * 33 + nn;
;         u32x4 o; o.x = cvtpk(sr[0 * 33] * g0[0], sr[1 * 33] * g0[1]); o.y = cvtpk(sr[2 * 33] * g0[2], sr[3 * 33] * g0[3]); o.z = cvtpk(sr[4 * 33] * g1[0], sr[5 * 33] * g1[1]); o.w = cvtpk(sr[6 * 33] * g1[2], sr[7 * 33] * g1[3]);
;         *(u32x4*)(j.WT + (size_t)(j.g * 32 + nn) * j.K + k0 + 8 * c) = o; }
;     LDS_WAIT(); asm volatile("" ::: "memory");
; }
; template <int LIST> __device__ __forceinline__ void convert_list(int first, int stride, const Params& P, LAS float* scr, int lane) {
;     ...
;     for (int it = first; it < n; it += 3 * stride) {
;         conv_fetch(CONV_JOB(it + 2 * stride), lane, C); conv_emit(CONV_JOB(it), lane, A, scr);
.LBB0_240:
	s_add_i32 s73, s74, s33
	s_cmpk_lt_i32 s73, 0xb00
	s_cselect_b64 s[6:7], -1, 0
	s_and_b64 s[18:19], s[6:7], exec
	s_cselect_b32 s18, s73, 0xaff
	s_mul_hi_i32 s19, s18, 0x2e8ba2e9
	s_lshr_b32 s75, s19, 31
	s_ashr_i32 s19, s19, 5
	s_add_i32 s19, s19, s75
	s_mul_i32 s75, s19, 0xb0
	s_sub_i32 s75, s18, s75
	s_lshl_b32 s18, s19, 6
	s_bfe_i32 s19, s75, 0x10002
	s_lshl_b32 s77, s75, 4
	s_and_b32 s19, s19, 0xb00
	s_and_b32 s77, s77, 0xffffff80
	s_lshl_b32 s75, s75, 5
	s_add_i32 s19, s19, s77
	s_and_b32 s75, s75, 0x60
	s_or_b32 s78, s19, s75
	s_ashr_i32 s19, s18, 31
	s_waitcnt vmcnt(31)
	v_or_b32_e32 v90, s18, v130
	v_mov_b64_e32 v[128:129], s[44:45]
	v_lshl_add_u64 v[82:83], s[18:19], 2, v[124:125]
	v_mad_i64_i32 v[90:91], s[18:19], v90, s20, v[128:129]
	s_ashr_i32 s79, s78, 31
	v_lshl_add_u64 v[90:91], s[78:79], 2, v[90:91]
	s_waitcnt vmcnt(25)
	v_lshl_add_u64 v[114:115], v[90:91], 0, v[122:123]
	v_add_co_u32_e32 v94, vcc, s21, v114
	v_mov_b32_e32 v150, s45
	s_nop 0
	v_addc_co_u32_e32 v95, vcc, 0, v115, vcc
	v_add_co_u32_e32 v98, vcc, s24, v114
	v_mov_b32_e32 v151, s44
	s_nop 0
	v_addc_co_u32_e32 v99, vcc, 0, v115, vcc
	v_add_co_u32_e32 v102, vcc, s25, v114
	v_cndmask_b32_e64 v87, v83, v150, s[0:1]
	s_nop 0
	v_addc_co_u32_e32 v103, vcc, 0, v115, vcc
	v_add_co_u32_e32 v106, vcc, s28, v114
	v_cndmask_b32_e64 v86, v82, v151, s[0:1]
	s_nop 0
	v_addc_co_u32_e32 v107, vcc, 0, v115, vcc
	v_add_co_u32_e32 v110, vcc, s29, v114
	v_add_u32_e32 v136, 0x420, v135
	s_nop 0
	v_addc_co_u32_e32 v111, vcc, 0, v115, vcc
	v_add_co_u32_e32 v116, vcc, s30, v114
	v_add_u32_e32 v137, 0x428, v135
	s_nop 0
	v_addc_co_u32_e32 v117, vcc, 0, v115, vcc
	s_waitcnt vmcnt(24)
	v_add_co_u32_e32 v118, vcc, s31, v114
	v_add_u32_e32 v138, 0x840, v135
	s_nop 0
	v_addc_co_u32_e32 v119, vcc, 0, v115, vcc
	v_add_u32_e32 v139, 0x848, v135
	v_add_u32_e32 v140, 0xc60, v135
	v_add_u32_e32 v141, 0xc68, v135
	v_add_u32_e32 v142, 0x1080, v135
	v_add_u32_e32 v143, 0x1088, v135
	v_add_u32_e32 v144, 0x14a0, v135
	v_add_u32_e32 v145, 0x14a8, v135
	v_add_u32_e32 v146, 0x18c0, v135
	v_add_u32_e32 v147, 0x18c8, v135
	v_add_u32_e32 v148, 0x1ce0, v135
	v_add_u32_e32 v149, 0x1ce8, v135
	global_load_dwordx4 v[82:85], v[86:87], off offset:16 nt
	s_nop 0
	global_load_dwordx4 v[86:89], v[86:87], off nt
	s_nop 0
	global_load_dwordx4 v[90:93], v[114:115], off nt
	s_nop 0
	global_load_dwordx4 v[94:97], v[94:95], off nt
	s_nop 0
	global_load_dwordx4 v[98:101], v[98:99], off nt
	s_nop 0
	global_load_dwordx4 v[102:105], v[102:103], off nt
	s_nop 0
	global_load_dwordx4 v[106:109], v[106:107], off nt
	s_nop 0
	global_load_dwordx4 v[110:113], v[110:111], off nt
	s_nop 0
	global_load_dwordx4 v[114:117], v[116:117], off nt
	s_nop 0
	global_load_dwordx4 v[118:121], v[118:119], off nt
	s_waitcnt vmcnt(27)
	ds_write2_b32 v135, v10, v11 offset1:1
	ds_write2_b32 v135, v12, v13 offset0:2 offset1:3
	s_waitcnt vmcnt(26)
	ds_write2_b32 v136, v14, v15 offset1:1
	ds_write2_b32 v137, v16, v17 offset1:1
	s_waitcnt vmcnt(25)
	ds_write2_b32 v138, v22, v23 offset1:1
	ds_write2_b32 v139, v24, v25 offset1:1
	s_waitcnt vmcnt(24)
	ds_write2_b32 v140, v26, v27 offset1:1
	ds_write2_b32 v141, v28, v29 offset1:1
	s_waitcnt vmcnt(23)
	ds_write2_b32 v142, v34, v35 offset1:1
	ds_write2_b32 v143, v36, v37 offset1:1
	s_waitcnt vmcnt(22)
	ds_write2_b32 v144, v38, v39 offset1:1
	ds_write2_b32 v145, v40, v41 offset1:1
	s_waitcnt vmcnt(21)
	ds_write2_b32 v146, v42, v43 offset1:1
	ds_write2_b32 v147, v44, v45 offset1:1
	s_waitcnt vmcnt(20)
	ds_write2_b32 v148, v46, v47 offset1:1
	ds_write2_b32 v149, v48, v49 offset1:1
	s_waitcnt lgkmcnt(0)
	ds_read2_b32 v[12:13], v134 offset1:8
	ds_read2_b32 v[16:17], v134 offset0:33 offset1:41
	ds_read2_b32 v[22:23], v134 offset0:66 offset1:74
	ds_read2_b32 v[24:25], v134 offset0:99 offset1:107
	ds_read2_b32 v[26:27], v134 offset0:132 offset1:140
	ds_read2_b32 v[28:29], v134 offset0:165 offset1:173
	ds_read2_b32 v[34:35], v134 offset0:198 offset1:206
	ds_read2_b32 v[36:37], v134 offset0:231 offset1:239
	s_mul_hi_i32 s18, s74, 0x2e8ba2e9
	s_lshr_b32 s19, s18, 31
	s_ashr_i32 s18, s18, 5
	s_add_i32 s18, s18, s19
	v_cndmask_b32_e64 v9, v9, 1.0, s[0:1]
	v_cndmask_b32_e64 v8, v8, 1.0, s[0:1]
	v_cndmask_b32_e64 v7, v7, 1.0, s[0:1]
	v_cndmask_b32_e64 v6, v6, 1.0, s[0:1]
	v_cndmask_b32_e64 v11, v5, 1.0, s[0:1]
	v_cndmask_b32_e64 v10, v4, 1.0, s[0:1]
	v_cndmask_b32_e64 v15, v3, 1.0, s[0:1]
	v_cndmask_b32_e64 v14, v2, 1.0, s[0:1]
	s_waitcnt lgkmcnt(7)
	v_mov_b32_e32 v2, v12
	s_waitcnt lgkmcnt(6)
	v_mov_b32_e32 v3, v16
	s_waitcnt lgkmcnt(5)
	v_mov_b32_e32 v4, v22
	s_waitcnt lgkmcnt(4)
	v_mov_b32_e32 v5, v24
	s_mul_i32 s19, s18, 0xb0
	v_pk_mul_f32 v[2:3], v[6:7], v[2:3]
	v_pk_mul_f32 v[4:5], v[8:9], v[4:5]
	s_sub_i32 s75, s74, s19
	v_cvt_pk_bf16_f32 v2, v2, v3
	v_cvt_pk_bf16_f32 v3, v4, v5
	s_waitcnt lgkmcnt(3)
	v_mov_b32_e32 v4, v26
	s_waitcnt lgkmcnt(2)
	v_mov_b32_e32 v5, v28
	s_waitcnt lgkmcnt(1)
	v_mov_b32_e32 v38, v34
	s_waitcnt lgkmcnt(0)
; #define LAS __attribute__((address_space(3)))
; __device__ __forceinline__ unsigned cvtpk(float lo, float hi) { f32x2_t v = {lo, hi}; bf16x2_t b = __builtin_convertvector(v, bf16x2_t); return __builtin_bit_cast(unsigned, b); }
; #define LDS_WAIT() asm volatile("s_waitcnt lgkmcnt(0)" ::: "memory")
; #define CONV_JOB(it_) conv_job<LIST>((it_) < n ? (it_) : n - 1, P)
; __device__ __forceinline__ void conv_emit(const ConvJob& j, int lane, const ConvSet& s, LAS float* scr) {
;     const int k0 = 64 * j.kb; int cnt; (void)vgroup_src(j.kind, j.g, cnt);
;     const int ks = lane >> 3, n4 = (lane & 7) * 4, c = lane & 7; const bool okc = n4 < cnt;
;     const f32x4 one = (f32x4){1.f, 1.f, 1.f, 1.f}; const f32x4 g0 = j.gain ? s.g0 : one, g1 = j.gain ? s.g1 : one;
; #pragma unroll
;     for (int i = 0; i < 8; ++i) { LAS float* sp = scr + (8 * i + ks) * 33 + n4;
; #pragma unroll
;         for (int e = 0; e < 4; ++e) sp[e] = okc ? s.v[i][e] : 0.f; }
;     LDS_WAIT(); asm volatile("" ::: "memory");
; #pragma unroll
;     for (int q = 0; q < 4; ++q) { const int nn = (lane >> 3) + 8 * q; const LAS float* sr = scr + (8 * c) * 33 + nn;
;         u32x4 o; o.x = cvtpk(sr[0 * 33] * g0[0], sr[1 * 33] * g0[1]); o.y = cvtpk(sr[2 * 33] * g0[2], sr[3 * 33] * g0[3]); o.z = cvtpk(sr[4 * 33] * g1[0], sr[5 * 33] * g1[1]); o.w = cvtpk(sr[6 * 33] * g1[2], sr[7 * 33] * g1[3]);
;         *(u32x4*)(j.WT + (size_t)(j.g * 32 + nn) * j.K + k0 + 8 * c) = o; }
;     LDS_WAIT(); asm volatile("" ::: "memory");
; }
; template <int LIST> __device__ __forceinline__ void convert_list(int first, int stride, const Params& P, LAS float* scr, int lane) {
;     ...
;         conv_fetch(CONV_JOB(it + 3 * stride), lane, A); if (it + stride < n) conv_emit(CONV_JOB(it + stride), lane, B, scr);
	v_mov_b32_e32 v39, v36
	v_pk_mul_f32 v[4:5], v[14:15], v[4:5]
	v_pk_mul_f32 v[38:39], v[10:11], v[38:39]
	s_lshl_b32 s75, s75, 5
	v_cvt_pk_bf16_f32 v4, v4, v5
	v_cvt_pk_bf16_f32 v5, v38, v39
	v_or_b32_e32 v38, s75, v130
	s_lshl_b32 s18, s18, 6
	v_ashrrev_i32_e32 v39, 31, v38
	v_readlane_b32 s78, v252, 9
	s_ashr_i32 s19, s18, 31
	v_lshlrev_b64 v[38:39], 11, v[38:39]
	v_readlane_b32 s79, v252, 10
	s_lshl_b64 s[18:19], s[18:19], 1
	v_mov_b32_e32 v127, v123
	v_lshl_add_u64 v[38:39], s[78:79], 0, v[38:39]
	v_lshl_add_u64 v[38:39], v[38:39], 0, s[18:19]
	v_lshl_add_u64 v[38:39], v[38:39], 0, v[126:127]
	v_mov_b32_e32 v16, v13
	v_mov_b32_e32 v24, v23
	global_store_dwordx4 v[38:39], v[2:5], off
	v_mov_b32_e32 v28, v27
	v_mov_b32_e32 v36, v35
	v_pk_mul_f32 v[2:3], v[6:7], v[16:17]
	v_pk_mul_f32 v[4:5], v[8:9], v[24:25]
	v_cvt_pk_bf16_f32 v2, v2, v3
	v_cvt_pk_bf16_f32 v3, v4, v5
	v_pk_mul_f32 v[4:5], v[14:15], v[28:29]
	v_pk_mul_f32 v[12:13], v[10:11], v[36:37]
	v_cvt_pk_bf16_f32 v4, v4, v5
	v_cvt_pk_bf16_f32 v5, v12, v13
	v_or_b32_e32 v12, s75, v131
	v_ashrrev_i32_e32 v13, 31, v12
	v_lshlrev_b64 v[12:13], 11, v[12:13]
	v_lshl_add_u64 v[12:13], s[78:79], 0, v[12:13]
	v_lshl_add_u64 v[12:13], v[12:13], 0, s[18:19]
	v_lshl_add_u64 v[12:13], v[12:13], 0, v[126:127]
	ds_read2_b32 v[16:17], v134 offset0:16 offset1:24
	ds_read2_b32 v[22:23], v134 offset0:49 offset1:57
	global_store_dwordx4 v[12:13], v[2:5], off
	ds_read2_b32 v[12:13], v134 offset0:82 offset1:90
	ds_read2_b32 v[24:25], v134 offset0:115 offset1:123
	ds_read2_b32 v[26:27], v134 offset0:148 offset1:156
	ds_read2_b32 v[28:29], v134 offset0:181 offset1:189
	ds_read2_b32 v[34:35], v134 offset0:214 offset1:222
	ds_read2_b32 v[36:37], v134 offset0:247 offset1:255
	s_waitcnt lgkmcnt(7)
	v_mov_b32_e32 v2, v16
	s_waitcnt lgkmcnt(6)
	v_mov_b32_e32 v3, v22
	s_waitcnt lgkmcnt(5)
	v_mov_b32_e32 v4, v12
	s_waitcnt lgkmcnt(4)
	v_mov_b32_e32 v5, v24
	v_pk_mul_f32 v[2:3], v[6:7], v[2:3]
	v_pk_mul_f32 v[4:5], v[8:9], v[4:5]
	v_cvt_pk_bf16_f32 v2, v2, v3
	v_cvt_pk_bf16_f32 v3, v4, v5
	s_waitcnt lgkmcnt(3)
	v_mov_b32_e32 v4, v26
	s_waitcnt lgkmcnt(2)
	v_mov_b32_e32 v5, v28
	s_waitcnt lgkmcnt(1)
	v_mov_b32_e32 v38, v34
	s_waitcnt lgkmcnt(0)
	v_mov_b32_e32 v39, v36
	v_pk_mul_f32 v[4:5], v[14:15], v[4:5]
	v_pk_mul_f32 v[38:39], v[10:11], v[38:39]
	v_cvt_pk_bf16_f32 v4, v4, v5
	v_cvt_pk_bf16_f32 v5, v38, v39
	v_or_b32_e32 v38, s75, v132
	v_ashrrev_i32_e32 v39, 31, v38
	v_lshlrev_b64 v[38:39], 11, v[38:39]
	v_lshl_add_u64 v[38:39], s[78:79], 0, v[38:39]
	v_lshl_add_u64 v[38:39], v[38:39], 0, s[18:19]
	v_lshl_add_u64 v[38:39], v[38:39], 0, v[126:127]
	v_mov_b32_e32 v22, v17
	v_mov_b32_e32 v24, v13
	global_store_dwordx4 v[38:39], v[2:5], off
	v_mov_b32_e32 v28, v27
	v_mov_b32_e32 v36, v35
	v_pk_mul_f32 v[2:3], v[6:7], v[22:23]
	v_pk_mul_f32 v[4:5], v[8:9], v[24:25]
	v_cvt_pk_bf16_f32 v2, v2, v3
	v_cvt_pk_bf16_f32 v3, v4, v5
	v_pk_mul_f32 v[4:5], v[14:15], v[28:29]
	v_pk_mul_f32 v[6:7], v[10:11], v[36:37]
	v_cvt_pk_bf16_f32 v4, v4, v5
	v_cvt_pk_bf16_f32 v5, v6, v7
	v_or_b32_e32 v6, s75, v133
	v_ashrrev_i32_e32 v7, 31, v6
	v_lshlrev_b64 v[6:7], 11, v[6:7]
	v_lshl_add_u64 v[6:7], s[78:79], 0, v[6:7]
	v_lshl_add_u64 v[6:7], v[6:7], 0, s[18:19]
	s_add_i32 s18, s34, s74
	s_min_i32 s18, s18, 0xaff
	s_mul_hi_i32 s19, s18, 0x2e8ba2e9
	s_lshr_b32 s75, s19, 31
	s_ashr_i32 s19, s19, 5
	s_add_i32 s19, s19, s75
	s_mul_i32 s75, s19, 0xb0
	s_sub_i32 s75, s18, s75
	s_lshl_b32 s18, s19, 6
	s_bfe_i32 s19, s75, 0x10002
	s_lshl_b32 s77, s75, 4
	s_and_b32 s19, s19, 0xb00
	s_and_b32 s77, s77, 0xffffff80
	s_lshl_b32 s75, s75, 5
	s_add_i32 s19, s19, s77
	s_and_b32 s75, s75, 0x60
	v_lshl_add_u64 v[6:7], v[6:7], 0, v[126:127]
	s_or_b32 s78, s19, s75
	s_ashr_i32 s19, s18, 31
	v_or_b32_e32 v10, s18, v130
	global_store_dwordx4 v[6:7], v[2:5], off
	s_ashr_i32 s79, s78, 31
	s_waitcnt lgkmcnt(0)
	s_cmpk_gt_i32 s35, 0xaff
	v_lshl_add_u64 v[2:3], s[18:19], 2, v[124:125]
	v_mad_i64_i32 v[10:11], s[18:19], v10, s20, v[128:129]
	v_lshl_add_u64 v[10:11], s[78:79], 2, v[10:11]
	v_lshl_add_u64 v[42:43], v[10:11], 0, v[122:123]
	v_add_co_u32_e32 v14, vcc, s21, v42
	v_cndmask_b32_e64 v7, v3, v150, s[0:1]
	s_nop 0
	v_addc_co_u32_e32 v15, vcc, 0, v43, vcc
	v_add_co_u32_e32 v22, vcc, s24, v42
	v_cndmask_b32_e64 v6, v2, v151, s[0:1]
	s_nop 0
	v_addc_co_u32_e32 v23, vcc, 0, v43, vcc
	v_add_co_u32_e32 v26, vcc, s25, v42
	global_load_dwordx4 v[2:5], v[6:7], off offset:16 nt
	s_nop 0
	global_load_dwordx4 v[6:9], v[6:7], off nt
	v_addc_co_u32_e32 v27, vcc, 0, v43, vcc
	v_add_co_u32_e32 v34, vcc, s28, v42
	global_load_dwordx4 v[10:13], v[42:43], off nt
	s_nop 0
	global_load_dwordx4 v[14:17], v[14:15], off nt
	v_addc_co_u32_e32 v35, vcc, 0, v43, vcc
	v_add_co_u32_e32 v38, vcc, 0xdc000, v42
	global_load_dwordx4 v[22:25], v[22:23], off nt
	s_nop 0
	global_load_dwordx4 v[26:29], v[26:27], off nt
	v_addc_co_u32_e32 v39, vcc, 0, v43, vcc
	v_add_co_u32_e32 v44, vcc, 0x108000, v42
	global_load_dwordx4 v[34:37], v[34:35], off nt
	s_nop 0
	global_load_dwordx4 v[38:41], v[38:39], off nt
	v_addc_co_u32_e32 v45, vcc, 0, v43, vcc
	v_add_co_u32_e32 v46, vcc, 0x134000, v42
	s_nop 1
	v_addc_co_u32_e32 v47, vcc, 0, v43, vcc
	global_load_dwordx4 v[42:45], v[44:45], off nt
	s_nop 0
	global_load_dwordx4 v[46:49], v[46:47], off nt
	s_cbranch_scc1 .LBB0_242
; #define LAS __attribute__((address_space(3)))
; __device__ __forceinline__ unsigned cvtpk(float lo, float hi) { f32x2_t v = {lo, hi}; bf16x2_t b = __builtin_convertvector(v, bf16x2_t); return __builtin_bit_cast(unsigned, b); }
; #define LDS_WAIT() asm volatile("s_waitcnt lgkmcnt(0)" ::: "memory")
; #define CONV_JOB(it_) conv_job<LIST>((it_) < n ? (it_) : n - 1, P)
; __device__ __forceinline__ void conv_emit(const ConvJob& j, int lane, const ConvSet& s, LAS float* scr) {
;     const int k0 = 64 * j.kb; int cnt; (void)vgroup_src(j.kind, j.g, cnt);
;     const int ks = lane >> 3, n4 = (lane & 7) * 4, c = lane & 7; const bool okc = n4 < cnt;
;     const f32x4 one = (f32x4){1.f, 1.f, 1.f, 1.f}; const f32x4 g0 = j.gain ? s.g0 : one, g1 = j.gain ? s.g1 : one;
; #pragma unroll
;     for (int i = 0; i < 8; ++i) { LAS float* sp = scr + (8 * i + ks) * 33 + n4;
; #pragma unroll
;         for (int e = 0; e < 4; ++e) sp[e] = okc ? s.v[i][e] : 0.f; }
;     LDS_WAIT(); asm volatile("" ::: "memory");
; #pragma unroll
;     for (int q = 0; q < 4; ++q) { const int nn = (lane >> 3) + 8 * q; const LAS float* sr = scr + (8 * c) * 33 + nn;
;         u32x4 o; o.x = cvtpk(sr[0 * 33] * g0[0], sr[1 * 33] * g0[1]); o.y = cvtpk(sr[2 * 33] * g0[2], sr[3 * 33] * g0[3]); o.z = cvtpk(sr[4 * 33] * g1[0], sr[5 * 33] * g1[1]); o.w = cvtpk(sr[6 * 33] * g1[2], sr[7 * 33] * g1[3]);
;         *(u32x4*)(j.WT + (size_t)(j.g * 32 + nn) * j.K + k0 + 8 * c) = o; }
;     LDS_WAIT(); asm volatile("" ::: "memory");
; }
; template <int LIST> __device__ __forceinline__ void convert_list(int first, int stride, const Params& P, LAS float* scr, int lane) {
;     ...
;         conv_fetch(CONV_JOB(it + 3 * stride), lane, A); if (it + stride < n) conv_emit(CONV_JOB(it + stride), lane, B, scr);
	s_waitcnt vmcnt(31)
	ds_write2_b32 v135, v50, v51 offset1:1
	ds_write2_b32 v135, v52, v53 offset0:2 offset1:3
	s_waitcnt vmcnt(30)
	ds_write2_b32 v136, v54, v55 offset1:1
	ds_write2_b32 v137, v56, v57 offset1:1
	s_waitcnt vmcnt(29)
	ds_write2_b32 v138, v58, v59 offset1:1
	ds_write2_b32 v139, v60, v61 offset1:1
	s_waitcnt vmcnt(28)
	ds_write2_b32 v140, v62, v63 offset1:1
	ds_write2_b32 v141, v64, v65 offset1:1
	s_waitcnt vmcnt(27)
	ds_write2_b32 v142, v66, v67 offset1:1
	ds_write2_b32 v143, v68, v69 offset1:1
	s_waitcnt vmcnt(26)
	ds_write2_b32 v144, v70, v71 offset1:1
	ds_write2_b32 v145, v72, v73 offset1:1
	s_waitcnt vmcnt(25)
	ds_write2_b32 v146, v74, v75 offset1:1
	ds_write2_b32 v147, v76, v77 offset1:1
	s_waitcnt vmcnt(24)
	ds_write2_b32 v148, v78, v79 offset1:1
	ds_write2_b32 v149, v80, v81 offset1:1
	s_waitcnt lgkmcnt(0)
	ds_read2_b32 v[52:53], v134 offset1:8
	ds_read2_b32 v[56:57], v134 offset0:33 offset1:41
	ds_read2_b32 v[58:59], v134 offset0:66 offset1:74
	ds_read2_b32 v[60:61], v134 offset0:99 offset1:107
	ds_read2_b32 v[62:63], v134 offset0:132 offset1:140
	ds_read2_b32 v[64:65], v134 offset0:165 offset1:173
	ds_read2_b32 v[66:67], v134 offset0:198 offset1:206
	ds_read2_b32 v[68:69], v134 offset0:231 offset1:239
	s_mul_hi_i32 s18, s35, 0x2e8ba2e9
	s_lshr_b32 s19, s18, 31
	s_ashr_i32 s18, s18, 5
	s_add_i32 s18, s18, s19
	v_cndmask_b32_e64 v33, v33, 1.0, s[0:1]
	v_cndmask_b32_e64 v32, v32, 1.0, s[0:1]
	v_cndmask_b32_e64 v31, v31, 1.0, s[0:1]
	v_cndmask_b32_e64 v30, v30, 1.0, s[0:1]
	v_cndmask_b32_e64 v51, v21, 1.0, s[0:1]
	v_cndmask_b32_e64 v50, v20, 1.0, s[0:1]
	v_cndmask_b32_e64 v55, v19, 1.0, s[0:1]
	v_cndmask_b32_e64 v54, v18, 1.0, s[0:1]
	s_waitcnt lgkmcnt(7)
	v_mov_b32_e32 v18, v52
	s_waitcnt lgkmcnt(6)
	v_mov_b32_e32 v19, v56
	s_waitcnt lgkmcnt(5)
	v_mov_b32_e32 v20, v58
	s_waitcnt lgkmcnt(4)
	v_mov_b32_e32 v21, v60
	s_mul_i32 s19, s18, 0xb0
	v_pk_mul_f32 v[18:19], v[30:31], v[18:19]
	v_pk_mul_f32 v[20:21], v[32:33], v[20:21]
	s_sub_i32 s75, s35, s19
	v_cvt_pk_bf16_f32 v18, v18, v19
	v_cvt_pk_bf16_f32 v19, v20, v21
	s_waitcnt lgkmcnt(3)
	v_mov_b32_e32 v20, v62
	s_waitcnt lgkmcnt(2)
	v_mov_b32_e32 v21, v64
	s_waitcnt lgkmcnt(1)
	v_mov_b32_e32 v70, v66
	s_waitcnt lgkmcnt(0)
	v_mov_b32_e32 v71, v68
	v_pk_mul_f32 v[20:21], v[54:55], v[20:21]
	v_pk_mul_f32 v[70:71], v[50:51], v[70:71]
	s_lshl_b32 s75, s75, 5
	v_cvt_pk_bf16_f32 v20, v20, v21
	v_cvt_pk_bf16_f32 v21, v70, v71
	v_or_b32_e32 v70, s75, v130
	s_lshl_b32 s18, s18, 6
	v_ashrrev_i32_e32 v71, 31, v70
	v_readlane_b32 s78, v252, 9
	s_ashr_i32 s19, s18, 31
	v_lshlrev_b64 v[70:71], 11, v[70:71]
	v_readlane_b32 s79, v252, 10
	s_lshl_b64 s[18:19], s[18:19], 1
	v_mov_b32_e32 v56, v53
	v_lshl_add_u64 v[70:71], s[78:79], 0, v[70:71]
	v_lshl_add_u64 v[70:71], v[70:71], 0, s[18:19]
	v_lshl_add_u64 v[70:71], v[70:71], 0, v[126:127]
	v_mov_b32_e32 v60, v59
	global_store_dwordx4 v[70:71], v[18:21], off
	v_mov_b32_e32 v64, v63
	v_mov_b32_e32 v68, v67
	v_pk_mul_f32 v[18:19], v[30:31], v[56:57]
	v_pk_mul_f32 v[20:21], v[32:33], v[60:61]
	v_cvt_pk_bf16_f32 v18, v18, v19
	v_cvt_pk_bf16_f32 v19, v20, v21
	v_pk_mul_f32 v[20:21], v[54:55], v[64:65]
	v_pk_mul_f32 v[52:53], v[50:51], v[68:69]
	v_cvt_pk_bf16_f32 v20, v20, v21
	v_cvt_pk_bf16_f32 v21, v52, v53
	v_or_b32_e32 v52, s75, v131
	v_ashrrev_i32_e32 v53, 31, v52
	v_lshlrev_b64 v[52:53], 11, v[52:53]
	v_lshl_add_u64 v[52:53], s[78:79], 0, v[52:53]
	v_lshl_add_u64 v[52:53], v[52:53], 0, s[18:19]
	v_lshl_add_u64 v[52:53], v[52:53], 0, v[126:127]
	ds_read2_b32 v[56:57], v134 offset0:16 offset1:24
	ds_read2_b32 v[58:59], v134 offset0:49 offset1:57
	global_store_dwordx4 v[52:53], v[18:21], off
	ds_read2_b32 v[52:53], v134 offset0:82 offset1:90
	ds_read2_b32 v[60:61], v134 offset0:115 offset1:123
	ds_read2_b32 v[62:63], v134 offset0:148 offset1:156
	ds_read2_b32 v[64:65], v134 offset0:181 offset1:189
	ds_read2_b32 v[66:67], v134 offset0:214 offset1:222
	ds_read2_b32 v[68:69], v134 offset0:247 offset1:255
	s_waitcnt lgkmcnt(7)
	v_mov_b32_e32 v18, v56
	s_waitcnt lgkmcnt(6)
	v_mov_b32_e32 v19, v58
	s_waitcnt lgkmcnt(5)
	v_mov_b32_e32 v20, v52
	s_waitcnt lgkmcnt(4)
	v_mov_b32_e32 v21, v60
	v_pk_mul_f32 v[18:19], v[30:31], v[18:19]
	v_pk_mul_f32 v[20:21], v[32:33], v[20:21]
	v_cvt_pk_bf16_f32 v18, v18, v19
	v_cvt_pk_bf16_f32 v19, v20, v21
	s_waitcnt lgkmcnt(3)
	v_mov_b32_e32 v20, v62
	s_waitcnt lgkmcnt(2)
	v_mov_b32_e32 v21, v64
	s_waitcnt lgkmcnt(1)
	v_mov_b32_e32 v70, v66
	s_waitcnt lgkmcnt(0)
	v_mov_b32_e32 v71, v68
	v_pk_mul_f32 v[20:21], v[54:55], v[20:21]
	v_pk_mul_f32 v[70:71], v[50:51], v[70:71]
	v_cvt_pk_bf16_f32 v20, v20, v21
	v_cvt_pk_bf16_f32 v21, v70, v71
	v_or_b32_e32 v70, s75, v132
	v_ashrrev_i32_e32 v71, 31, v70
	v_lshlrev_b64 v[70:71], 11, v[70:71]
	v_lshl_add_u64 v[70:71], s[78:79], 0, v[70:71]
	v_lshl_add_u64 v[70:71], v[70:71], 0, s[18:19]
	v_lshl_add_u64 v[70:71], v[70:71], 0, v[126:127]
	v_mov_b32_e32 v58, v57
	v_mov_b32_e32 v60, v53
	global_store_dwordx4 v[70:71], v[18:21], off
	v_mov_b32_e32 v64, v63
	v_mov_b32_e32 v68, v67
	v_pk_mul_f32 v[18:19], v[30:31], v[58:59]
	v_pk_mul_f32 v[20:21], v[32:33], v[60:61]
	v_cvt_pk_bf16_f32 v18, v18, v19
	v_cvt_pk_bf16_f32 v19, v20, v21
	v_pk_mul_f32 v[20:21], v[54:55], v[64:65]
	v_pk_mul_f32 v[30:31], v[50:51], v[68:69]
	v_cvt_pk_bf16_f32 v20, v20, v21
	v_cvt_pk_bf16_f32 v21, v30, v31
	v_or_b32_e32 v30, s75, v133
	v_ashrrev_i32_e32 v31, 31, v30
	v_lshlrev_b64 v[30:31], 11, v[30:31]
	v_lshl_add_u64 v[30:31], s[78:79], 0, v[30:31]
	v_lshl_add_u64 v[30:31], v[30:31], 0, s[18:19]
	v_lshl_add_u64 v[30:31], v[30:31], 0, v[126:127]
	global_store_dwordx4 v[30:31], v[18:21], off
	s_waitcnt lgkmcnt(0)
; #define LAS __attribute__((address_space(3)))
; __device__ __forceinline__ unsigned cvtpk(float lo, float hi) { f32x2_t v = {lo, hi}; bf16x2_t b = __builtin_convertvector(v, bf16x2_t); return __builtin_bit_cast(unsigned, b); }
; #define LDS_WAIT() asm volatile("s_waitcnt lgkmcnt(0)" ::: "memory")
; #define CONV_JOB(it_) conv_job<LIST>((it_) < n ? (it_) : n - 1, P)
; __device__ __forceinline__ void conv_fetch(const ConvJob& j, int lane, ConvSet& s) {
;     const int k0 = 64 * j.kb; int cnt; const int src = vgroup_src(j.kind, j.g, cnt);
;     const int ks = lane >> 3, n4 = (lane & 7) * 4, c = lane & 7; const bool okc = n4 < cnt;
;     const float* gp = j.gain ? j.gain + k0 + 8 * c : j.W;
;     s.g0 = *(const f32x4*)gp; s.g1 = *(const f32x4*)(gp + 4);
;     const float* wp = j.W + (size_t)(k0 + ks) * j.Norig + src + (okc ? n4 : 0);
; #pragma unroll
;     for (int i = 0; i < 8; ++i) s.v[i] = *(const f32x4*)(wp + (size_t)(8 * i) * j.Norig);
; }
; __device__ __forceinline__ void conv_emit(const ConvJob& j, int lane, const ConvSet& s, LAS float* scr) {
;     const int k0 = 64 * j.kb; int cnt; (void)vgroup_src(j.kind, j.g, cnt);
;     const int ks = lane >> 3, n4 = (lane & 7) * 4, c = lane & 7; const bool okc = n4 < cnt;
;     const f32x4 one = (f32x4){1.f, 1.f, 1.f, 1.f}; const f32x4 g0 = j.gain ? s.g0 : one, g1 = j.gain ? s.g1 : one;
; #pragma unroll
;     for (int i = 0; i < 8; ++i) { LAS float* sp = scr + (8 * i + ks) * 33 + n4;
; #pragma unroll
;         for (int e = 0; e < 4; ++e) sp[e] = okc ? s.v[i][e] : 0.f; }
;     LDS_WAIT(); asm volatile("" ::: "memory");
; #pragma unroll
;     for (int q = 0; q < 4; ++q) { const int nn = (lane >> 3) + 8 * q; const LAS float* sr = scr + (8 * c) * 33 + nn;
;         u32x4 o; o.x = cvtpk(sr[0 * 33] * g0[0], sr[1 * 33] * g0[1]); o.y = cvtpk(sr[2 * 33] * g0[2], sr[3 * 33] * g0[3]); o.z = cvtpk(sr[4 * 33] * g1[0], sr[5 * 33] * g1[1]); o.w = cvtpk(sr[6 * 33] * g1[2], sr[7 * 33] * g1[3]);
;         *(u32x4*)(j.WT + (size_t)(j.g * 32 + nn) * j.K + k0 + 8 * c) = o; }
;     LDS_WAIT(); asm volatile("" ::: "memory");
; }
; template <int LIST> __device__ __forceinline__ void convert_list(int first, int stride, const Params& P, LAS float* scr, int lane) {
;     ...
;         conv_fetch(CONV_JOB(it + 4 * stride), lane, B); if (it + 2 * stride < n) conv_emit(CONV_JOB(it + 2 * stride), lane, C, scr);
.LBB0_242:
	s_add_i32 s18, s72, s74
	s_min_i32 s18, s18, 0xaff
	s_mul_hi_i32 s19, s18, 0x2e8ba2e9
	s_lshr_b32 s74, s19, 31
	s_ashr_i32 s19, s19, 5
	s_add_i32 s19, s19, s74
	s_mul_i32 s74, s19, 0xb0
	s_sub_i32 s74, s18, s74
	s_lshl_b32 s18, s19, 6
	s_bfe_i32 s19, s74, 0x10002
	s_lshl_b32 s75, s74, 4
	s_and_b32 s19, s19, 0xb00
	s_and_b32 s75, s75, 0xffffff80
	s_lshl_b32 s74, s74, 5
	s_add_i32 s19, s19, s75
	s_and_b32 s74, s74, 0x60
	s_or_b32 s74, s19, s74
	s_ashr_i32 s19, s18, 31
	s_waitcnt vmcnt(31)
	v_or_b32_e32 v52, s18, v130
	v_mov_b64_e32 v[50:51], s[44:45]
	v_lshl_add_u64 v[18:19], s[18:19], 2, v[124:125]
	v_mad_i64_i32 v[50:51], s[18:19], v52, s20, v[50:51]
	s_ashr_i32 s75, s74, 31
	v_lshl_add_u64 v[50:51], s[74:75], 2, v[50:51]
	s_waitcnt vmcnt(25)
	v_lshl_add_u64 v[74:75], v[50:51], 0, v[122:123]
	v_add_co_u32_e32 v54, vcc, s21, v74
	v_mov_b32_e32 v20, s45
	s_nop 0
	v_addc_co_u32_e32 v55, vcc, 0, v75, vcc
	v_add_co_u32_e32 v58, vcc, s24, v74
	v_cndmask_b32_e64 v31, v19, v20, s[0:1]
	s_nop 0
	v_addc_co_u32_e32 v59, vcc, 0, v75, vcc
	v_add_co_u32_e32 v62, vcc, s25, v74
	v_mov_b32_e32 v19, s44
	s_nop 0
	v_addc_co_u32_e32 v63, vcc, 0, v75, vcc
	v_add_co_u32_e32 v66, vcc, s28, v74
	v_cndmask_b32_e64 v30, v18, v19, s[0:1]
	s_nop 0
	v_addc_co_u32_e32 v67, vcc, 0, v75, vcc
	v_add_co_u32_e32 v70, vcc, 0xdc000, v74
	global_load_dwordx4 v[18:21], v[30:31], off offset:16 nt
	s_nop 0
	global_load_dwordx4 v[30:33], v[30:31], off nt
	v_addc_co_u32_e32 v71, vcc, 0, v75, vcc
	v_add_co_u32_e32 v76, vcc, 0x108000, v74
	global_load_dwordx4 v[50:53], v[74:75], off nt
	s_nop 0
	global_load_dwordx4 v[54:57], v[54:55], off nt
	v_addc_co_u32_e32 v77, vcc, 0, v75, vcc
	s_waitcnt vmcnt(28)
	v_add_co_u32_e32 v78, vcc, 0x134000, v74
	global_load_dwordx4 v[58:61], v[58:59], off nt
	s_nop 0
	global_load_dwordx4 v[62:65], v[62:63], off nt
	v_addc_co_u32_e32 v79, vcc, 0, v75, vcc
	global_load_dwordx4 v[66:69], v[66:67], off nt
	s_nop 0
	global_load_dwordx4 v[70:73], v[70:71], off nt
	s_nop 0
	global_load_dwordx4 v[74:77], v[76:77], off nt
	s_nop 0
	global_load_dwordx4 v[78:81], v[78:79], off nt
	s_andn2_b64 vcc, exec, s[6:7]
	s_cbranch_vccnz .LBB0_239
	s_waitcnt vmcnt(31)
	ds_write2_b32 v135, v90, v91 offset1:1
	ds_write2_b32 v135, v92, v93 offset0:2 offset1:3
	s_waitcnt vmcnt(30)
	ds_write2_b32 v136, v94, v95 offset1:1
	ds_write2_b32 v137, v96, v97 offset1:1
	s_waitcnt vmcnt(29)
	ds_write2_b32 v138, v98, v99 offset1:1
	ds_write2_b32 v139, v100, v101 offset1:1
	s_waitcnt vmcnt(28)
	ds_write2_b32 v140, v102, v103 offset1:1
	ds_write2_b32 v141, v104, v105 offset1:1
	s_waitcnt vmcnt(27)
	ds_write2_b32 v142, v106, v107 offset1:1
	ds_write2_b32 v143, v108, v109 offset1:1
	s_waitcnt vmcnt(26)
	ds_write2_b32 v144, v110, v111 offset1:1
	ds_write2_b32 v145, v112, v113 offset1:1
	s_waitcnt vmcnt(25)
	ds_write2_b32 v146, v114, v115 offset1:1
	ds_write2_b32 v147, v116, v117 offset1:1
	s_waitcnt vmcnt(24)
	ds_write2_b32 v148, v118, v119 offset1:1
	ds_write2_b32 v149, v120, v121 offset1:1
	s_waitcnt lgkmcnt(0)
	ds_read2_b32 v[92:93], v134 offset1:8
	ds_read2_b32 v[96:97], v134 offset0:33 offset1:41
	ds_read2_b32 v[98:99], v134 offset0:66 offset1:74
	ds_read2_b32 v[100:101], v134 offset0:99 offset1:107
	ds_read2_b32 v[102:103], v134 offset0:132 offset1:140
	ds_read2_b32 v[104:105], v134 offset0:165 offset1:173
	ds_read2_b32 v[106:107], v134 offset0:198 offset1:206
	ds_read2_b32 v[108:109], v134 offset0:231 offset1:239
	s_mul_hi_i32 s6, s73, 0x2e8ba2e9
	s_lshr_b32 s7, s6, 31
	s_ashr_i32 s6, s6, 5
	s_add_i32 s6, s6, s7
	v_cndmask_b32_e64 v89, v89, 1.0, s[0:1]
	v_cndmask_b32_e64 v88, v88, 1.0, s[0:1]
	v_cndmask_b32_e64 v87, v87, 1.0, s[0:1]
	v_cndmask_b32_e64 v86, v86, 1.0, s[0:1]
	v_cndmask_b32_e64 v91, v85, 1.0, s[0:1]
	v_cndmask_b32_e64 v90, v84, 1.0, s[0:1]
	v_cndmask_b32_e64 v95, v83, 1.0, s[0:1]
	v_cndmask_b32_e64 v94, v82, 1.0, s[0:1]
	s_waitcnt lgkmcnt(7)
	v_mov_b32_e32 v82, v92
	s_waitcnt lgkmcnt(6)
	v_mov_b32_e32 v83, v96
	s_waitcnt lgkmcnt(5)
	v_mov_b32_e32 v84, v98
	s_waitcnt lgkmcnt(4)
	v_mov_b32_e32 v85, v100
	s_mul_i32 s7, s6, 0xb0
	v_pk_mul_f32 v[82:83], v[86:87], v[82:83]
	v_pk_mul_f32 v[84:85], v[88:89], v[84:85]
	s_sub_i32 s18, s73, s7
	v_cvt_pk_bf16_f32 v82, v82, v83
	v_cvt_pk_bf16_f32 v83, v84, v85
	s_waitcnt lgkmcnt(3)
	v_mov_b32_e32 v84, v102
	s_waitcnt lgkmcnt(2)
	v_mov_b32_e32 v85, v104
	s_waitcnt lgkmcnt(1)
	v_mov_b32_e32 v110, v106
	s_waitcnt lgkmcnt(0)
	v_mov_b32_e32 v111, v108
	v_pk_mul_f32 v[84:85], v[94:95], v[84:85]
	v_pk_mul_f32 v[110:111], v[90:91], v[110:111]
	s_lshl_b32 s18, s18, 5
	v_cvt_pk_bf16_f32 v84, v84, v85
	v_cvt_pk_bf16_f32 v85, v110, v111
	v_or_b32_e32 v110, s18, v130
	s_lshl_b32 s6, s6, 6
	v_ashrrev_i32_e32 v111, 31, v110
	v_readlane_b32 s74, v252, 9
	s_ashr_i32 s7, s6, 31
	v_lshlrev_b64 v[110:111], 11, v[110:111]
	v_readlane_b32 s75, v252, 10
	s_lshl_b64 s[6:7], s[6:7], 1
	v_mov_b32_e32 v127, v123
	v_lshl_add_u64 v[110:111], s[74:75], 0, v[110:111]
	v_lshl_add_u64 v[110:111], v[110:111], 0, s[6:7]
	v_lshl_add_u64 v[110:111], v[110:111], 0, v[126:127]
	v_mov_b32_e32 v96, v93
	v_mov_b32_e32 v100, v99
	global_store_dwordx4 v[110:111], v[82:85], off
	v_mov_b32_e32 v104, v103
	v_mov_b32_e32 v108, v107
	v_pk_mul_f32 v[82:83], v[86:87], v[96:97]
	v_pk_mul_f32 v[84:85], v[88:89], v[100:101]
	v_cvt_pk_bf16_f32 v82, v82, v83
	v_cvt_pk_bf16_f32 v83, v84, v85
	v_pk_mul_f32 v[84:85], v[94:95], v[104:105]
	v_pk_mul_f32 v[92:93], v[90:91], v[108:109]
	v_cvt_pk_bf16_f32 v84, v84, v85
	v_cvt_pk_bf16_f32 v85, v92, v93
	v_or_b32_e32 v92, s18, v131
	v_ashrrev_i32_e32 v93, 31, v92
	v_lshlrev_b64 v[92:93], 11, v[92:93]
	v_lshl_add_u64 v[92:93], s[74:75], 0, v[92:93]
	v_lshl_add_u64 v[92:93], v[92:93], 0, s[6:7]
	v_lshl_add_u64 v[92:93], v[92:93], 0, v[126:127]
	ds_read2_b32 v[96:97], v134 offset0:16 offset1:24
	ds_read2_b32 v[98:99], v134 offset0:49 offset1:57
	global_store_dwordx4 v[92:93], v[82:85], off
	ds_read2_b32 v[92:93], v134 offset0:82 offset1:90
	ds_read2_b32 v[100:101], v134 offset0:115 offset1:123
	ds_read2_b32 v[102:103], v134 offset0:148 offset1:156
	ds_read2_b32 v[104:105], v134 offset0:181 offset1:189
	ds_read2_b32 v[106:107], v134 offset0:214 offset1:222
	ds_read2_b32 v[108:109], v134 offset0:247 offset1:255
	s_waitcnt lgkmcnt(7)
; #define LAS __attribute__((address_space(3)))
; __device__ __forceinline__ unsigned cvtpk(float lo, float hi) { f32x2_t v = {lo, hi}; bf16x2_t b = __builtin_convertvector(v, bf16x2_t); return __builtin_bit_cast(unsigned, b); }
; #define LDS_WAIT() asm volatile("s_waitcnt lgkmcnt(0)" ::: "memory")
; __device__ __forceinline__ void conv_fetch(const ConvJob& j, int lane, ConvSet& s) {
;     const int k0 = 64 * j.kb; int cnt; const int src = vgroup_src(j.kind, j.g, cnt);
;     const int ks = lane >> 3, n4 = (lane & 7) * 4, c = lane & 7; const bool okc = n4 < cnt;
;     const float* gp = j.gain ? j.gain + k0 + 8 * c : j.W;
;     s.g0 = *(const f32x4*)gp; s.g1 = *(const f32x4*)(gp + 4);
;     const float* wp = j.W + (size_t)(k0 + ks) * j.Norig + src + (okc ? n4 : 0);
; #pragma unroll
;     for (int i = 0; i < 8; ++i) s.v[i] = *(const f32x4*)(wp + (size_t)(8 * i) * j.Norig);
; }
; __device__ __forceinline__ void conv_emit(const ConvJob& j, int lane, const ConvSet& s, LAS float* scr) {
;     const int k0 = 64 * j.kb; int cnt; (void)vgroup_src(j.kind, j.g, cnt);
;     const int ks = lane >> 3, n4 = (lane & 7) * 4, c = lane & 7; const bool okc = n4 < cnt;
;     const f32x4 one = (f32x4){1.f, 1.f, 1.f, 1.f}; const f32x4 g0 = j.gain ? s.g0 : one, g1 = j.gain ? s.g1 : one;
; #pragma unroll
;     for (int i = 0; i < 8; ++i) { LAS float* sp = scr + (8 * i + ks) * 33 + n4;
; #pragma unroll
;         for (int e = 0; e < 4; ++e) sp[e] = okc ? s.v[i][e] : 0.f; }
;     LDS_WAIT(); asm volatile("" ::: "memory");
; #pragma unroll
;     for (int q = 0; q < 4; ++q) { const int nn = (lane >> 3) + 8 * q; const LAS float* sr = scr + (8 * c) * 33 + nn;
;         u32x4 o; o.x = cvtpk(sr[0 * 33] * g0[0], sr[1 * 33] * g0[1]); o.y = cvtpk(sr[2 * 33] * g0[2], sr[3 * 33] * g0[3]); o.z = cvtpk(sr[4 * 33] * g1[0], sr[5 * 33] * g1[1]); o.w = cvtpk(sr[6 * 33] * g1[2], sr[7 * 33] * g1[3]);
;         *(u32x4*)(j.WT + (size_t)(j.g * 32 + nn) * j.K + k0 + 8 * c) = o; }
;     LDS_WAIT(); asm volatile("" ::: "memory");
; }
	v_mov_b32_e32 v82, v96
	s_waitcnt lgkmcnt(6)
	v_mov_b32_e32 v83, v98
	s_waitcnt lgkmcnt(5)
	v_mov_b32_e32 v84, v92
	s_waitcnt lgkmcnt(4)
	v_mov_b32_e32 v85, v100
	v_pk_mul_f32 v[82:83], v[86:87], v[82:83]
	v_pk_mul_f32 v[84:85], v[88:89], v[84:85]
	v_cvt_pk_bf16_f32 v82, v82, v83
	v_cvt_pk_bf16_f32 v83, v84, v85
	s_waitcnt lgkmcnt(3)
	v_mov_b32_e32 v84, v102
	s_waitcnt lgkmcnt(2)
	v_mov_b32_e32 v85, v104
	s_waitcnt lgkmcnt(1)
	v_mov_b32_e32 v110, v106
	s_waitcnt lgkmcnt(0)
	v_mov_b32_e32 v111, v108
	v_pk_mul_f32 v[84:85], v[94:95], v[84:85]
	v_pk_mul_f32 v[110:111], v[90:91], v[110:111]
	v_cvt_pk_bf16_f32 v84, v84, v85
	v_cvt_pk_bf16_f32 v85, v110, v111
	v_or_b32_e32 v110, s18, v132
	v_ashrrev_i32_e32 v111, 31, v110
	v_lshlrev_b64 v[110:111], 11, v[110:111]
	v_lshl_add_u64 v[110:111], s[74:75], 0, v[110:111]
	v_lshl_add_u64 v[110:111], v[110:111], 0, s[6:7]
	v_lshl_add_u64 v[110:111], v[110:111], 0, v[126:127]
	v_mov_b32_e32 v98, v97
	v_mov_b32_e32 v100, v93
	global_store_dwordx4 v[110:111], v[82:85], off
	v_mov_b32_e32 v104, v103
	v_mov_b32_e32 v108, v107
	v_pk_mul_f32 v[82:83], v[86:87], v[98:99]
	v_pk_mul_f32 v[84:85], v[88:89], v[100:101]
	v_cvt_pk_bf16_f32 v82, v82, v83
	v_cvt_pk_bf16_f32 v83, v84, v85
	v_pk_mul_f32 v[84:85], v[94:95], v[104:105]
	v_pk_mul_f32 v[86:87], v[90:91], v[108:109]
	v_cvt_pk_bf16_f32 v84, v84, v85
	v_cvt_pk_bf16_f32 v85, v86, v87
	v_or_b32_e32 v86, s18, v133
	v_ashrrev_i32_e32 v87, 31, v86
	v_lshlrev_b64 v[86:87], 11, v[86:87]
	v_lshl_add_u64 v[86:87], s[74:75], 0, v[86:87]
	v_lshl_add_u64 v[86:87], v[86:87], 0, s[6:7]
	v_lshl_add_u64 v[86:87], v[86:87], 0, v[126:127]
	global_store_dwordx4 v[86:87], v[82:85], off
	s_waitcnt lgkmcnt(0)
	s_branch .LBB0_239
.LBB0_244:
	s_cmpk_gt_i32 s70, 0x57f
	s_cbranch_scc1 .LBB0_251
	s_ashr_i32 s0, s70, 31
	s_lshr_b32 s0, s0, 27
	s_add_i32 s0, s70, s0
	s_and_b32 s1, s0, 0x7ffffe0
	s_lshl_b32 s0, s0, 1
	s_and_b32 s6, s0, 0xffffffc0
	s_waitcnt vmcnt(27)
	v_lshrrev_b32_e32 v102, 3, v198
	s_waitcnt vmcnt(19)
	v_or_b32_e32 v2, s6, v102
	s_sub_i32 s1, s70, s1
	v_ashrrev_i32_e32 v3, 31, v2
	s_lshl_b32 s0, s1, 5
	v_lshlrev_b64 v[2:3], 12, v[2:3]
	s_waitcnt vmcnt(1)
	v_and_b32_e32 v75, 7, v0
	v_lshl_add_u64 v[2:3], s[46:47], 0, v[2:3]
	s_ashr_i32 s1, s0, 31
	v_mov_b32_e32 v99, 0
	v_lshl_add_u64 v[2:3], s[0:1], 2, v[2:3]
	v_lshlrev_b32_e32 v98, 4, v75
	v_lshl_add_u64 v[26:27], v[2:3], 0, v[98:99]
	s_mov_b32 s6, 0x8000
	v_add_co_u32_e32 v6, vcc, s6, v26
	s_mov_b32 s7, 0x10000
	s_nop 0
	v_addc_co_u32_e32 v7, vcc, 0, v27, vcc
	s_add_i32 s0, s92, s70
	v_add_co_u32_e32 v10, vcc, s7, v26
	s_min_i32 s0, s0, 0x57f
	s_nop 0
	v_addc_co_u32_e32 v11, vcc, 0, v27, vcc
	s_mov_b32 s18, 0x18000
	s_ashr_i32 s1, s0, 31
	v_add_co_u32_e32 v14, vcc, s18, v26
	s_lshr_b32 s1, s1, 27
	s_nop 0
	v_addc_co_u32_e32 v15, vcc, 0, v27, vcc
	s_mov_b32 s19, 0x20000
	s_add_i32 s1, s0, s1
	v_add_co_u32_e32 v18, vcc, s19, v26
	s_and_b32 s25, s1, 0x7ffffe0
	s_lshl_b32 s1, s1, 1
	v_addc_co_u32_e32 v19, vcc, 0, v27, vcc
	s_mov_b32 s20, 0x28000
	s_andn2_b32 s1, s1, 63
	v_add_co_u32_e32 v22, vcc, s20, v26
	v_or_b32_e32 v34, s1, v102
	s_nop 0
	v_addc_co_u32_e32 v23, vcc, 0, v27, vcc
	s_mov_b32 s21, 0x30000
	s_sub_i32 s0, s0, s25
	v_ashrrev_i32_e32 v35, 31, v34
	v_add_co_u32_e32 v28, vcc, s21, v26
	s_lshl_b32 s0, s0, 5
	v_lshlrev_b64 v[34:35], 12, v[34:35]
	v_addc_co_u32_e32 v29, vcc, 0, v27, vcc
	s_mov_b32 s24, 0x38000
	v_lshl_add_u64 v[34:35], s[46:47], 0, v[34:35]
	s_ashr_i32 s1, s0, 31
	v_add_co_u32_e32 v30, vcc, s24, v26
	v_lshl_add_u64 v[34:35], s[0:1], 2, v[34:35]
	s_nop 0
	v_addc_co_u32_e32 v31, vcc, 0, v27, vcc
	v_lshl_add_u64 v[58:59], v[34:35], 0, v[98:99]
	v_add_co_u32_e32 v38, vcc, s6, v58
	global_load_dwordx4 v[66:69], v99, s[46:47] offset:16 nt
	global_load_dwordx4 v[70:73], v99, s[46:47] nt
	v_addc_co_u32_e32 v39, vcc, 0, v59, vcc
	v_add_co_u32_e32 v42, vcc, s7, v58
	global_load_dwordx4 v[2:5], v[26:27], off nt
	s_nop 0
	global_load_dwordx4 v[6:9], v[6:7], off nt
	v_addc_co_u32_e32 v43, vcc, 0, v59, vcc
	v_add_co_u32_e32 v46, vcc, s18, v58
	global_load_dwordx4 v[10:13], v[10:11], off nt
	s_nop 0
	global_load_dwordx4 v[14:17], v[14:15], off nt
	v_addc_co_u32_e32 v47, vcc, 0, v59, vcc
	s_waitcnt vmcnt(6)
	v_add_co_u32_e32 v50, vcc, s19, v58
	global_load_dwordx4 v[18:21], v[18:19], off nt
	s_nop 0
	global_load_dwordx4 v[22:25], v[22:23], off nt
	v_addc_co_u32_e32 v51, vcc, 0, v59, vcc
	v_add_co_u32_e32 v54, vcc, s20, v58
	global_load_dwordx4 v[26:29], v[28:29], off nt
	s_nop 0
	global_load_dwordx4 v[30:33], v[30:31], off nt
	v_addc_co_u32_e32 v55, vcc, 0, v59, vcc
	v_add_co_u32_e32 v60, vcc, s21, v58
	global_load_dwordx4 v[34:37], v[58:59], off nt
	s_nop 0
	global_load_dwordx4 v[38:41], v[38:39], off nt
	v_addc_co_u32_e32 v61, vcc, 0, v59, vcc
	v_add_co_u32_e32 v62, vcc, s24, v58
	global_load_dwordx4 v[42:45], v[42:43], off nt
	s_nop 0
	global_load_dwordx4 v[46:49], v[46:47], off nt
	v_addc_co_u32_e32 v63, vcc, 0, v59, vcc
	global_load_dwordx4 v[50:53], v[50:51], off nt
	s_nop 0
	global_load_dwordx4 v[54:57], v[54:55], off nt
	s_nop 0
	global_load_dwordx4 v[58:61], v[60:61], off nt
	s_nop 0
	global_load_dwordx4 v[62:65], v[62:63], off nt
	s_waitcnt vmcnt(8)
	s_waitcnt vmcnt(0)
	v_mul_u32_u24_e32 v69, 0x420, v75
	v_lshlrev_b32_e32 v70, 2, v102
	s_mul_i32 s0, s70, 0x2c000
	v_lshlrev_b32_e32 v74, 2, v75
	s_lshl_b32 s25, s71, 4
	v_add_u32_e32 v67, s3, v98
	v_mul_u32_u24_e32 v68, 0x84, v102
	v_lshlrev_b32_e32 v66, 3, v75
	v_add3_u32 v106, s3, v69, v70
	s_mul_i32 s3, s71, 24
	s_movk_i32 s28, 0x1600
	v_mov_b32_e32 v69, s0
	v_readlane_b32 s78, v252, 14
	v_or_b32_e32 v103, 8, v102
	v_or_b32_e32 v104, 16, v102
	v_or_b32_e32 v105, 24, v102
	v_mad_u32_u24 v107, v102, s28, v69
	s_mul_i32 s29, s71, 0x420000
	s_sub_i32 s30, s3, s25
	s_add_i32 s31, s3, s92
	v_lshlrev_b32_e32 v98, 2, v74
	v_lshlrev_b32_e32 v100, 1, v66
	v_add_u32_e32 v108, v67, v68
	s_mov_b32 s34, s70
	v_readlane_b32 s79, v252, 15
	s_branch .LBB0_247

; #define LAS __attribute__((address_space(3)))
; __device__ __forceinline__ unsigned cvtpk(float lo, float hi) { f32x2_t v = {lo, hi}; bf16x2_t b = __builtin_convertvector(v, bf16x2_t); return __builtin_bit_cast(unsigned, b); }
; #define LDS_WAIT() asm volatile("s_waitcnt lgkmcnt(0)" ::: "memory")
; #define CONV_JOB(it_) conv_job<LIST>((it_) < n ? (it_) : n - 1, P)
; __device__ __forceinline__ void conv_fetch(const ConvJob& j, int lane, ConvSet& s) {
;     const int k0 = 64 * j.kb; int cnt; const int src = vgroup_src(j.kind, j.g, cnt);
;     const int ks = lane >> 3, n4 = (lane & 7) * 4, c = lane & 7; const bool okc = n4 < cnt;
;     const float* gp = j.gain ? j.gain + k0 + 8 * c : j.W;
;     s.g0 = *(const f32x4*)gp; s.g1 = *(const f32x4*)(gp + 4);
;     const float* wp = j.W + (size_t)(k0 + ks) * j.Norig + src + (okc ? n4 : 0);
; #pragma unroll
;     for (int i = 0; i < 8; ++i) s.v[i] = *(const f32x4*)(wp + (size_t)(8 * i) * j.Norig);
; }
; __device__ __forceinline__ void conv_emit(const ConvJob& j, int lane, const ConvSet& s, LAS float* scr) {
;     const int k0 = 64 * j.kb; int cnt; (void)vgroup_src(j.kind, j.g, cnt);
;     const int ks = lane >> 3, n4 = (lane & 7) * 4, c = lane & 7; const bool okc = n4 < cnt;
;     const f32x4 one = (f32x4){1.f, 1.f, 1.f, 1.f}; const f32x4 g0 = j.gain ? s.g0 : one, g1 = j.gain ? s.g1 : one;
; #pragma unroll
;     for (int i = 0; i < 8; ++i) { LAS float* sp = scr + (8 * i + ks) * 33 + n4;
; #pragma unroll
;         for (int e = 0; e < 4; ++e) sp[e] = okc ? s.v[i][e] : 0.f; }
;     LDS_WAIT(); asm volatile("" ::: "memory");
; #pragma unroll
;     for (int q = 0; q < 4; ++q) { const int nn = (lane >> 3) + 8 * q; const LAS float* sr = scr + (8 * c) * 33 + nn;
;         u32x4 o; o.x = cvtpk(sr[0 * 33] * g0[0], sr[1 * 33] * g0[1]); o.y = cvtpk(sr[2 * 33] * g0[2], sr[3 * 33] * g0[3]); o.z = cvtpk(sr[4 * 33] * g1[0], sr[5 * 33] * g1[1]); o.w = cvtpk(sr[6 * 33] * g1[2], sr[7 * 33] * g1[3]);
;         *(u32x4*)(j.WT + (size_t)(j.g * 32 + nn) * j.K + k0 + 8 * c) = o; }
;     LDS_WAIT(); asm volatile("" ::: "memory");
; }
; template <int LIST> __device__ __forceinline__ void convert_list(int first, int stride, const Params& P, LAS float* scr, int lane) {
;     ...
;     for (int it = first; it < n; it += 3 * stride) {
;         conv_fetch(CONV_JOB(it + 2 * stride), lane, C); conv_emit(CONV_JOB(it), lane, A, scr);
.LBB0_247:
	s_add_i32 s33, s25, s34
	s_cmpk_lt_i32 s33, 0x580
	s_cselect_b64 s[0:1], -1, 0
	s_and_b64 s[72:73], s[0:1], exec
	s_cselect_b32 s35, s33, 0x57f
	s_ashr_i32 s72, s35, 31
	s_lshr_b32 s72, s72, 27
	s_add_i32 s72, s35, s72
	s_and_b32 s73, s72, 0x7ffffe0
	s_lshl_b32 s72, s72, 1
	s_sub_i32 s35, s35, s73
	s_and_b32 s73, s72, 0xffffffc0
	s_waitcnt vmcnt(27)
	v_or_b32_e32 v66, s73, v102
	v_ashrrev_i32_e32 v67, 31, v66
	s_lshl_b32 s72, s35, 5
	v_lshlrev_b64 v[66:67], 12, v[66:67]
	v_lshl_add_u64 v[66:67], s[46:47], 0, v[66:67]
	s_ashr_i32 s73, s72, 31
	v_lshl_add_u64 v[66:67], s[72:73], 2, v[66:67]
	s_waitcnt vmcnt(20)
	v_lshl_add_u64 v[90:91], v[66:67], 0, v[98:99]
	v_add_co_u32_e32 v70, vcc, s6, v90
	s_ashr_i32 s35, s34, 31
	s_nop 0
	v_addc_co_u32_e32 v71, vcc, 0, v91, vcc
	v_add_co_u32_e32 v74, vcc, s7, v90
	global_load_dwordx4 v[66:69], v[90:91], off nt
	s_nop 0
	global_load_dwordx4 v[70:73], v[70:71], off nt
	v_addc_co_u32_e32 v75, vcc, 0, v91, vcc
	v_add_co_u32_e32 v78, vcc, s18, v90
	v_add_u32_e32 v109, 0x420, v108
	s_nop 0
	v_addc_co_u32_e32 v79, vcc, 0, v91, vcc
	v_add_co_u32_e32 v82, vcc, s19, v90
	v_add_u32_e32 v110, 0x428, v108
	s_nop 0
	v_addc_co_u32_e32 v83, vcc, 0, v91, vcc
	v_add_co_u32_e32 v86, vcc, s20, v90
	v_add_u32_e32 v111, 0x840, v108
	s_nop 0
	v_addc_co_u32_e32 v87, vcc, 0, v91, vcc
	v_add_co_u32_e32 v92, vcc, s21, v90
	v_add_u32_e32 v112, 0x848, v108
	s_nop 0
	v_addc_co_u32_e32 v93, vcc, 0, v91, vcc
	v_add_co_u32_e32 v90, vcc, s24, v90
	v_add_u32_e32 v113, 0xc60, v108
	s_nop 0
	v_addc_co_u32_e32 v91, vcc, 0, v91, vcc
	v_add_u32_e32 v114, 0xc68, v108
	v_add_u32_e32 v115, 0x1080, v108
	v_add_u32_e32 v116, 0x1088, v108
	v_add_u32_e32 v117, 0x14a0, v108
	v_add_u32_e32 v118, 0x14a8, v108
	v_add_u32_e32 v119, 0x18c0, v108
	v_add_u32_e32 v120, 0x18c8, v108
	v_add_u32_e32 v121, 0x1ce0, v108
	v_add_u32_e32 v122, 0x1ce8, v108
	global_load_dwordx4 v[74:77], v[74:75], off nt
	s_nop 0
	global_load_dwordx4 v[78:81], v[78:79], off nt
	s_nop 0
	global_load_dwordx4 v[82:85], v[82:83], off nt
	s_nop 0
	global_load_dwordx4 v[86:89], v[86:87], off nt
	s_nop 0
	global_load_dwordx4 v[94:97], v[92:93], off nt
	s_nop 0
	global_load_dwordx4 v[90:93], v[90:91], off nt
	s_lshr_b32 s35, s35, 27
	s_waitcnt vmcnt(23)
	ds_write2_b32 v108, v2, v3 offset1:1
	ds_write2_b32 v108, v4, v5 offset0:2 offset1:3
	s_waitcnt vmcnt(22)
	ds_write2_b32 v109, v6, v7 offset1:1
	ds_write2_b32 v110, v8, v9 offset1:1
	s_waitcnt vmcnt(21)
	ds_write2_b32 v111, v10, v11 offset1:1
	ds_write2_b32 v112, v12, v13 offset1:1
	s_waitcnt vmcnt(20)
	ds_write2_b32 v113, v14, v15 offset1:1
	ds_write2_b32 v114, v16, v17 offset1:1
	s_waitcnt vmcnt(19)
	ds_write2_b32 v115, v18, v19 offset1:1
	ds_write2_b32 v116, v20, v21 offset1:1
	s_waitcnt vmcnt(18)
	ds_write2_b32 v117, v22, v23 offset1:1
	ds_write2_b32 v118, v24, v25 offset1:1
	s_waitcnt vmcnt(17)
	ds_write2_b32 v119, v26, v27 offset1:1
	ds_write2_b32 v120, v28, v29 offset1:1
	s_waitcnt vmcnt(16)
	ds_write2_b32 v121, v30, v31 offset1:1
	ds_write2_b32 v122, v32, v33 offset1:1
	s_add_i32 s35, s34, s35
	s_waitcnt lgkmcnt(0)
	s_ashr_i32 s35, s35, 5
	s_lshl_b32 s72, s35, 6
	ds_read2_b32 v[6:7], v106 offset0:33 offset1:41
	ds_read2_b32 v[8:9], v106 offset1:8
	ds_read2_b32 v[10:11], v106 offset0:66 offset1:74
	ds_read2_b32 v[12:13], v106 offset0:99 offset1:107
	ds_read2_b32 v[14:15], v106 offset0:132 offset1:140
	ds_read2_b32 v[16:17], v106 offset0:165 offset1:173
	ds_read2_b32 v[18:19], v106 offset0:198 offset1:206
	ds_read2_b32 v[20:21], v106 offset0:231 offset1:239
	s_mul_i32 s35, s35, 0xffa80000
	v_add_u32_e32 v22, s35, v107
	s_ashr_i32 s73, s72, 31
	v_ashrrev_i32_e32 v23, 31, v22
	v_lshl_add_u64 v[24:25], s[78:79], 0, v[22:23]
	s_lshl_b64 s[72:73], s[72:73], 1
	v_lshl_add_u64 v[24:25], v[24:25], 0, s[72:73]
	v_mov_b32_e32 v101, v99
	s_waitcnt lgkmcnt(6)
	v_cvt_pk_bf16_f32 v2, v8, v6
	s_waitcnt lgkmcnt(4)
	v_cvt_pk_bf16_f32 v3, v10, v12
	s_waitcnt lgkmcnt(2)
	v_cvt_pk_bf16_f32 v4, v14, v16
	s_waitcnt lgkmcnt(0)
	v_cvt_pk_bf16_f32 v5, v18, v20
	v_lshl_add_u64 v[24:25], v[24:25], 0, v[100:101]
	v_add_u32_e32 v6, 0xb000, v22
	global_store_dwordx4 v[24:25], v[2:5], off
	s_add_i32 s35, s34, s3
	s_nop 0
	v_cvt_pk_bf16_f32 v2, v9, v7
	v_ashrrev_i32_e32 v7, 31, v6
	v_lshl_add_u64 v[6:7], s[78:79], 0, v[6:7]
	v_lshl_add_u64 v[6:7], v[6:7], 0, s[72:73]
	v_cvt_pk_bf16_f32 v3, v11, v13
	v_cvt_pk_bf16_f32 v4, v15, v17
	v_cvt_pk_bf16_f32 v5, v19, v21
	v_lshl_add_u64 v[6:7], v[6:7], 0, v[100:101]
	ds_read2_b32 v[8:9], v106 offset0:49 offset1:57
	ds_read2_b32 v[10:11], v106 offset0:16 offset1:24
	ds_read2_b32 v[12:13], v106 offset0:82 offset1:90
	ds_read2_b32 v[14:15], v106 offset0:115 offset1:123
	ds_read2_b32 v[16:17], v106 offset0:148 offset1:156
	ds_read2_b32 v[18:19], v106 offset0:181 offset1:189
	ds_read2_b32 v[20:21], v106 offset0:214 offset1:222
	ds_read2_b32 v[24:25], v106 offset0:247 offset1:255
	global_store_dwordx4 v[6:7], v[2:5], off
	v_add_u32_e32 v6, 0x16000, v22
	v_ashrrev_i32_e32 v7, 31, v6
	v_lshl_add_u64 v[6:7], s[78:79], 0, v[6:7]
	v_lshl_add_u64 v[6:7], v[6:7], 0, s[72:73]
	s_waitcnt lgkmcnt(6)
	v_cvt_pk_bf16_f32 v2, v10, v8
	s_waitcnt lgkmcnt(4)
	v_cvt_pk_bf16_f32 v3, v12, v14
	s_waitcnt lgkmcnt(2)
	v_cvt_pk_bf16_f32 v4, v16, v18
	s_waitcnt lgkmcnt(0)
; #define LAS __attribute__((address_space(3)))
; __device__ __forceinline__ unsigned cvtpk(float lo, float hi) { f32x2_t v = {lo, hi}; bf16x2_t b = __builtin_convertvector(v, bf16x2_t); return __builtin_bit_cast(unsigned, b); }
; #define LDS_WAIT() asm volatile("s_waitcnt lgkmcnt(0)" ::: "memory")
; #define CONV_JOB(it_) conv_job<LIST>((it_) < n ? (it_) : n - 1, P)
; __device__ __forceinline__ void conv_emit(const ConvJob& j, int lane, const ConvSet& s, LAS float* scr) {
;     const int k0 = 64 * j.kb; int cnt; (void)vgroup_src(j.kind, j.g, cnt);
;     const int ks = lane >> 3, n4 = (lane & 7) * 4, c = lane & 7; const bool okc = n4 < cnt;
;     const f32x4 one = (f32x4){1.f, 1.f, 1.f, 1.f}; const f32x4 g0 = j.gain ? s.g0 : one, g1 = j.gain ? s.g1 : one;
; #pragma unroll
;     for (int i = 0; i < 8; ++i) { LAS float* sp = scr + (8 * i + ks) * 33 + n4;
; #pragma unroll
;         for (int e = 0; e < 4; ++e) sp[e] = okc ? s.v[i][e] : 0.f; }
;     LDS_WAIT(); asm volatile("" ::: "memory");
; #pragma unroll
;     for (int q = 0; q < 4; ++q) { const int nn = (lane >> 3) + 8 * q; const LAS float* sr = scr + (8 * c) * 33 + nn;
;         u32x4 o; o.x = cvtpk(sr[0 * 33] * g0[0], sr[1 * 33] * g0[1]); o.y = cvtpk(sr[2 * 33] * g0[2], sr[3 * 33] * g0[3]); o.z = cvtpk(sr[4 * 33] * g1[0], sr[5 * 33] * g1[1]); o.w = cvtpk(sr[6 * 33] * g1[2], sr[7 * 33] * g1[3]);
;         *(u32x4*)(j.WT + (size_t)(j.g * 32 + nn) * j.K + k0 + 8 * c) = o; }
;     LDS_WAIT(); asm volatile("" ::: "memory");
; }
; template <int LIST> __device__ __forceinline__ void convert_list(int first, int stride, const Params& P, LAS float* scr, int lane) {
;     ...
;         conv_fetch(CONV_JOB(it + 3 * stride), lane, A); if (it + stride < n) conv_emit(CONV_JOB(it + stride), lane, B, scr);
;         conv_fetch(CONV_JOB(it + 4 * stride), lane, B); if (it + 2 * stride < n) conv_emit(CONV_JOB(it + 2 * stride), lane, C, scr);
	v_cvt_pk_bf16_f32 v5, v20, v24
	v_lshl_add_u64 v[6:7], v[6:7], 0, v[100:101]
	global_store_dwordx4 v[6:7], v[2:5], off
	v_add_u32_e32 v6, 0x21000, v22
	v_ashrrev_i32_e32 v7, 31, v6
	v_lshl_add_u64 v[6:7], s[78:79], 0, v[6:7]
	v_lshl_add_u64 v[6:7], v[6:7], 0, s[72:73]
	s_min_i32 s72, s35, 0x57f
	s_ashr_i32 s73, s72, 31
	s_lshr_b32 s73, s73, 27
	s_add_i32 s73, s72, s73
	s_and_b32 s74, s73, 0x7ffffe0
	s_lshl_b32 s73, s73, 1
	v_cvt_pk_bf16_f32 v2, v11, v9
	v_cvt_pk_bf16_f32 v3, v13, v15
	v_cvt_pk_bf16_f32 v4, v17, v19
	v_cvt_pk_bf16_f32 v5, v21, v25
	v_lshl_add_u64 v[6:7], v[6:7], 0, v[100:101]
	s_andn2_b32 s73, s73, 63
	global_store_dwordx4 v[6:7], v[2:5], off
	s_sub_i32 s72, s72, s74
	s_lshl_b32 s72, s72, 5
	v_or_b32_e32 v2, s73, v102
	v_ashrrev_i32_e32 v3, 31, v2
	v_lshlrev_b64 v[2:3], 12, v[2:3]
	v_lshl_add_u64 v[2:3], s[46:47], 0, v[2:3]
	s_ashr_i32 s73, s72, 31
	v_lshl_add_u64 v[2:3], s[72:73], 2, v[2:3]
	v_lshl_add_u64 v[26:27], v[2:3], 0, v[98:99]
	v_add_co_u32_e32 v6, vcc, s6, v26
	s_waitcnt lgkmcnt(0)
	s_add_i32 s72, s30, s34
	s_nop 0
	v_addc_co_u32_e32 v7, vcc, 0, v27, vcc
	v_add_co_u32_e32 v10, vcc, s7, v26
	global_load_dwordx4 v[2:5], v[26:27], off nt
	s_nop 0
	global_load_dwordx4 v[6:9], v[6:7], off nt
	v_addc_co_u32_e32 v11, vcc, 0, v27, vcc
	v_add_co_u32_e32 v14, vcc, s18, v26
	s_cmpk_gt_i32 s72, 0x57f
	s_nop 0
	v_addc_co_u32_e32 v15, vcc, 0, v27, vcc
	v_add_co_u32_e32 v18, vcc, s19, v26
	global_load_dwordx4 v[10:13], v[10:11], off nt
	s_nop 0
	global_load_dwordx4 v[14:17], v[14:15], off nt
	v_addc_co_u32_e32 v19, vcc, 0, v27, vcc
	v_add_co_u32_e32 v22, vcc, 0x28000, v26
	s_nop 1
	v_addc_co_u32_e32 v23, vcc, 0, v27, vcc
	v_add_co_u32_e32 v28, vcc, 0x30000, v26
	global_load_dwordx4 v[18:21], v[18:19], off nt
	s_nop 0
	global_load_dwordx4 v[22:25], v[22:23], off nt
	v_addc_co_u32_e32 v29, vcc, 0, v27, vcc
	v_add_co_u32_e32 v30, vcc, 0x38000, v26
	s_nop 1
	v_addc_co_u32_e32 v31, vcc, 0, v27, vcc
	global_load_dwordx4 v[26:29], v[28:29], off nt
	s_nop 0
	global_load_dwordx4 v[30:33], v[30:31], off nt
	s_cbranch_scc1 .LBB0_249
	s_ashr_i32 s73, s72, 31
	s_lshr_b32 s73, s73, 27
	s_add_i32 s73, s72, s73
	s_waitcnt vmcnt(27)
	ds_write2_b32 v108, v34, v35 offset1:1
	ds_write2_b32 v108, v36, v37 offset0:2 offset1:3
	s_waitcnt vmcnt(26)
	ds_write2_b32 v109, v38, v39 offset1:1
	ds_write2_b32 v110, v40, v41 offset1:1
	s_waitcnt vmcnt(25)
	ds_write2_b32 v111, v42, v43 offset1:1
	ds_write2_b32 v112, v44, v45 offset1:1
	s_waitcnt vmcnt(24)
	ds_write2_b32 v113, v46, v47 offset1:1
	ds_write2_b32 v114, v48, v49 offset1:1
	s_waitcnt vmcnt(23)
	ds_write2_b32 v115, v50, v51 offset1:1
	ds_write2_b32 v116, v52, v53 offset1:1
	s_waitcnt vmcnt(22)
	ds_write2_b32 v117, v54, v55 offset1:1
	ds_write2_b32 v118, v56, v57 offset1:1
	s_waitcnt vmcnt(21)
	ds_write2_b32 v119, v58, v59 offset1:1
	ds_write2_b32 v120, v60, v61 offset1:1
	s_waitcnt vmcnt(20)
	ds_write2_b32 v121, v62, v63 offset1:1
	ds_write2_b32 v122, v64, v65 offset1:1
	s_and_b32 s74, s73, 0x7ffffe0
	s_waitcnt lgkmcnt(0)
	s_sub_i32 s74, s72, s74
	ds_read2_b32 v[38:39], v106 offset0:33 offset1:41
	ds_read2_b32 v[40:41], v106 offset1:8
	ds_read2_b32 v[42:43], v106 offset0:66 offset1:74
	ds_read2_b32 v[44:45], v106 offset0:99 offset1:107
	ds_read2_b32 v[46:47], v106 offset0:132 offset1:140
	ds_read2_b32 v[48:49], v106 offset0:165 offset1:173
	ds_read2_b32 v[50:51], v106 offset0:198 offset1:206
	ds_read2_b32 v[52:53], v106 offset0:231 offset1:239
	s_lshl_b32 s74, s74, 5
	s_lshl_b32 s72, s73, 1
	s_waitcnt lgkmcnt(6)
	v_cvt_pk_bf16_f32 v34, v40, v38
	v_or_b32_e32 v38, s74, v102
	s_andn2_b32 s72, s72, 63
	v_mul_lo_u32 v54, v38, s28
	s_ashr_i32 s73, s72, 31
	v_ashrrev_i32_e32 v55, 31, v54
	v_lshl_add_u64 v[54:55], s[78:79], 0, v[54:55]
	s_lshl_b64 s[72:73], s[72:73], 1
	v_lshl_add_u64 v[54:55], v[54:55], 0, s[72:73]
	v_or_b32_e32 v38, s74, v103
	s_waitcnt lgkmcnt(4)
	v_cvt_pk_bf16_f32 v35, v42, v44
	s_waitcnt lgkmcnt(2)
	v_cvt_pk_bf16_f32 v36, v46, v48
	s_waitcnt lgkmcnt(0)
	v_cvt_pk_bf16_f32 v37, v50, v52
	v_lshl_add_u64 v[54:55], v[54:55], 0, v[100:101]
	v_mul_lo_u32 v38, v38, s28
	global_store_dwordx4 v[54:55], v[34:37], off
	s_nop 1
	v_cvt_pk_bf16_f32 v34, v41, v39
	v_ashrrev_i32_e32 v39, 31, v38
	v_lshl_add_u64 v[38:39], s[78:79], 0, v[38:39]
	v_lshl_add_u64 v[38:39], v[38:39], 0, s[72:73]
	v_cvt_pk_bf16_f32 v35, v43, v45
	v_cvt_pk_bf16_f32 v36, v47, v49
	v_cvt_pk_bf16_f32 v37, v51, v53
	v_lshl_add_u64 v[38:39], v[38:39], 0, v[100:101]
	ds_read2_b32 v[40:41], v106 offset0:49 offset1:57
	ds_read2_b32 v[42:43], v106 offset0:16 offset1:24
	ds_read2_b32 v[44:45], v106 offset0:82 offset1:90
	ds_read2_b32 v[46:47], v106 offset0:115 offset1:123
	ds_read2_b32 v[48:49], v106 offset0:148 offset1:156
	ds_read2_b32 v[50:51], v106 offset0:181 offset1:189
	ds_read2_b32 v[52:53], v106 offset0:214 offset1:222
	ds_read2_b32 v[54:55], v106 offset0:247 offset1:255
	global_store_dwordx4 v[38:39], v[34:37], off
	v_or_b32_e32 v38, s74, v104
	v_mul_lo_u32 v38, v38, s28
	v_ashrrev_i32_e32 v39, 31, v38
	v_lshl_add_u64 v[38:39], s[78:79], 0, v[38:39]
	v_lshl_add_u64 v[38:39], v[38:39], 0, s[72:73]
	s_waitcnt lgkmcnt(6)
	v_cvt_pk_bf16_f32 v34, v42, v40
	s_waitcnt lgkmcnt(4)
	v_cvt_pk_bf16_f32 v35, v44, v46
	s_waitcnt lgkmcnt(2)
	v_cvt_pk_bf16_f32 v36, v48, v50
	s_waitcnt lgkmcnt(0)
	v_cvt_pk_bf16_f32 v37, v52, v54
	v_lshl_add_u64 v[38:39], v[38:39], 0, v[100:101]
	global_store_dwordx4 v[38:39], v[34:37], off
	v_or_b32_e32 v38, s74, v105
	v_mul_lo_u32 v38, v38, s28
	v_ashrrev_i32_e32 v39, 31, v38
	v_lshl_add_u64 v[38:39], s[78:79], 0, v[38:39]
	v_lshl_add_u64 v[38:39], v[38:39], 0, s[72:73]
	v_cvt_pk_bf16_f32 v34, v43, v41
	v_cvt_pk_bf16_f32 v35, v45, v47
	v_cvt_pk_bf16_f32 v36, v49, v51
	v_cvt_pk_bf16_f32 v37, v53, v55
	v_lshl_add_u64 v[38:39], v[38:39], 0, v[100:101]
	global_store_dwordx4 v[38:39], v[34:37], off
	s_waitcnt lgkmcnt(0)
; #define LAS __attribute__((address_space(3)))
; __device__ __forceinline__ unsigned cvtpk(float lo, float hi) { f32x2_t v = {lo, hi}; bf16x2_t b = __builtin_convertvector(v, bf16x2_t); return __builtin_bit_cast(unsigned, b); }
; #define LDS_WAIT() asm volatile("s_waitcnt lgkmcnt(0)" ::: "memory")
; #define CONV_JOB(it_) conv_job<LIST>((it_) < n ? (it_) : n - 1, P)
; __device__ __forceinline__ void conv_fetch(const ConvJob& j, int lane, ConvSet& s) {
;     const int k0 = 64 * j.kb; int cnt; const int src = vgroup_src(j.kind, j.g, cnt);
;     const int ks = lane >> 3, n4 = (lane & 7) * 4, c = lane & 7; const bool okc = n4 < cnt;
;     const float* gp = j.gain ? j.gain + k0 + 8 * c : j.W;
;     s.g0 = *(const f32x4*)gp; s.g1 = *(const f32x4*)(gp + 4);
;     const float* wp = j.W + (size_t)(k0 + ks) * j.Norig + src + (okc ? n4 : 0);
; #pragma unroll
;     for (int i = 0; i < 8; ++i) s.v[i] = *(const f32x4*)(wp + (size_t)(8 * i) * j.Norig);
; }
; __device__ __forceinline__ void conv_emit(const ConvJob& j, int lane, const ConvSet& s, LAS float* scr) {
;     const int k0 = 64 * j.kb; int cnt; (void)vgroup_src(j.kind, j.g, cnt);
;     const int ks = lane >> 3, n4 = (lane & 7) * 4, c = lane & 7; const bool okc = n4 < cnt;
;     const f32x4 one = (f32x4){1.f, 1.f, 1.f, 1.f}; const f32x4 g0 = j.gain ? s.g0 : one, g1 = j.gain ? s.g1 : one;
; #pragma unroll
;     for (int i = 0; i < 8; ++i) { LAS float* sp = scr + (8 * i + ks) * 33 + n4;
; #pragma unroll
;         for (int e = 0; e < 4; ++e) sp[e] = okc ? s.v[i][e] : 0.f; }
;     LDS_WAIT(); asm volatile("" ::: "memory");
; #pragma unroll
;     for (int q = 0; q < 4; ++q) { const int nn = (lane >> 3) + 8 * q; const LAS float* sr = scr + (8 * c) * 33 + nn;
;         u32x4 o; o.x = cvtpk(sr[0 * 33] * g0[0], sr[1 * 33] * g0[1]); o.y = cvtpk(sr[2 * 33] * g0[2], sr[3 * 33] * g0[3]); o.z = cvtpk(sr[4 * 33] * g1[0], sr[5 * 33] * g1[1]); o.w = cvtpk(sr[6 * 33] * g1[2], sr[7 * 33] * g1[3]);
;         *(u32x4*)(j.WT + (size_t)(j.g * 32 + nn) * j.K + k0 + 8 * c) = o; }
;     LDS_WAIT(); asm volatile("" ::: "memory");
; }
; template <int LIST> __device__ __forceinline__ void convert_list(int first, int stride, const Params& P, LAS float* scr, int lane) {
;     ...
;         conv_fetch(CONV_JOB(it + 4 * stride), lane, B); if (it + 2 * stride < n) conv_emit(CONV_JOB(it + 2 * stride), lane, C, scr);
.LBB0_249:
	s_add_i32 s34, s31, s34
	s_min_i32 s34, s34, 0x57f
	s_ashr_i32 s72, s34, 31
	s_lshr_b32 s72, s72, 27
	s_add_i32 s72, s34, s72
	s_and_b32 s73, s72, 0x7ffffe0
	s_lshl_b32 s72, s72, 1
	s_sub_i32 s34, s34, s73
	s_and_b32 s73, s72, 0xffffffc0
	s_waitcnt vmcnt(27)
	v_or_b32_e32 v34, s73, v102
	v_ashrrev_i32_e32 v35, 31, v34
	s_lshl_b32 s72, s34, 5
	v_lshlrev_b64 v[34:35], 12, v[34:35]
	v_lshl_add_u64 v[34:35], s[46:47], 0, v[34:35]
	s_ashr_i32 s73, s72, 31
	v_lshl_add_u64 v[34:35], s[72:73], 2, v[34:35]
	s_waitcnt vmcnt(21)
	v_lshl_add_u64 v[58:59], v[34:35], 0, v[98:99]
	v_add_co_u32_e32 v38, vcc, s6, v58
	s_nop 1
	v_addc_co_u32_e32 v39, vcc, 0, v59, vcc
	v_add_co_u32_e32 v42, vcc, s7, v58
	global_load_dwordx4 v[34:37], v[58:59], off nt
	s_nop 0
	global_load_dwordx4 v[38:41], v[38:39], off nt
	v_addc_co_u32_e32 v43, vcc, 0, v59, vcc
	v_add_co_u32_e32 v46, vcc, s18, v58
	s_nop 1
	v_addc_co_u32_e32 v47, vcc, 0, v59, vcc
	v_add_co_u32_e32 v50, vcc, s19, v58
	global_load_dwordx4 v[42:45], v[42:43], off nt
	s_nop 0
	global_load_dwordx4 v[46:49], v[46:47], off nt
	v_addc_co_u32_e32 v51, vcc, 0, v59, vcc
	v_add_co_u32_e32 v54, vcc, 0x28000, v58
	s_nop 1
	v_addc_co_u32_e32 v55, vcc, 0, v59, vcc
	v_add_co_u32_e32 v60, vcc, 0x30000, v58
	global_load_dwordx4 v[50:53], v[50:51], off nt
	s_nop 0
	global_load_dwordx4 v[54:57], v[54:55], off nt
	v_addc_co_u32_e32 v61, vcc, 0, v59, vcc
	s_waitcnt vmcnt(26)
	v_add_co_u32_e32 v62, vcc, 0x38000, v58
	s_nop 1
	v_addc_co_u32_e32 v63, vcc, 0, v59, vcc
	global_load_dwordx4 v[58:61], v[60:61], off nt
	s_nop 0
	global_load_dwordx4 v[62:65], v[62:63], off nt
	s_andn2_b64 vcc, exec, s[0:1]
	s_cbranch_vccnz .LBB0_246
	s_ashr_i32 s0, s33, 31
	s_lshr_b32 s0, s0, 27
	s_add_i32 s0, s33, s0
	s_waitcnt vmcnt(27)
	ds_write2_b32 v108, v66, v67 offset1:1
	ds_write2_b32 v108, v68, v69 offset0:2 offset1:3
	s_waitcnt vmcnt(26)
	ds_write2_b32 v109, v70, v71 offset1:1
	ds_write2_b32 v110, v72, v73 offset1:1
	s_waitcnt vmcnt(25)
	ds_write2_b32 v111, v74, v75 offset1:1
	ds_write2_b32 v112, v76, v77 offset1:1
	s_waitcnt vmcnt(24)
	ds_write2_b32 v113, v78, v79 offset1:1
	ds_write2_b32 v114, v80, v81 offset1:1
	s_waitcnt vmcnt(23)
	ds_write2_b32 v115, v82, v83 offset1:1
	ds_write2_b32 v116, v84, v85 offset1:1
	s_waitcnt vmcnt(22)
	ds_write2_b32 v117, v86, v87 offset1:1
	ds_write2_b32 v118, v88, v89 offset1:1
	s_waitcnt vmcnt(21)
	ds_write2_b32 v119, v94, v95 offset1:1
	ds_write2_b32 v120, v96, v97 offset1:1
	s_waitcnt vmcnt(20)
	ds_write2_b32 v121, v90, v91 offset1:1
	ds_write2_b32 v122, v92, v93 offset1:1
	s_and_b32 s1, s0, 0x7ffffe0
	s_waitcnt lgkmcnt(0)
	s_sub_i32 s33, s33, s1
	ds_read2_b32 v[70:71], v106 offset0:33 offset1:41
	ds_read2_b32 v[72:73], v106 offset1:8
	ds_read2_b32 v[74:75], v106 offset0:66 offset1:74
	ds_read2_b32 v[76:77], v106 offset0:99 offset1:107
	ds_read2_b32 v[78:79], v106 offset0:132 offset1:140
	ds_read2_b32 v[80:81], v106 offset0:165 offset1:173
	ds_read2_b32 v[82:83], v106 offset0:198 offset1:206
	ds_read2_b32 v[84:85], v106 offset0:231 offset1:239
	s_lshl_b32 s33, s33, 5
	s_lshl_b32 s0, s0, 1
	s_waitcnt lgkmcnt(6)
	v_cvt_pk_bf16_f32 v66, v72, v70
	v_or_b32_e32 v70, s33, v102
	s_andn2_b32 s0, s0, 63
	v_mul_lo_u32 v86, v70, s28
	s_ashr_i32 s1, s0, 31
	v_ashrrev_i32_e32 v87, 31, v86
	v_lshl_add_u64 v[86:87], s[78:79], 0, v[86:87]
	s_lshl_b64 s[0:1], s[0:1], 1
	v_lshl_add_u64 v[86:87], v[86:87], 0, s[0:1]
	v_mov_b32_e32 v101, v99
	v_or_b32_e32 v70, s33, v103
	s_waitcnt lgkmcnt(4)
	v_cvt_pk_bf16_f32 v67, v74, v76
	s_waitcnt lgkmcnt(2)
	v_cvt_pk_bf16_f32 v68, v78, v80
	s_waitcnt lgkmcnt(0)
	v_cvt_pk_bf16_f32 v69, v82, v84
	v_lshl_add_u64 v[86:87], v[86:87], 0, v[100:101]
	v_mul_lo_u32 v70, v70, s28
	global_store_dwordx4 v[86:87], v[66:69], off
	s_nop 1
	v_cvt_pk_bf16_f32 v66, v73, v71
	v_ashrrev_i32_e32 v71, 31, v70
	v_lshl_add_u64 v[70:71], s[78:79], 0, v[70:71]
	v_lshl_add_u64 v[70:71], v[70:71], 0, s[0:1]
	v_cvt_pk_bf16_f32 v67, v75, v77
	v_cvt_pk_bf16_f32 v68, v79, v81
	v_cvt_pk_bf16_f32 v69, v83, v85
	v_lshl_add_u64 v[70:71], v[70:71], 0, v[100:101]
	ds_read2_b32 v[72:73], v106 offset0:49 offset1:57
	ds_read2_b32 v[74:75], v106 offset0:16 offset1:24
	ds_read2_b32 v[76:77], v106 offset0:82 offset1:90
	ds_read2_b32 v[78:79], v106 offset0:115 offset1:123
	ds_read2_b32 v[80:81], v106 offset0:148 offset1:156
	ds_read2_b32 v[82:83], v106 offset0:181 offset1:189
	ds_read2_b32 v[84:85], v106 offset0:214 offset1:222
	ds_read2_b32 v[86:87], v106 offset0:247 offset1:255
	global_store_dwordx4 v[70:71], v[66:69], off
	v_or_b32_e32 v70, s33, v104
	v_mul_lo_u32 v70, v70, s28
	v_ashrrev_i32_e32 v71, 31, v70
	v_lshl_add_u64 v[70:71], s[78:79], 0, v[70:71]
	v_lshl_add_u64 v[70:71], v[70:71], 0, s[0:1]
	s_waitcnt lgkmcnt(6)
	v_cvt_pk_bf16_f32 v66, v74, v72
	s_waitcnt lgkmcnt(4)
	v_cvt_pk_bf16_f32 v67, v76, v78
	s_waitcnt lgkmcnt(2)
	v_cvt_pk_bf16_f32 v68, v80, v82
	s_waitcnt lgkmcnt(0)
	v_cvt_pk_bf16_f32 v69, v84, v86
	v_lshl_add_u64 v[70:71], v[70:71], 0, v[100:101]
	global_store_dwordx4 v[70:71], v[66:69], off
	v_or_b32_e32 v70, s33, v105
	v_mul_lo_u32 v70, v70, s28
	v_ashrrev_i32_e32 v71, 31, v70
	v_lshl_add_u64 v[70:71], s[78:79], 0, v[70:71]
	v_lshl_add_u64 v[70:71], v[70:71], 0, s[0:1]
	v_cvt_pk_bf16_f32 v66, v75, v73
	v_cvt_pk_bf16_f32 v67, v77, v79
	v_cvt_pk_bf16_f32 v68, v81, v83
	v_cvt_pk_bf16_f32 v69, v85, v87
	v_lshl_add_u64 v[70:71], v[70:71], 0, v[100:101]
	global_store_dwordx4 v[70:71], v[66:69], off
	s_waitcnt lgkmcnt(0)
	s_branch .LBB0_246
; __device__ __forceinline__ float wave_sum(float v) {
; #pragma unroll
;     for (int o = 1; o < 64; o <<= 1) v += __shfl_xor(v, o);
;     return v;
; __global__ void __launch_bounds__(NTHREADS, 2) fwd_kernel(Params P) {
;     ...
;             f32x4 v[2][4], vn[2][4];
;             auto xrow = [&](int m) -> const f32x4* { const float* xr = (m < MP) ? P.in[0] + (size_t)m * D : P.in[1] + (size_t)(m - MP) * D; return (const f32x4*)xr + lane; };
;             int m0 = 2 * gw;
;             if (m0 < M) {
; #pragma unroll
;                 for (int q = 0; q < 2; ++q) { const f32x4* xv = xrow(m0 + q);
; #pragma unroll
;                     for (int j = 0; j < 4; ++j) v[q][j] = xv[64 * j]; }
;             }
.LBB0_251:
	v_readlane_b32 s78, v252, 14
	s_cmpk_gt_i32 s70, 0x207f
	v_readlane_b32 s79, v252, 15
	s_cbranch_scc1 .LBB0_262
	s_lshl_b32 s6, s70, 1
	s_add_i32 s0, s6, 0xffffc000
	s_ashr_i32 s7, s6, 31
	s_cmpk_lt_i32 s70, 0x2000
	s_cselect_b32 s1, s7, 0
	s_cselect_b32 s0, s6, s0
	s_cselect_b32 s3, s9, s11
	s_cselect_b32 s18, s8, s10
	s_lshl_b64 s[0:1], s[0:1], 12
	s_add_u32 s0, s18, s0
	s_addc_u32 s1, s3, s1
	s_waitcnt vmcnt(6)
	v_lshlrev_b32_e32 v30, 4, v198
	global_load_dwordx4 v[2:5], v30, s[0:1] nt
	global_load_dwordx4 v[6:9], v30, s[0:1] offset:1024 nt
	global_load_dwordx4 v[10:13], v30, s[0:1] offset:2048 nt
	global_load_dwordx4 v[14:17], v30, s[0:1] offset:3072 nt
	s_or_b32 s0, s6, 1
	s_add_i32 s3, s6, 0xffffc001
	s_ashr_i32 s1, s0, 31
	s_cmpk_lt_i32 s0, 0x4000
	s_cselect_b32 s1, s1, 0
	s_cselect_b32 s0, s0, s3
	s_cselect_b32 s3, s9, s11
	s_cselect_b32 s18, s8, s10
	s_lshl_b64 s[0:1], s[0:1], 12
	s_add_u32 s0, s18, s0
	s_addc_u32 s1, s3, s1
	global_load_dwordx4 v[18:21], v30, s[0:1] nt
	global_load_dwordx4 v[22:25], v30, s[0:1] offset:1024 nt
	global_load_dwordx4 v[26:29], v30, s[0:1] offset:2048 nt
	s_nop 0
	global_load_dwordx4 v[30:33], v30, s[0:1] offset:3072 nt
	s_waitcnt vmcnt(13)
	v_mbcnt_lo_u32_b32 v34, -1, 0
	v_mbcnt_hi_u32_b32 v34, -1, v34
	v_and_b32_e32 v35, 64, v34
	v_add_u32_e32 v35, 64, v35
	v_xor_b32_e32 v36, 1, v34
	v_cmp_lt_i32_e32 vcc, v36, v35
	s_lshl_b32 s18, s71, 4
	s_lshl_b64 s[20:21], s[6:7], 6
	v_cndmask_b32_e32 v36, v34, v36, vcc
	s_waitcnt vmcnt(10)
	v_lshlrev_b32_e32 v70, 2, v36
	v_xor_b32_e32 v36, 2, v34
	v_cmp_lt_i32_e32 vcc, v36, v35
	s_lshl_b64 s[24:25], s[6:7], 11
	s_lshl_b32 s3, s2, 4
	v_cndmask_b32_e32 v36, v34, v36, vcc
	v_lshlrev_b32_e32 v71, 2, v36
	v_xor_b32_e32 v36, 4, v34
	v_cmp_lt_i32_e32 vcc, v36, v35
	v_readlane_b32 s7, v252, 11
	s_add_i32 s3, s3, s18
	v_cndmask_b32_e32 v36, v34, v36, vcc
	v_lshlrev_b32_e32 v72, 2, v36
	v_xor_b32_e32 v36, 8, v34
	v_cmp_lt_i32_e32 vcc, v36, v35
	s_lshl_b32 s7, s7, 1
	s_ashr_i32 s19, s18, 31
	v_cndmask_b32_e32 v36, v34, v36, vcc
	v_lshlrev_b32_e32 v73, 2, v36
	v_xor_b32_e32 v36, 16, v34
	v_cmp_lt_i32_e32 vcc, v36, v35
	s_add_i32 s3, s3, s7
	v_cmp_eq_u32_e64 s[0:1], 0, v198
	v_cndmask_b32_e32 v36, v34, v36, vcc
	s_waitcnt vmcnt(9)
	v_lshlrev_b32_e32 v74, 2, v36
	v_xor_b32_e32 v36, 32, v34
	v_cmp_lt_i32_e32 vcc, v36, v35
	s_lshl_b64 s[28:29], s[18:19], 6
	v_lshl_or_b32 v66, v198, 3, s24
	v_cndmask_b32_e32 v34, v34, v36, vcc
	v_lshlrev_b32_e32 v75, 2, v34
	v_mov_b32_e32 v67, s25
	s_lshl_b64 s[30:31], s[18:19], 11
	s_ashr_i32 s7, s3, 31
	v_lshlrev_b32_e32 v76, 4, v198
	s_mov_b32 s24, 0x580000
	v_mov_b32_e32 v77, 0x358637bd
	s_waitcnt vmcnt(8)
	v_mov_b32_e32 v78, 0x10000
	s_branch .LBB0_254

; __global__ void __launch_bounds__(NTHREADS, 2) fwd_kernel(Params P) {
;     ...
;             for (; m0 < M; m0 += 2 * NGW) {
;                 const int mn = m0 + 2 * NGW; const bool more = mn < M;
;                 if (more) {
; #pragma unroll
;                     for (int q = 0; q < 2; ++q) { const f32x4* xv = xrow(mn + q);
; #pragma unroll
;                         for (int j = 0; j < 4; ++j) vn[q][j] = xv[64 * j]; }
;                 }
.LBB0_254:
	s_cmpk_lt_i32 s3, 0x4100
	s_cselect_b64 s[34:35], -1, 0
	s_cmpk_gt_i32 s3, 0x40ff
	s_cbranch_scc1 .LBB0_256
	s_add_i32 s25, s3, 0xffffc000
	s_cmpk_lt_i32 s3, 0x4000
	s_cselect_b32 s73, s7, 0
	s_cselect_b32 s72, s3, s25
	s_cselect_b32 s25, s9, s11
	s_cselect_b32 s33, s8, s10
	s_lshl_b64 s[72:73], s[72:73], 12
	s_add_u32 s72, s33, s72
	s_addc_u32 s73, s25, s73
	s_add_u32 s25, s3, 1
	global_load_dwordx4 v[34:37], v76, s[72:73] nt
	global_load_dwordx4 v[38:41], v76, s[72:73] offset:1024 nt
	global_load_dwordx4 v[42:45], v76, s[72:73] offset:2048 nt
	global_load_dwordx4 v[46:49], v76, s[72:73] offset:3072 nt
	s_addc_u32 s33, s7, 0
	s_add_i32 s72, s3, 0xffffc001
	s_cmpk_lt_i32 s25, 0x4000
	s_cselect_b32 s73, s33, 0
	s_cselect_b32 s72, s25, s72
	s_cselect_b32 s25, s9, s11
	s_cselect_b32 s33, s8, s10
	s_lshl_b64 s[72:73], s[72:73], 12
	s_add_u32 s72, s33, s72
	s_addc_u32 s73, s25, s73
	global_load_dwordx4 v[50:53], v76, s[72:73] nt
	global_load_dwordx4 v[54:57], v76, s[72:73] offset:1024 nt
	global_load_dwordx4 v[58:61], v76, s[72:73] offset:2048 nt
	global_load_dwordx4 v[62:65], v76, s[72:73] offset:3072 nt
